# v12: v11 with sc1 (L2 write-through) policy on the row phases' output stores (P0 h rows, P3, P5, P6b) instead of write-back: less dirty data to flush at the grid barriers
# baseline (speedup 1.0000x reference)
.LBB0_153:
	s_waitcnt vmcnt(15)
	v_mul_f32_e32 v140, v1, v1
	v_mul_f32_e32 v141, v3, v3
	v_fmac_f32_e32 v140, v0, v0
	v_fmac_f32_e32 v141, v2, v2
	v_add_f32_e32 v140, v140, v141
	s_waitcnt vmcnt(14)
	v_mul_f32_e32 v141, v5, v5
	v_mul_f32_e32 v142, v7, v7
	v_fmac_f32_e32 v141, v4, v4
	v_fmac_f32_e32 v142, v6, v6
	v_add_f32_e32 v141, v141, v142
	v_add_f32_e32 v140, v140, v141
	s_waitcnt vmcnt(13)
	v_mul_f32_e32 v141, v9, v9
	v_mul_f32_e32 v142, v11, v11
	v_fmac_f32_e32 v141, v8, v8
	v_fmac_f32_e32 v142, v10, v10
	v_add_f32_e32 v141, v141, v142
	v_add_f32_e32 v140, v140, v141
	s_waitcnt vmcnt(12)
	v_mul_f32_e32 v141, v13, v13
	v_mul_f32_e32 v142, v15, v15
	v_fmac_f32_e32 v141, v12, v12
	v_fmac_f32_e32 v142, v14, v14
	v_add_f32_e32 v141, v141, v142
	v_add_f32_e32 v140, v140, v141
	s_waitcnt vmcnt(1)
	v_mul_f32_e32 v141, v33, v33
	v_mul_f32_e32 v142, v35, v35
	v_fmac_f32_e32 v141, v32, v32
	v_fmac_f32_e32 v142, v34, v34
	v_add_f32_e32 v141, v141, v142
	v_add_f32_e32 v140, v140, v141
	v_mul_f32_e32 v141, v17, v17
	v_mul_f32_e32 v142, v19, v19
	v_fmac_f32_e32 v141, v16, v16
	v_fmac_f32_e32 v142, v18, v18
	v_add_f32_e32 v141, v141, v142
	v_add_f32_e32 v140, v140, v141
	v_mul_f32_e32 v141, v21, v21
	v_mul_f32_e32 v142, v23, v23
	v_fmac_f32_e32 v141, v20, v20
	v_fmac_f32_e32 v142, v22, v22
	v_add_f32_e32 v141, v141, v142
	v_add_f32_e32 v140, v140, v141
	v_mul_f32_e32 v141, v37, v37
	v_mul_f32_e32 v142, v39, v39
	v_fmac_f32_e32 v141, v36, v36
	v_fmac_f32_e32 v142, v38, v38
	v_add_f32_e32 v141, v141, v142
	v_add_f32_e32 v140, v140, v141
	v_mul_f32_e32 v141, v25, v25
	v_mul_f32_e32 v142, v27, v27
	v_fmac_f32_e32 v141, v24, v24
	v_fmac_f32_e32 v142, v26, v26
	v_add_f32_e32 v141, v141, v142
	v_add_f32_e32 v140, v140, v141
	v_mul_f32_e32 v141, v29, v29
	v_mul_f32_e32 v142, v31, v31
	v_fmac_f32_e32 v141, v28, v28
	v_fmac_f32_e32 v142, v30, v30
	v_add_f32_e32 v141, v141, v142
	v_add_f32_e32 v140, v140, v141
	v_mul_f32_e32 v141, v41, v41
	v_mul_f32_e32 v142, v43, v43
	v_fmac_f32_e32 v141, v40, v40
	v_fmac_f32_e32 v142, v42, v42
	v_add_f32_e32 v141, v141, v142
	v_add_f32_e32 v140, v140, v141
	v_mul_f32_e32 v141, v45, v45
	v_mul_f32_e32 v142, v47, v47
	v_fmac_f32_e32 v141, v44, v44
	v_fmac_f32_e32 v142, v46, v46
	v_add_f32_e32 v141, v141, v142
	v_add_f32_e32 v140, v140, v141
	v_mul_f32_e32 v141, v49, v49
	v_mul_f32_e32 v142, v51, v51
	v_fmac_f32_e32 v141, v48, v48
	v_fmac_f32_e32 v142, v50, v50
	v_add_f32_e32 v141, v141, v142
	v_add_f32_e32 v140, v140, v141
	v_mul_f32_e32 v141, v53, v53
	v_mul_f32_e32 v142, v55, v55
	v_fmac_f32_e32 v141, v52, v52
	v_fmac_f32_e32 v142, v54, v54
	v_add_f32_e32 v141, v141, v142
	v_add_f32_e32 v140, v140, v141
	v_mul_f32_e32 v141, v57, v57
	v_mul_f32_e32 v142, v59, v59
	v_fmac_f32_e32 v141, v56, v56
	v_fmac_f32_e32 v142, v58, v58
	v_add_f32_e32 v141, v141, v142
	v_add_f32_e32 v140, v140, v141
	s_waitcnt vmcnt(0)
	v_mul_f32_e32 v141, v61, v61
	v_mul_f32_e32 v142, v63, v63
	v_fmac_f32_e32 v141, v60, v60
	v_fmac_f32_e32 v142, v62, v62
	v_add_f32_e32 v141, v141, v142
	v_add_f32_e32 v140, v140, v141
	ds_swizzle_b32 v141, v140 offset:swizzle(SWAP,1)
	s_cmpk_lt_i32 s37, 0x6000
	s_waitcnt lgkmcnt(0)
	v_add_f32_e32 v140, v140, v141
	ds_swizzle_b32 v141, v140 offset:swizzle(SWAP,2)
	s_waitcnt lgkmcnt(0)
	v_add_f32_e32 v140, v140, v141
	ds_swizzle_b32 v141, v140 offset:swizzle(SWAP,4)
	s_waitcnt lgkmcnt(0)
	v_add_f32_e32 v140, v140, v141
	ds_swizzle_b32 v141, v140 offset:swizzle(SWAP,8)
	s_waitcnt lgkmcnt(0)
	v_add_f32_e32 v140, v140, v141
	ds_swizzle_b32 v141, v140 offset:swizzle(SWAP,16)
	s_waitcnt lgkmcnt(0)
	v_add_f32_e32 v140, v140, v141
	v_mov_b32_e32 v141, v140
	s_nop 1
	v_permlane32_swap_b32_e32 v140, v141
	v_add_f32_e32 v140, v140, v141
	v_fmamk_f32 v140, v140, 0x39800000, v137
	v_mul_f32_e32 v141, 0x4f800000, v140
	v_cmp_gt_f32_e32 vcc, s34, v140
	s_nop 1
	v_cndmask_b32_e32 v140, v140, v141, vcc
	v_sqrt_f32_e32 v141, v140
	s_nop 0
	v_add_u32_e32 v142, -1, v141
	v_fma_f32 v143, -v142, v141, v140
	v_cmp_ge_f32_e64 s[6:7], 0, v143
	v_add_u32_e32 v143, 1, v141
	s_nop 0
	v_cndmask_b32_e64 v142, v141, v142, s[6:7]
	v_fma_f32 v141, -v143, v141, v140
	v_cmp_lt_f32_e64 s[6:7], 0, v141
	s_nop 1
	v_cndmask_b32_e64 v141, v142, v143, s[6:7]
	v_mul_f32_e32 v142, 0x37800000, v141
	v_cndmask_b32_e32 v141, v141, v142, vcc
	v_cmp_class_f32_e32 vcc, v140, v138
	s_cselect_b64 s[6:7], -1, 0
	s_and_b64 s[26:27], s[4:5], s[6:7]
	v_cndmask_b32_e32 v140, v141, v140, vcc
	s_and_saveexec_b64 s[6:7], s[26:27]
	s_cbranch_execz .LBB0_155
	s_add_u32 s26, s18, s30
	s_addc_u32 s27, s19, s31
	global_store_dword v139, v140, s[26:27] sc1
.LBB0_155:
	s_or_b64 exec, exec, s[6:7]
	v_div_scale_f32 v141, s[6:7], v140, v140, 1.0
	v_rcp_f32_e32 v146, v141
	v_div_scale_f32 v142, vcc, 1.0, v140, 1.0
	v_fma_f32 v143, -v141, v146, 1.0
	v_fmac_f32_e32 v146, v143, v146
	v_mul_f32_e32 v147, v142, v146
	v_fma_f32 v143, -v141, v147, v142
	v_fmac_f32_e32 v147, v143, v146
	v_fma_f32 v141, -v141, v147, v142
	ds_read_b128 v[142:145], v136
	v_div_fmas_f32 v141, v141, v146, v147
	v_div_fixup_f32 v148, v141, v140, 1.0
	v_mul_f32_e32 v140, v148, v0
	v_mul_f32_e32 v141, v148, v1
	s_waitcnt lgkmcnt(0)
	v_mul_f32_e32 v140, v142, v140
	v_mul_f32_e32 v141, v143, v141
	v_cvt_pk_bf16_f32 v146, v140, v141
	v_mul_f32_e32 v140, v148, v2
	v_mul_f32_e32 v141, v148, v3
	v_mul_f32_e32 v140, v144, v140
	v_mul_f32_e32 v141, v145, v141
	v_cvt_pk_bf16_f32 v147, v140, v141
	ds_read_b128 v[140:143], v136 offset:1024
	v_mul_f32_e32 v144, v148, v4
	global_store_dwordx2 v[134:135], v[146:147], off sc1
	v_add_co_u32_e32 v146, vcc, s35, v132
	s_waitcnt lgkmcnt(0)
	v_mul_f32_e32 v140, v140, v144
	v_mul_f32_e32 v144, v148, v5
	v_mul_f32_e32 v141, v141, v144
	v_cvt_pk_bf16_f32 v144, v140, v141
	v_mul_f32_e32 v140, v148, v6
	v_mul_f32_e32 v141, v148, v7
	v_mul_f32_e32 v140, v142, v140
	v_mul_f32_e32 v141, v143, v141
	v_cvt_pk_bf16_f32 v145, v140, v141
	ds_read_b128 v[140:143], v136 offset:2048
	v_addc_co_u32_e32 v147, vcc, 0, v133, vcc
	global_store_dwordx2 v[146:147], v[144:145], off offset:512 sc1
	v_mul_f32_e32 v144, v148, v8
	s_waitcnt lgkmcnt(0)
	v_mul_f32_e32 v140, v140, v144
	v_mul_f32_e32 v144, v148, v9
	v_mul_f32_e32 v141, v141, v144
	v_cvt_pk_bf16_f32 v144, v140, v141
	v_mul_f32_e32 v140, v148, v10
	v_mul_f32_e32 v141, v148, v11
	v_mul_f32_e32 v140, v142, v140
	v_mul_f32_e32 v141, v143, v141
	v_cvt_pk_bf16_f32 v145, v140, v141
	ds_read_b128 v[140:143], v136 offset:3072
	global_store_dwordx2 v[146:147], v[144:145], off offset:1024 sc1
	v_mul_f32_e32 v144, v148, v12
	s_waitcnt lgkmcnt(0)
	v_mul_f32_e32 v140, v140, v144
	v_mul_f32_e32 v144, v148, v13
	v_mul_f32_e32 v141, v141, v144
	v_cvt_pk_bf16_f32 v140, v140, v141
	v_mul_f32_e32 v141, v148, v14
	v_mul_f32_e32 v141, v142, v141
	v_mul_f32_e32 v142, v148, v15
	v_mul_f32_e32 v142, v143, v142
	v_cvt_pk_bf16_f32 v141, v141, v142
	global_store_dwordx2 v[146:147], v[140:141], off offset:1536 sc1
	ds_read_b128 v[140:143], v136 offset:4096
	v_mul_f32_e32 v144, v148, v32
	s_waitcnt lgkmcnt(0)
	v_mul_f32_e32 v140, v140, v144
	v_mul_f32_e32 v144, v148, v33
	v_mul_f32_e32 v141, v141, v144
	v_cvt_pk_bf16_f32 v144, v140, v141
	v_mul_f32_e32 v140, v148, v34
	v_mul_f32_e32 v141, v148, v35
	v_mul_f32_e32 v140, v142, v140
	v_mul_f32_e32 v141, v143, v141
	v_cvt_pk_bf16_f32 v145, v140, v141
	ds_read_b128 v[140:143], v136 offset:5120
	global_store_dwordx2 v[146:147], v[144:145], off offset:2048 sc1
	v_mul_f32_e32 v144, v148, v16
	s_waitcnt lgkmcnt(0)
	v_mul_f32_e32 v140, v140, v144
	v_mul_f32_e32 v144, v148, v17
	v_mul_f32_e32 v141, v141, v144
	v_cvt_pk_bf16_f32 v144, v140, v141
	v_mul_f32_e32 v140, v148, v18
	v_mul_f32_e32 v141, v148, v19
	v_mul_f32_e32 v140, v142, v140
	v_mul_f32_e32 v141, v143, v141
	v_cvt_pk_bf16_f32 v145, v140, v141
	ds_read_b128 v[140:143], v136 offset:6144
	global_store_dwordx2 v[146:147], v[144:145], off offset:2560 sc1
	v_mul_f32_e32 v144, v148, v20
	s_waitcnt lgkmcnt(0)
	v_mul_f32_e32 v140, v140, v144
	v_mul_f32_e32 v144, v148, v21
	v_mul_f32_e32 v141, v141, v144
	v_cvt_pk_bf16_f32 v144, v140, v141
	v_mul_f32_e32 v140, v148, v22
	v_mul_f32_e32 v141, v148, v23
	v_mul_f32_e32 v140, v142, v140
	v_mul_f32_e32 v141, v143, v141
	v_cvt_pk_bf16_f32 v145, v140, v141
	ds_read_b128 v[140:143], v136 offset:7168
	global_store_dwordx2 v[146:147], v[144:145], off offset:3072 sc1
	v_mul_f32_e32 v144, v148, v36
	s_waitcnt lgkmcnt(0)
	v_mul_f32_e32 v140, v140, v144
	v_mul_f32_e32 v144, v148, v37
	v_mul_f32_e32 v141, v141, v144
	v_cvt_pk_bf16_f32 v140, v140, v141
	v_mul_f32_e32 v141, v148, v38
	v_mul_f32_e32 v141, v142, v141
	v_mul_f32_e32 v142, v148, v39
	v_mul_f32_e32 v142, v143, v142
	v_cvt_pk_bf16_f32 v141, v141, v142
	global_store_dwordx2 v[146:147], v[140:141], off offset:3584 sc1
	ds_read_b128 v[140:143], v136 offset:8192
	v_mul_f32_e32 v144, v148, v24
	v_add_co_u32_e32 v146, vcc, s36, v132
	s_waitcnt lgkmcnt(0)
	v_mul_f32_e32 v140, v140, v144
	v_mul_f32_e32 v144, v148, v25
	v_mul_f32_e32 v141, v141, v144
	v_cvt_pk_bf16_f32 v144, v140, v141
	v_mul_f32_e32 v140, v148, v26
	v_mul_f32_e32 v141, v148, v27
	v_mul_f32_e32 v140, v142, v140
	v_mul_f32_e32 v141, v143, v141
	v_cvt_pk_bf16_f32 v145, v140, v141
	ds_read_b128 v[140:143], v136 offset:9216
	v_addc_co_u32_e32 v147, vcc, 0, v133, vcc
	global_store_dwordx2 v[146:147], v[144:145], off sc1
	v_mul_f32_e32 v144, v148, v28
	s_waitcnt lgkmcnt(0)
	v_mul_f32_e32 v140, v140, v144
	v_mul_f32_e32 v144, v148, v29
	v_mul_f32_e32 v141, v141, v144
	v_cvt_pk_bf16_f32 v144, v140, v141
	v_mul_f32_e32 v140, v148, v30
	v_mul_f32_e32 v141, v148, v31
	v_mul_f32_e32 v140, v142, v140
	v_mul_f32_e32 v141, v143, v141
	v_cvt_pk_bf16_f32 v145, v140, v141
	ds_read_b128 v[140:143], v136 offset:10240
	global_store_dwordx2 v[146:147], v[144:145], off offset:512 sc1
	v_mul_f32_e32 v144, v148, v40
	s_waitcnt lgkmcnt(0)
	v_mul_f32_e32 v140, v140, v144
	v_mul_f32_e32 v144, v148, v41
	v_mul_f32_e32 v141, v141, v144
	v_cvt_pk_bf16_f32 v144, v140, v141
	v_mul_f32_e32 v140, v148, v42
	v_mul_f32_e32 v141, v148, v43
	v_mul_f32_e32 v140, v142, v140
	v_mul_f32_e32 v141, v143, v141
	v_cvt_pk_bf16_f32 v145, v140, v141
	ds_read_b128 v[140:143], v136 offset:11264
	global_store_dwordx2 v[146:147], v[144:145], off offset:1024 sc1
	v_mul_f32_e32 v144, v148, v44
	s_waitcnt lgkmcnt(0)
	v_mul_f32_e32 v140, v140, v144
	v_mul_f32_e32 v144, v148, v45
	v_mul_f32_e32 v141, v141, v144
	v_cvt_pk_bf16_f32 v140, v140, v141
	v_mul_f32_e32 v141, v148, v46
	v_mul_f32_e32 v141, v142, v141
	v_mul_f32_e32 v142, v148, v47
	v_mul_f32_e32 v142, v143, v142
	v_cvt_pk_bf16_f32 v141, v141, v142
	global_store_dwordx2 v[146:147], v[140:141], off offset:1536 sc1
	ds_read_b128 v[140:143], v136 offset:12288
	v_mul_f32_e32 v144, v148, v48
	s_waitcnt lgkmcnt(0)
	v_mul_f32_e32 v140, v140, v144
	v_mul_f32_e32 v144, v148, v49
	v_mul_f32_e32 v141, v141, v144
	v_cvt_pk_bf16_f32 v144, v140, v141
	v_mul_f32_e32 v140, v148, v50
	v_mul_f32_e32 v141, v148, v51
	v_mul_f32_e32 v140, v142, v140
	v_mul_f32_e32 v141, v143, v141
	v_cvt_pk_bf16_f32 v145, v140, v141
	ds_read_b128 v[140:143], v136 offset:13312
	global_store_dwordx2 v[146:147], v[144:145], off offset:2048 sc1
	v_mul_f32_e32 v144, v148, v52
	s_waitcnt lgkmcnt(0)
	v_mul_f32_e32 v140, v140, v144
	v_mul_f32_e32 v144, v148, v53
	v_mul_f32_e32 v141, v141, v144
	v_cvt_pk_bf16_f32 v144, v140, v141
	v_mul_f32_e32 v140, v148, v54
	v_mul_f32_e32 v141, v148, v55
	v_mul_f32_e32 v140, v142, v140
	v_mul_f32_e32 v141, v143, v141
	v_cvt_pk_bf16_f32 v145, v140, v141
	ds_read_b128 v[140:143], v136 offset:14336
	global_store_dwordx2 v[146:147], v[144:145], off offset:2560 sc1
	v_mul_f32_e32 v144, v148, v56
	s_waitcnt lgkmcnt(0)
	v_mul_f32_e32 v140, v140, v144
	v_mul_f32_e32 v144, v148, v57
	v_mul_f32_e32 v141, v141, v144
	v_cvt_pk_bf16_f32 v144, v140, v141
	v_mul_f32_e32 v140, v148, v58
	v_mul_f32_e32 v141, v148, v59
	v_mul_f32_e32 v140, v142, v140
	v_mul_f32_e32 v141, v143, v141
	v_cvt_pk_bf16_f32 v145, v140, v141
	ds_read_b128 v[140:143], v136 offset:15360
	global_store_dwordx2 v[146:147], v[144:145], off offset:3072 sc1
	v_mul_f32_e32 v144, v148, v60
	s_waitcnt lgkmcnt(0)
	v_mul_f32_e32 v140, v140, v144
	v_mul_f32_e32 v144, v148, v61
	v_mul_f32_e32 v141, v141, v144
	v_cvt_pk_bf16_f32 v140, v140, v141
	v_mul_f32_e32 v141, v148, v62
	v_mul_f32_e32 v141, v142, v141
	v_mul_f32_e32 v142, v148, v63
	v_mul_f32_e32 v142, v143, v142
	v_cvt_pk_bf16_f32 v141, v141, v142
	global_store_dwordx2 v[146:147], v[140:141], off offset:3584 sc1
	s_branch .LBB0_152
.LBB0_156:
	s_mov_b32 s8, s9
	v_mov_b64_e32 v[140:141], s[8:9]
	global_store_dwordx2 v[134:135], v[140:141], off sc1
	v_add_co_u32_e32 v134, vcc, 0x16e00000, v132
	s_nop 1
	v_addc_co_u32_e32 v135, vcc, 0, v133, vcc
	v_add_co_u32_e32 v132, vcc, 0x16e01000, v132
	global_store_dwordx2 v[134:135], v[140:141], off offset:512 sc1
	global_store_dwordx2 v[134:135], v[140:141], off offset:1024 sc1
	global_store_dwordx2 v[134:135], v[140:141], off offset:1536 sc1
	global_store_dwordx2 v[134:135], v[140:141], off offset:2048 sc1
	global_store_dwordx2 v[134:135], v[140:141], off offset:2560 sc1
	global_store_dwordx2 v[134:135], v[140:141], off offset:3072 sc1
	global_store_dwordx2 v[134:135], v[140:141], off offset:3584 sc1
	v_addc_co_u32_e32 v133, vcc, 0, v133, vcc
	global_store_dwordx2 v[132:133], v[140:141], off sc1
	global_store_dwordx2 v[132:133], v[140:141], off offset:512 sc1
	global_store_dwordx2 v[132:133], v[140:141], off offset:1024 sc1
	global_store_dwordx2 v[132:133], v[140:141], off offset:1536 sc1
	global_store_dwordx2 v[132:133], v[140:141], off offset:2048 sc1
	global_store_dwordx2 v[132:133], v[140:141], off offset:2560 sc1
	global_store_dwordx2 v[132:133], v[140:141], off offset:3072 sc1
	global_store_dwordx2 v[132:133], v[140:141], off offset:3584 sc1
	s_cmpk_gt_i32 s24, 0x60ff
	s_cselect_b64 s[6:7], -1, 0
	s_and_b64 vcc, exec, s[6:7]
	s_cbranch_vccnz .LBB0_139

.LBB0_568:
	v_add_co_u32_e32 v18, vcc, 0xfffff000, v2
	global_load_dwordx2 v[4:5], v[2:3], off offset:-4096 nt
	global_load_dwordx2 v[6:7], v[2:3], off offset:-3584 nt
	global_load_dwordx2 v[8:9], v[2:3], off offset:-3072 nt
	global_load_dwordx2 v[10:11], v[2:3], off offset:-2560 nt
	global_load_dwordx2 v[12:13], v[2:3], off offset:-2048 nt
	global_load_dwordx2 v[14:15], v[2:3], off offset:-1536 nt
	global_load_dwordx2 v[16:17], v[2:3], off offset:-1024 nt
	global_load_dwordx2 v[20:21], v[2:3], off offset:-512 nt
	v_addc_co_u32_e32 v19, vcc, -1, v3, vcc
	global_load_dwordx2 v[22:23], v[2:3], off nt
	global_load_dwordx2 v[24:25], v[18:19], off offset:-2560 nt
	global_load_dwordx2 v[26:27], v[18:19], off offset:-2048 nt
	global_load_dwordx2 v[28:29], v[18:19], off offset:-1536 nt
	global_load_dwordx2 v[30:31], v[18:19], off offset:-1024 nt
	global_load_dwordx2 v[32:33], v[18:19], off offset:-512 nt
	global_load_dwordx2 v[34:35], v[18:19], off offset:-3072 nt
	global_load_dwordx2 v[36:37], v[18:19], off offset:-3584 nt
	s_add_u32 s24, s10, s16
	s_addc_u32 s25, s11, s17
	global_load_dwordx2 v[18:19], v38, s[24:25]
	s_waitcnt vmcnt(16)
	v_lshlrev_b32_e32 v42, 16, v4
	v_and_b32_e32 v43, 0xffff0000, v4
	v_lshlrev_b32_e32 v4, 16, v5
	v_and_b32_e32 v5, 0xffff0000, v5
	s_waitcnt vmcnt(15)
	v_lshlrev_b32_e32 v44, 16, v6
	s_waitcnt vmcnt(7)
	v_lshlrev_b32_e32 v60, 16, v24
	v_and_b32_e32 v61, 0xffff0000, v24
	v_lshlrev_b32_e32 v24, 16, v25
	v_and_b32_e32 v25, 0xffff0000, v25
	s_waitcnt vmcnt(6)
	v_lshlrev_b32_e32 v62, 16, v26
	v_and_b32_e32 v63, 0xffff0000, v26
	v_lshlrev_b32_e32 v26, 16, v27
	v_and_b32_e32 v27, 0xffff0000, v27
	s_waitcnt vmcnt(5)
	v_lshlrev_b32_e32 v64, 16, v28
	v_and_b32_e32 v65, 0xffff0000, v28
	v_lshlrev_b32_e32 v28, 16, v29
	v_and_b32_e32 v29, 0xffff0000, v29
	s_waitcnt vmcnt(4)
	v_lshlrev_b32_e32 v66, 16, v30
	v_and_b32_e32 v67, 0xffff0000, v30
	v_lshlrev_b32_e32 v30, 16, v31
	v_and_b32_e32 v31, 0xffff0000, v31
	s_waitcnt vmcnt(3)
	v_lshlrev_b32_e32 v68, 16, v32
	v_and_b32_e32 v69, 0xffff0000, v32
	v_lshlrev_b32_e32 v32, 16, v33
	v_and_b32_e32 v33, 0xffff0000, v33
	s_waitcnt vmcnt(2)
	v_lshlrev_b32_e32 v70, 16, v34
	v_and_b32_e32 v71, 0xffff0000, v34
	v_lshlrev_b32_e32 v34, 16, v35
	v_and_b32_e32 v35, 0xffff0000, v35
	s_waitcnt vmcnt(1)
	v_lshlrev_b32_e32 v72, 16, v36
	v_and_b32_e32 v73, 0xffff0000, v36
	v_lshlrev_b32_e32 v36, 16, v37
	v_and_b32_e32 v37, 0xffff0000, v37
	v_and_b32_e32 v45, 0xffff0000, v6
	v_lshlrev_b32_e32 v6, 16, v7
	v_and_b32_e32 v7, 0xffff0000, v7
	v_lshlrev_b32_e32 v46, 16, v8
	v_and_b32_e32 v47, 0xffff0000, v8
	v_lshlrev_b32_e32 v8, 16, v9
	v_and_b32_e32 v9, 0xffff0000, v9
	v_lshlrev_b32_e32 v48, 16, v10
	v_and_b32_e32 v49, 0xffff0000, v10
	v_lshlrev_b32_e32 v10, 16, v11
	v_and_b32_e32 v11, 0xffff0000, v11
	v_lshlrev_b32_e32 v50, 16, v12
	v_and_b32_e32 v51, 0xffff0000, v12
	v_lshlrev_b32_e32 v12, 16, v13
	v_and_b32_e32 v13, 0xffff0000, v13
	v_lshlrev_b32_e32 v52, 16, v14
	v_and_b32_e32 v53, 0xffff0000, v14
	v_lshlrev_b32_e32 v14, 16, v15
	v_and_b32_e32 v15, 0xffff0000, v15
	v_lshlrev_b32_e32 v54, 16, v16
	v_and_b32_e32 v55, 0xffff0000, v16
	v_lshlrev_b32_e32 v16, 16, v17
	v_and_b32_e32 v17, 0xffff0000, v17
	v_lshlrev_b32_e32 v56, 16, v20
	v_and_b32_e32 v57, 0xffff0000, v20
	v_lshlrev_b32_e32 v20, 16, v21
	v_and_b32_e32 v21, 0xffff0000, v21
	v_lshlrev_b32_e32 v58, 16, v22
	v_and_b32_e32 v59, 0xffff0000, v22
	v_lshlrev_b32_e32 v22, 16, v23
	v_and_b32_e32 v23, 0xffff0000, v23
	v_pk_add_f32 v[74:75], v[36:37], v[34:35]
	v_pk_add_f32 v[76:77], v[72:73], v[70:71]
	v_sub_f32_e32 v35, v37, v35
	v_sub_f32_e32 v34, v36, v34
	v_sub_f32_e32 v37, v73, v71
	v_sub_f32_e32 v36, v72, v70
	v_pk_add_f32 v[70:71], v[24:25], v[26:27]
	v_pk_add_f32 v[72:73], v[60:61], v[62:63]
	v_sub_f32_e32 v25, v25, v27
	v_sub_f32_e32 v24, v24, v26
	v_sub_f32_e32 v27, v61, v63
	v_sub_f32_e32 v26, v60, v62
	v_pk_add_f32 v[60:61], v[28:29], v[30:31]
	v_pk_add_f32 v[62:63], v[64:65], v[66:67]
	v_sub_f32_e32 v29, v29, v31
	v_sub_f32_e32 v28, v28, v30
	v_sub_f32_e32 v31, v65, v67
	v_sub_f32_e32 v30, v64, v66
	v_pk_add_f32 v[64:65], v[32:33], v[4:5]
	v_pk_add_f32 v[66:67], v[68:69], v[42:43]
	v_sub_f32_e32 v5, v33, v5
	v_sub_f32_e32 v4, v32, v4
	v_sub_f32_e32 v33, v69, v43
	v_sub_f32_e32 v32, v68, v42
	v_pk_add_f32 v[42:43], v[6:7], v[8:9]
	v_pk_add_f32 v[68:69], v[44:45], v[46:47]
	v_sub_f32_e32 v7, v7, v9
	v_sub_f32_e32 v6, v6, v8
	v_sub_f32_e32 v9, v45, v47
	v_sub_f32_e32 v8, v44, v46
	v_pk_add_f32 v[44:45], v[10:11], v[12:13]
	v_pk_add_f32 v[46:47], v[48:49], v[50:51]
	v_sub_f32_e32 v11, v11, v13
	v_sub_f32_e32 v10, v10, v12
	v_sub_f32_e32 v13, v49, v51
	v_sub_f32_e32 v12, v48, v50
	v_pk_add_f32 v[48:49], v[14:15], v[16:17]
	v_pk_add_f32 v[50:51], v[52:53], v[54:55]
	v_sub_f32_e32 v15, v15, v17
	v_sub_f32_e32 v14, v14, v16
	v_sub_f32_e32 v17, v53, v55
	v_sub_f32_e32 v16, v52, v54
	v_pk_add_f32 v[52:53], v[20:21], v[22:23]
	v_pk_add_f32 v[54:55], v[56:57], v[58:59]
	v_sub_f32_e32 v21, v21, v23
	v_sub_f32_e32 v20, v20, v22
	v_sub_f32_e32 v23, v57, v59
	v_sub_f32_e32 v22, v56, v58
	v_pk_add_f32 v[56:57], v[76:77], v[72:73]
	v_pk_add_f32 v[58:59], v[74:75], v[70:71]
	v_sub_f32_e32 v73, v77, v73
	v_sub_f32_e32 v72, v76, v72
	v_sub_f32_e32 v71, v75, v71
	v_sub_f32_e32 v70, v74, v70
	v_pk_add_f32 v[74:75], v[36:37], v[26:27]
	v_pk_add_f32 v[76:77], v[34:35], v[24:25]
	v_sub_f32_e32 v79, v37, v27
	v_sub_f32_e32 v78, v36, v26
	v_sub_f32_e32 v81, v35, v25
	v_sub_f32_e32 v80, v34, v24
	v_pk_add_f32 v[24:25], v[62:63], v[66:67]
	v_pk_add_f32 v[26:27], v[60:61], v[64:65]
	v_sub_f32_e32 v63, v63, v67
	v_sub_f32_e32 v62, v62, v66
	v_pk_add_f32 v[66:67], v[28:29], v[4:5]
	v_sub_f32_e32 v61, v61, v65
	v_sub_f32_e32 v60, v60, v64
	v_pk_add_f32 v[64:65], v[30:31], v[32:33]
	v_sub_f32_e32 v5, v29, v5
	v_sub_f32_e32 v4, v28, v4
	v_pk_add_f32 v[84:85], v[68:69], v[46:47]
	v_pk_add_f32 v[86:87], v[42:43], v[44:45]
	v_sub_f32_e32 v47, v69, v47
	v_sub_f32_e32 v46, v68, v46
	v_sub_f32_e32 v43, v43, v45
	v_sub_f32_e32 v42, v42, v44
	v_pk_add_f32 v[44:45], v[8:9], v[12:13]
	v_pk_add_f32 v[68:69], v[6:7], v[10:11]
	v_sub_f32_e32 v89, v9, v13
	v_sub_f32_e32 v88, v8, v12
	v_sub_f32_e32 v91, v7, v11
	v_sub_f32_e32 v90, v6, v10
	v_pk_add_f32 v[6:7], v[50:51], v[54:55]
	v_pk_add_f32 v[8:9], v[48:49], v[52:53]
	v_sub_f32_e32 v49, v49, v53
	v_sub_f32_e32 v48, v48, v52
	v_pk_add_f32 v[34:35], v[58:59], v[26:27]
	v_pk_add_f32 v[28:29], v[76:77], v[66:67]
	v_sub_f32_e32 v83, v31, v33
	v_sub_f32_e32 v82, v30, v32
	v_pk_add_f32 v[52:53], v[14:15], v[20:21]
	v_sub_f32_e32 v93, v15, v21
	v_sub_f32_e32 v92, v14, v20
	v_pk_add_f32 v[36:37], v[56:57], v[24:25]
	v_pk_add_f32 v[32:33], v[74:75], v[64:65]
	v_sub_f32_e32 v65, v75, v65
	v_sub_f32_e32 v64, v74, v64
	v_pk_add_f32 v[20:21], v[84:85], v[6:7]
	v_sub_f32_e32 v74, v85, v7
	v_sub_f32_e32 v75, v84, v6
	v_pk_add_f32 v[6:7], v[42:43], v[48:49]
	v_sub_f32_e32 v49, v43, v49
	v_sub_f32_e32 v48, v42, v48
	v_max_f32_e64 v42, |v34|, |v35|
	v_max_f32_e64 v43, |v28|, |v29|
	v_sub_f32_e32 v51, v51, v55
	v_sub_f32_e32 v50, v50, v54
	v_pk_add_f32 v[12:13], v[16:17], v[22:23]
	v_sub_f32_e32 v55, v17, v23
	v_sub_f32_e32 v54, v16, v22
	v_sub_f32_e32 v57, v57, v25
	v_sub_f32_e32 v56, v56, v24
	v_pk_add_f32 v[24:25], v[70:71], v[60:61]
	v_pk_add_f32 v[22:23], v[80:81], v[4:5]
	v_max3_f32 v42, |v36|, |v37|, v42
	v_max3_f32 v43, |v32|, |v33|, v43
	v_sub_f32_e32 v59, v59, v27
	v_sub_f32_e32 v58, v58, v26
	v_pk_add_f32 v[30:31], v[72:73], v[62:63]
	v_pk_add_f32 v[26:27], v[78:79], v[82:83]
	v_pk_add_f32 v[10:11], v[68:69], v[52:53]
	v_sub_f32_e32 v52, v68, v52
	v_max3_f32 v42, v42, 0, v43
	v_max_f32_e64 v43, |v24|, |v25|
	v_max_f32_e64 v68, |v22|, |v23|
	v_sub_f32_e32 v67, v77, v67
	v_sub_f32_e32 v66, v76, v66
	v_max3_f32 v43, |v30|, |v31|, v43
	v_max3_f32 v68, |v26|, |v27|, v68
	v_max3_f32 v42, v42, v43, v68
	v_max_f32_e64 v43, |v58|, |v59|
	v_max_f32_e64 v68, |v66|, |v67|
	v_sub_f32_e32 v63, v73, v63
	v_sub_f32_e32 v62, v72, v62
	v_sub_f32_e32 v61, v71, v61
	v_sub_f32_e32 v60, v70, v60
	v_sub_f32_e32 v72, v81, v5
	v_sub_f32_e32 v73, v80, v4
	v_max3_f32 v43, |v56|, |v57|, v43
	v_max3_f32 v68, |v64|, |v65|, v68
	v_sub_f32_e32 v70, v79, v83
	v_sub_f32_e32 v71, v78, v82
	v_max3_f32 v42, v42, v43, v68
	v_max_f32_e64 v43, |v60|, |v61|
	v_max_f32_e64 v68, |v73|, |v72|
	v_pk_add_f32 v[16:17], v[86:87], v[8:9]
	v_max3_f32 v43, |v62|, |v63|, v43
	v_max3_f32 v68, |v71|, |v70|, v68
	s_waitcnt vmcnt(0)
	v_fmamk_f32 v18, v18, 0x3a000000, v39
	v_pk_add_f32 v[14:15], v[44:45], v[12:13]
	v_max3_f32 v42, v42, v43, v68
	v_max_f32_e64 v43, |v16|, |v17|
	v_max_f32_e64 v68, |v10|, |v11|
	v_mul_f32_e32 v78, 0x4f800000, v18
	v_cmp_gt_f32_e32 vcc, s2, v18
	v_pk_add_f32 v[4:5], v[90:91], v[92:93]
	v_max3_f32 v43, |v20|, |v21|, v43
	v_max3_f32 v68, |v14|, |v15|, v68
	v_cndmask_b32_e32 v18, v18, v78, vcc
	v_sub_f32_e32 v76, v87, v9
	v_sub_f32_e32 v77, v86, v8
	v_sub_f32_e32 v45, v45, v13
	v_sub_f32_e32 v44, v44, v12
	v_sub_f32_e32 v53, v69, v53
	v_pk_add_f32 v[12:13], v[46:47], v[50:51]
	v_pk_add_f32 v[8:9], v[88:89], v[54:55]
	v_max3_f32 v43, v43, 0, v68
	v_max_f32_e64 v68, |v6|, |v7|
	v_max_f32_e64 v69, |v4|, |v5|
	v_sqrt_f32_e32 v78, v18
	v_max3_f32 v68, |v12|, |v13|, v68
	v_max3_f32 v69, |v8|, |v9|, v69
	v_max3_f32 v43, v43, v68, v69
	v_max_f32_e64 v68, |v77|, |v76|
	v_max_f32_e64 v69, |v52|, |v53|
	v_max3_f32 v68, |v75|, |v74|, v68
	v_max3_f32 v69, |v44|, |v45|, v69
	v_max3_f32 v43, v43, v68, v69
	v_add_u32_e32 v69, -1, v78
	v_fma_f32 v79, -v69, v78, v18
	v_cmp_ge_f32_e64 s[6:7], 0, v79
	v_add_u32_e32 v79, 1, v78
	v_sub_f32_e32 v47, v47, v51
	v_cndmask_b32_e64 v69, v78, v69, s[6:7]
	v_fma_f32 v78, -v79, v78, v18
	v_cmp_lt_f32_e64 s[6:7], 0, v78
	v_sub_f32_e32 v46, v46, v50
	v_sub_f32_e32 v50, v89, v55
	v_cndmask_b32_e64 v69, v69, v79, s[6:7]
	v_mul_f32_e32 v78, 0x37800000, v69
	v_cndmask_b32_e32 v69, v69, v78, vcc
	v_cmp_class_f32_e32 vcc, v18, v40
	v_sub_f32_e32 v51, v88, v54
	v_sub_f32_e32 v54, v91, v93
	v_cndmask_b32_e32 v18, v69, v18, vcc
	v_div_scale_f32 v69, s[6:7], v18, v18, 1.0
	v_rcp_f32_e32 v78, v69
	v_sub_f32_e32 v55, v90, v92
	v_max_f32_e64 v68, |v48|, |v49|
	v_max_f32_e64 v79, |v55|, |v54|
	v_max3_f32 v68, |v46|, |v47|, v68
	v_max3_f32 v79, |v51|, |v50|, v79
	v_max3_f32 v43, v43, v68, v79
	v_fma_f32 v68, -v69, v78, 1.0
	v_fmac_f32_e32 v78, v68, v78
	v_div_scale_f32 v68, vcc, 1.0, v18, 1.0
	v_mul_f32_e32 v79, v68, v78
	v_fma_f32 v80, -v69, v79, v68
	v_fmac_f32_e32 v79, v80, v78
	v_fmamk_f32 v19, v19, 0x3a000000, v39
	v_fma_f32 v68, -v69, v79, v68
	v_mul_f32_e32 v69, 0x4f800000, v19
	v_cmp_gt_f32_e64 s[6:7], s2, v19
	v_div_fmas_f32 v68, v68, v78, v79
	v_div_fixup_f32 v68, v68, v18, 1.0
	v_cndmask_b32_e64 v19, v19, v69, s[6:7]
	v_sqrt_f32_e32 v69, v19
	ds_swizzle_b32 v82, v43 offset:swizzle(SWAP,1)
	v_add_u32_e32 v18, -1, v69
	v_fma_f32 v78, -v18, v69, v19
	v_cmp_ge_f32_e32 vcc, 0, v78
	v_add_u32_e32 v78, 1, v69
	s_nop 0
	v_cndmask_b32_e32 v18, v69, v18, vcc
	v_fma_f32 v69, -v78, v69, v19
	v_cmp_lt_f32_e32 vcc, 0, v69
	s_nop 1
	v_cndmask_b32_e32 v18, v18, v78, vcc
	v_mul_f32_e32 v69, 0x37800000, v18
	v_cndmask_b32_e64 v18, v18, v69, s[6:7]
	v_cmp_class_f32_e32 vcc, v19, v40
	ds_swizzle_b32 v69, v42 offset:swizzle(SWAP,1)
	s_waitcnt lgkmcnt(0)
	v_max_f32_e32 v69, v69, v69
	v_cndmask_b32_e32 v18, v18, v19, vcc
	v_div_scale_f32 v19, s[6:7], v18, v18, 1.0
	v_rcp_f32_e32 v78, v19
	v_max_f32_e32 v42, v42, v69
	ds_swizzle_b32 v69, v42 offset:swizzle(SWAP,2)
	v_fma_f32 v79, -v19, v78, 1.0
	v_fmac_f32_e32 v78, v79, v78
	v_div_scale_f32 v79, vcc, 1.0, v18, 1.0
	v_mul_f32_e32 v80, v79, v78
	v_fma_f32 v81, -v19, v80, v79
	v_fmac_f32_e32 v80, v81, v78
	v_max_f32_e32 v81, v82, v82
	v_max_f32_e32 v43, v43, v81
	s_waitcnt lgkmcnt(0)
	v_max_f32_e32 v69, v69, v69
	ds_swizzle_b32 v81, v43 offset:swizzle(SWAP,2)
	v_max_f32_e32 v42, v42, v69
	ds_swizzle_b32 v69, v42 offset:swizzle(SWAP,4)
	v_fma_f32 v19, -v19, v80, v79
	v_div_fmas_f32 v19, v19, v78, v80
	s_waitcnt lgkmcnt(1)
	v_max_f32_e32 v79, v81, v81
	v_max_f32_e32 v43, v43, v79
	s_waitcnt lgkmcnt(0)
	v_max_f32_e32 v69, v69, v69
	ds_swizzle_b32 v79, v43 offset:swizzle(SWAP,4)
	v_max_f32_e32 v42, v42, v69
	ds_swizzle_b32 v69, v42 offset:swizzle(SWAP,8)
	v_div_fixup_f32 v78, v19, v18, 1.0
	s_waitcnt lgkmcnt(1)
	v_max_f32_e32 v19, v79, v79
	v_max_f32_e32 v19, v43, v19
	s_waitcnt lgkmcnt(0)
	v_max_f32_e32 v69, v69, v69
	ds_swizzle_b32 v43, v19 offset:swizzle(SWAP,8)
	v_max_f32_e32 v42, v42, v69
	ds_swizzle_b32 v69, v42 offset:swizzle(SWAP,16)
	s_waitcnt lgkmcnt(1)
	v_max_f32_e32 v43, v43, v43
	v_max_f32_e32 v19, v19, v43
	s_waitcnt lgkmcnt(0)
	v_max_f32_e32 v18, v69, v69
	ds_swizzle_b32 v43, v19 offset:swizzle(SWAP,16)
	v_max_f32_e32 v18, v42, v18
	v_mov_b32_e32 v42, v18
	s_nop 1
	v_permlane32_swap_b32_e32 v18, v42
	v_max_f32_e32 v42, v42, v42
	v_max_f32_e32 v18, v18, v18
	v_max_f32_e32 v18, v18, v42
	s_waitcnt lgkmcnt(0)
	v_max_f32_e32 v42, v43, v43
	v_max_f32_e32 v19, v19, v42
	v_mov_b32_e32 v42, v19
	s_nop 1
	v_permlane32_swap_b32_e32 v19, v42
	v_max_f32_e32 v42, v42, v42
	v_max_f32_e32 v19, v19, v19
	v_max_f32_e32 v19, v19, v42
	v_mul_f32_e32 v19, v78, v19
	v_mul_f32_e32 v18, v68, v18
	v_mul_f32_e32 v42, 0x3d000000, v19
	v_max3_f32 v18, v18, v42, s23
	v_mul_f32_e32 v42, 0x3d000000, v18
	v_max_f32_e32 v19, v19, v42
	v_pk_mul_f32 v[18:19], v[18:19], s[22:23] op_sel_hi:[1,0]
	s_nop 0
	v_div_scale_f32 v42, s[6:7], v18, v18, v68
	v_rcp_f32_e32 v43, v42
	s_nop 0
	v_fma_f32 v69, -v42, v43, 1.0
	v_fmac_f32_e32 v43, v69, v43
	v_div_scale_f32 v69, vcc, v68, v18, v68
	v_mul_f32_e32 v79, v69, v43
	v_fma_f32 v80, -v42, v79, v69
	v_fmac_f32_e32 v79, v80, v43
	v_fma_f32 v42, -v42, v79, v69
	v_div_scale_f32 v69, s[6:7], v19, v19, v78
	v_rcp_f32_e32 v80, v69
	v_div_fmas_f32 v42, v42, v43, v79
	v_div_fixup_f32 v68, v42, v18, v68
	v_mul_f32_e32 v37, v68, v37
	v_fma_f32 v42, -v69, v80, 1.0
	v_fmac_f32_e32 v80, v42, v80
	v_div_scale_f32 v42, vcc, v78, v19, v78
	v_mul_f32_e32 v43, v42, v80
	v_fma_f32 v79, -v69, v43, v42
	v_fmac_f32_e32 v43, v79, v80
	v_fma_f32 v42, -v69, v43, v42
	v_div_fmas_f32 v42, v42, v80, v43
	v_div_fixup_f32 v69, v42, v19, v78
	v_mul_f32_e32 v36, v68, v36
	v_rndne_f32_e32 v37, v37
	v_mul_f32_e32 v34, v68, v34
	v_mul_f32_e32 v35, v68, v35
	v_mul_f32_e32 v33, v68, v33
	v_mul_f32_e32 v15, v69, v15
	v_rndne_f32_e32 v36, v36
	v_cvt_i32_f32_e32 v37, v37
	v_rndne_f32_e32 v34, v34
	v_rndne_f32_e32 v35, v35
	v_mul_f32_e32 v32, v68, v32
	v_rndne_f32_e32 v33, v33
	v_mul_f32_e32 v28, v68, v28
	v_mul_f32_e32 v29, v68, v29
	v_mul_f32_e32 v14, v69, v14
	v_rndne_f32_e32 v15, v15
	v_mul_f32_e32 v10, v69, v10
	v_mul_f32_e32 v11, v69, v11
	v_cvt_i32_f32_e32 v36, v36
	v_cvt_i32_f32_sdwa v34, v34 dst_sel:WORD_1 dst_unused:UNUSED_PAD src0_sel:DWORD
	v_cvt_i32_f32_e32 v35, v35
	v_rndne_f32_e32 v32, v32
	v_cvt_i32_f32_e32 v33, v33
	v_rndne_f32_e32 v28, v28
	v_rndne_f32_e32 v29, v29
	v_rndne_f32_e32 v14, v14
	v_cvt_i32_f32_e32 v15, v15
	v_rndne_f32_e32 v10, v10
	v_rndne_f32_e32 v11, v11
	v_cvt_i32_f32_e32 v32, v32
	v_cvt_i32_f32_sdwa v28, v28 dst_sel:WORD_1 dst_unused:UNUSED_PAD src0_sel:DWORD
	v_cvt_i32_f32_e32 v29, v29
	v_cvt_i32_f32_e32 v14, v14
	v_cvt_i32_f32_sdwa v10, v10 dst_sel:WORD_1 dst_unused:UNUSED_PAD src0_sel:DWORD
	v_cvt_i32_f32_e32 v11, v11
	v_lshlrev_b32_e32 v37, 8, v37
	v_lshl_add_u64 v[42:43], s[10:11], 0, v[0:1]
	v_and_b32_e32 v37, 0xff00, v37
	v_and_b32_e32 v34, 0xff0000, v34
	v_perm_b32 v35, v35, v36, s26
	v_lshlrev_b32_e32 v33, 8, v33
	v_lshlrev_b32_e32 v15, 8, v15
	v_or3_b32 v36, v35, v37, v34
	v_add_co_u32_e32 v34, vcc, s27, v42
	v_and_b32_e32 v33, 0xff00, v33
	v_and_b32_e32 v28, 0xff0000, v28
	v_perm_b32 v29, v29, v32, s26
	v_and_b32_e32 v15, 0xff00, v15
	v_and_b32_e32 v10, 0xff0000, v10
	v_perm_b32 v11, v11, v14, s26
	v_addc_co_u32_e32 v35, vcc, 0, v43, vcc
	v_or3_b32 v28, v29, v33, v28
	v_mul_f32_e32 v29, v68, v31
	v_or3_b32 v10, v11, v15, v10
	v_mul_f32_e32 v11, v69, v13
	global_store_dword v[34:35], v28, off offset:256 sc1
	v_mul_f32_e32 v28, v68, v30
	v_rndne_f32_e32 v29, v29
	v_mul_f32_e32 v24, v68, v24
	v_mul_f32_e32 v25, v68, v25
	global_store_dword v[34:35], v10, off offset:2304 sc1
	v_mul_f32_e32 v10, v69, v12
	v_rndne_f32_e32 v11, v11
	v_mul_f32_e32 v6, v69, v6
	v_mul_f32_e32 v7, v69, v7
	v_rndne_f32_e32 v28, v28
	v_cvt_i32_f32_e32 v29, v29
	v_rndne_f32_e32 v24, v24
	v_rndne_f32_e32 v25, v25
	v_rndne_f32_e32 v10, v10
	v_cvt_i32_f32_e32 v11, v11
	v_rndne_f32_e32 v6, v6
	v_rndne_f32_e32 v7, v7
	v_cvt_i32_f32_e32 v28, v28
	v_cvt_i32_f32_sdwa v24, v24 dst_sel:WORD_1 dst_unused:UNUSED_PAD src0_sel:DWORD
	v_cvt_i32_f32_e32 v25, v25
	v_cvt_i32_f32_e32 v10, v10
	v_cvt_i32_f32_sdwa v6, v6 dst_sel:WORD_1 dst_unused:UNUSED_PAD src0_sel:DWORD
	v_cvt_i32_f32_e32 v7, v7
	v_lshlrev_b32_e32 v29, 8, v29
	v_lshlrev_b32_e32 v11, 8, v11
	v_and_b32_e32 v29, 0xff00, v29
	v_and_b32_e32 v24, 0xff0000, v24
	v_perm_b32 v25, v25, v28, s26
	v_and_b32_e32 v11, 0xff00, v11
	v_and_b32_e32 v6, 0xff0000, v6
	v_perm_b32 v7, v7, v10, s26
	v_or3_b32 v24, v25, v29, v24
	v_mul_f32_e32 v25, v68, v27
	v_or3_b32 v6, v7, v11, v6
	v_mul_f32_e32 v7, v69, v9
	global_store_dword v[34:35], v24, off offset:512 sc1
	v_mul_f32_e32 v24, v68, v26
	v_rndne_f32_e32 v25, v25
	v_mul_f32_e32 v22, v68, v22
	v_mul_f32_e32 v23, v68, v23
	global_store_dword v[34:35], v6, off offset:2560 sc1
	v_mul_f32_e32 v6, v69, v8
	v_rndne_f32_e32 v7, v7
	v_mul_f32_e32 v4, v69, v4
	v_mul_f32_e32 v5, v69, v5
	v_rndne_f32_e32 v24, v24
	v_cvt_i32_f32_e32 v25, v25
	v_rndne_f32_e32 v22, v22
	v_rndne_f32_e32 v23, v23
	v_rndne_f32_e32 v6, v6
	v_cvt_i32_f32_e32 v7, v7
	v_rndne_f32_e32 v4, v4
	v_rndne_f32_e32 v5, v5
	v_cvt_i32_f32_e32 v24, v24
	v_cvt_i32_f32_sdwa v22, v22 dst_sel:WORD_1 dst_unused:UNUSED_PAD src0_sel:DWORD
	v_cvt_i32_f32_e32 v23, v23
	v_cvt_i32_f32_e32 v6, v6
	v_cvt_i32_f32_sdwa v4, v4 dst_sel:WORD_1 dst_unused:UNUSED_PAD src0_sel:DWORD
	v_cvt_i32_f32_e32 v5, v5
	v_lshlrev_b32_e32 v25, 8, v25
	v_lshlrev_b32_e32 v7, 8, v7
	v_and_b32_e32 v25, 0xff00, v25
	v_and_b32_e32 v22, 0xff0000, v22
	v_perm_b32 v23, v23, v24, s26
	v_and_b32_e32 v7, 0xff00, v7
	v_and_b32_e32 v4, 0xff0000, v4
	v_perm_b32 v5, v5, v6, s26
	v_or3_b32 v22, v23, v25, v22
	v_mul_f32_e32 v23, v68, v57
	v_or3_b32 v4, v5, v7, v4
	v_mul_f32_e32 v5, v69, v74
	global_store_dword v[34:35], v22, off offset:768 sc1
	v_mul_f32_e32 v22, v68, v56
	v_rndne_f32_e32 v23, v23
	v_mul_f32_e32 v24, v68, v58
	v_mul_f32_e32 v25, v68, v59
	global_store_dword v[34:35], v4, off offset:2816 sc1
	v_mul_f32_e32 v4, v69, v75
	v_rndne_f32_e32 v5, v5
	v_mul_f32_e32 v6, v69, v77
	v_mul_f32_e32 v7, v69, v76
	v_rndne_f32_e32 v22, v22
	v_cvt_i32_f32_e32 v23, v23
	v_rndne_f32_e32 v24, v24
	v_rndne_f32_e32 v25, v25
	v_rndne_f32_e32 v4, v4
	v_cvt_i32_f32_e32 v5, v5
	v_rndne_f32_e32 v6, v6
	v_rndne_f32_e32 v7, v7
	v_cvt_i32_f32_e32 v22, v22
	v_cvt_i32_f32_sdwa v24, v24 dst_sel:WORD_1 dst_unused:UNUSED_PAD src0_sel:DWORD
	v_cvt_i32_f32_e32 v25, v25
	v_cvt_i32_f32_e32 v4, v4
	v_cvt_i32_f32_sdwa v6, v6 dst_sel:WORD_1 dst_unused:UNUSED_PAD src0_sel:DWORD
	v_cvt_i32_f32_e32 v7, v7
	v_lshlrev_b32_e32 v23, 8, v23
	v_lshlrev_b32_e32 v5, 8, v5
	v_and_b32_e32 v23, 0xff00, v23
	v_and_b32_e32 v24, 0xff0000, v24
	v_perm_b32 v22, v25, v22, s26
	v_and_b32_e32 v5, 0xff00, v5
	v_and_b32_e32 v6, 0xff0000, v6
	v_perm_b32 v4, v7, v4, s26
	v_or3_b32 v22, v22, v23, v24
	v_mul_f32_e32 v23, v68, v65
	v_or3_b32 v4, v4, v5, v6
	v_mul_f32_e32 v5, v69, v45
	global_store_dword v[34:35], v22, off offset:1024 sc1
	v_mul_f32_e32 v22, v68, v64
	v_rndne_f32_e32 v23, v23
	v_mul_f32_e32 v24, v68, v66
	v_mul_f32_e32 v25, v68, v67
	global_store_dword v[34:35], v4, off offset:3072 sc1
	v_mul_f32_e32 v4, v69, v44
	v_rndne_f32_e32 v5, v5
	v_mul_f32_e32 v6, v69, v52
	v_mul_f32_e32 v7, v69, v53
	v_rndne_f32_e32 v22, v22
	v_cvt_i32_f32_e32 v23, v23
	v_rndne_f32_e32 v24, v24
	v_rndne_f32_e32 v25, v25
	v_rndne_f32_e32 v4, v4
	v_cvt_i32_f32_e32 v5, v5
	v_rndne_f32_e32 v6, v6
	v_rndne_f32_e32 v7, v7
	v_cvt_i32_f32_e32 v22, v22
	v_cvt_i32_f32_sdwa v24, v24 dst_sel:WORD_1 dst_unused:UNUSED_PAD src0_sel:DWORD
	v_cvt_i32_f32_e32 v25, v25
	v_cvt_i32_f32_e32 v4, v4
	v_cvt_i32_f32_sdwa v6, v6 dst_sel:WORD_1 dst_unused:UNUSED_PAD src0_sel:DWORD
	v_cvt_i32_f32_e32 v7, v7
	v_lshlrev_b32_e32 v23, 8, v23
	v_lshlrev_b32_e32 v5, 8, v5
	v_and_b32_e32 v23, 0xff00, v23
	v_and_b32_e32 v24, 0xff0000, v24
	v_perm_b32 v22, v25, v22, s26
	v_and_b32_e32 v5, 0xff00, v5
	v_and_b32_e32 v6, 0xff0000, v6
	v_perm_b32 v4, v7, v4, s26
	v_or3_b32 v22, v22, v23, v24
	v_mul_f32_e32 v23, v68, v63
	v_or3_b32 v4, v4, v5, v6
	v_mul_f32_e32 v5, v69, v47
	global_store_dword v[34:35], v22, off offset:1280 sc1
	v_mul_f32_e32 v22, v68, v62
	v_rndne_f32_e32 v23, v23
	v_mul_f32_e32 v24, v68, v60
	v_mul_f32_e32 v25, v68, v61
	global_store_dword v[34:35], v4, off offset:3328 sc1
	v_mul_f32_e32 v4, v69, v46
	v_rndne_f32_e32 v5, v5
	v_mul_f32_e32 v6, v69, v48
	v_mul_f32_e32 v7, v69, v49
	v_rndne_f32_e32 v22, v22
	v_cvt_i32_f32_e32 v23, v23
	v_rndne_f32_e32 v24, v24
	v_rndne_f32_e32 v25, v25
	v_rndne_f32_e32 v4, v4
	v_cvt_i32_f32_e32 v5, v5
	v_rndne_f32_e32 v6, v6
	v_rndne_f32_e32 v7, v7
	v_cvt_i32_f32_e32 v22, v22
	v_cvt_i32_f32_sdwa v24, v24 dst_sel:WORD_1 dst_unused:UNUSED_PAD src0_sel:DWORD
	v_cvt_i32_f32_e32 v25, v25
	v_cvt_i32_f32_e32 v4, v4
	v_cvt_i32_f32_sdwa v6, v6 dst_sel:WORD_1 dst_unused:UNUSED_PAD src0_sel:DWORD
	v_cvt_i32_f32_e32 v7, v7
	v_lshlrev_b32_e32 v23, 8, v23
	v_lshlrev_b32_e32 v5, 8, v5
	v_and_b32_e32 v23, 0xff00, v23
	v_and_b32_e32 v24, 0xff0000, v24
	v_perm_b32 v22, v25, v22, s26
	v_and_b32_e32 v5, 0xff00, v5
	v_and_b32_e32 v6, 0xff0000, v6
	v_perm_b32 v4, v7, v4, s26
	v_or3_b32 v22, v22, v23, v24
	v_mul_f32_e32 v23, v68, v70
	v_mul_f32_e32 v21, v69, v21
	v_or3_b32 v4, v4, v5, v6
	v_mul_f32_e32 v5, v69, v50
	global_store_dword v[34:35], v22, off offset:1536 sc1
	v_mul_f32_e32 v22, v68, v71
	v_rndne_f32_e32 v23, v23
	v_mul_f32_e32 v24, v68, v73
	v_mul_f32_e32 v25, v68, v72
	v_mul_f32_e32 v20, v69, v20
	v_rndne_f32_e32 v21, v21
	v_mul_f32_e32 v16, v69, v16
	v_mul_f32_e32 v17, v69, v17
	global_store_dword v[34:35], v4, off offset:3584 sc1
	v_mul_f32_e32 v4, v69, v51
	v_rndne_f32_e32 v5, v5
	v_mul_f32_e32 v6, v69, v55
	v_mul_f32_e32 v7, v69, v54
	v_rndne_f32_e32 v22, v22
	v_cvt_i32_f32_e32 v23, v23
	v_rndne_f32_e32 v24, v24
	v_rndne_f32_e32 v25, v25
	v_rndne_f32_e32 v20, v20
	v_cvt_i32_f32_e32 v21, v21
	v_rndne_f32_e32 v16, v16
	v_rndne_f32_e32 v17, v17
	v_rndne_f32_e32 v4, v4
	v_cvt_i32_f32_e32 v5, v5
	v_rndne_f32_e32 v6, v6
	v_rndne_f32_e32 v7, v7
	v_cvt_i32_f32_e32 v22, v22
	v_cvt_i32_f32_sdwa v24, v24 dst_sel:WORD_1 dst_unused:UNUSED_PAD src0_sel:DWORD
	v_cvt_i32_f32_e32 v25, v25
	v_cvt_i32_f32_e32 v20, v20
	v_cvt_i32_f32_sdwa v16, v16 dst_sel:WORD_1 dst_unused:UNUSED_PAD src0_sel:DWORD
	v_cvt_i32_f32_e32 v17, v17
	v_cvt_i32_f32_e32 v4, v4
	v_cvt_i32_f32_sdwa v6, v6 dst_sel:WORD_1 dst_unused:UNUSED_PAD src0_sel:DWORD
	v_cvt_i32_f32_e32 v7, v7
	v_lshlrev_b32_e32 v23, 8, v23
	v_lshlrev_b32_e32 v21, 8, v21
	v_lshlrev_b32_e32 v5, 8, v5
	v_and_b32_e32 v23, 0xff00, v23
	v_and_b32_e32 v24, 0xff0000, v24
	v_perm_b32 v22, v25, v22, s26
	v_and_b32_e32 v21, 0xff00, v21
	v_and_b32_e32 v16, 0xff0000, v16
	v_perm_b32 v17, v17, v20, s26
	v_and_b32_e32 v5, 0xff00, v5
	v_and_b32_e32 v6, 0xff0000, v6
	v_perm_b32 v4, v7, v4, s26
	v_or3_b32 v22, v22, v23, v24
	v_or3_b32 v16, v17, v21, v16
	v_or3_b32 v4, v4, v5, v6
	global_store_dword v[34:35], v36, off sc1
	global_store_dword v[34:35], v22, off offset:1792 sc1
	global_store_dword v[34:35], v16, off offset:2048 sc1
	global_store_dword v[34:35], v4, off offset:3840 sc1
	s_and_saveexec_b64 s[6:7], s[4:5]
	s_cbranch_execz .LBB0_567
	global_store_dwordx2 v41, v[18:19], s[24:25] sc1
	s_branch .LBB0_567

.LBB0_706:
	v_lshl_add_u64 v[6:7], s[18:19], 0, v[4:5]
	v_add_co_u32_e32 v8, vcc, 0x23000000, v6
	s_add_u32 s26, s18, s10
	s_nop 0
	v_addc_co_u32_e32 v9, vcc, 0, v7, vcc
	global_load_dwordx2 v[10:11], v[8:9], off nt
	global_load_dwordx2 v[12:13], v[8:9], off offset:512 nt
	global_load_dwordx2 v[14:15], v[8:9], off offset:1024 nt
	global_load_dwordx2 v[16:17], v[8:9], off offset:1536 nt
	global_load_dwordx2 v[18:19], v[8:9], off offset:2048 nt
	global_load_dwordx2 v[20:21], v[8:9], off offset:2560 nt
	global_load_dwordx2 v[22:23], v[8:9], off offset:3072 nt
	v_add_co_u32_e32 v24, vcc, s2, v6
	s_addc_u32 s27, s19, s11
	s_nop 0
	v_addc_co_u32_e32 v25, vcc, 0, v7, vcc
	global_load_dwordx2 v[28:29], v[8:9], off offset:3584 nt
	global_load_dwordx2 v[36:37], v[24:25], off nt
	global_load_dwordx2 v[38:39], v[24:25], off offset:512 nt
	global_load_dwordx2 v[40:41], v[24:25], off offset:1024 nt
	global_load_dwordx2 v[42:43], v[24:25], off offset:1536 nt
	global_load_dwordx2 v[44:45], v[24:25], off offset:2048 nt
	global_load_dwordx2 v[46:47], v[24:25], off offset:2560 nt
	global_load_dwordx2 v[52:53], v[24:25], off offset:3072 nt
	global_load_dwordx2 v[58:59], v[24:25], off offset:3584 nt
	global_load_dword v35, v31, s[26:27]
	v_add_co_u32_e32 v48, vcc, 0x16e00000, v6
	s_waitcnt vmcnt(16)
	v_and_b32_e32 v61, 0xffff0000, v10
	v_and_b32_e32 v67, 0xffff0000, v11
	s_waitcnt vmcnt(15)
	v_and_b32_e32 v72, 0xffff0000, v12
	v_and_b32_e32 v76, 0xffff0000, v13
	v_lshlrev_b32_e32 v51, 16, v10
	v_lshlrev_b32_e32 v62, 16, v11
	v_lshlrev_b32_e32 v69, 16, v12
	v_lshlrev_b32_e32 v74, 16, v13
	s_waitcnt vmcnt(14)
	v_and_b32_e32 v83, 0xffff0000, v14
	v_and_b32_e32 v86, 0xffff0000, v15
	v_mul_f32_e32 v8, v61, v61
	v_mul_f32_e32 v9, v67, v67
	v_mul_f32_e32 v10, v72, v72
	v_mul_f32_e32 v11, v76, v76
	v_lshlrev_b32_e32 v78, 16, v14
	v_lshlrev_b32_e32 v84, 16, v15
	s_waitcnt vmcnt(13)
	v_and_b32_e32 v93, 0xffff0000, v16
	v_and_b32_e32 v107, 0xffff0000, v17
	v_mul_f32_e32 v12, v83, v83
	v_mul_f32_e32 v13, v86, v86
	v_fmac_f32_e32 v8, v51, v51
	v_fmac_f32_e32 v9, v62, v62
	v_fmac_f32_e32 v10, v69, v69
	v_fmac_f32_e32 v11, v74, v74
	v_lshlrev_b32_e32 v88, 16, v16
	v_lshlrev_b32_e32 v106, 16, v17
	s_waitcnt vmcnt(12)
	v_and_b32_e32 v109, 0xffff0000, v18
	v_and_b32_e32 v111, 0xffff0000, v19
	v_mul_f32_e32 v14, v93, v93
	v_mul_f32_e32 v15, v107, v107
	v_fmac_f32_e32 v12, v78, v78
	v_fmac_f32_e32 v13, v84, v84
	v_add_f32_e32 v8, v8, v9
	v_add_f32_e32 v9, v10, v11
	v_lshlrev_b32_e32 v108, 16, v18
	v_lshlrev_b32_e32 v110, 16, v19
	s_waitcnt vmcnt(11)
	v_and_b32_e32 v113, 0xffff0000, v20
	v_and_b32_e32 v115, 0xffff0000, v21
	v_mul_f32_e32 v16, v109, v109
	v_mul_f32_e32 v17, v111, v111
	v_fmac_f32_e32 v14, v88, v88
	v_fmac_f32_e32 v15, v106, v106
	v_add_f32_e32 v10, v12, v13
	v_add_f32_e32 v8, v8, v9
	v_lshlrev_b32_e32 v112, 16, v20
	v_lshlrev_b32_e32 v114, 16, v21
	v_mul_f32_e32 v18, v113, v113
	v_mul_f32_e32 v19, v115, v115
	v_fmac_f32_e32 v16, v108, v108
	v_fmac_f32_e32 v17, v110, v110
	v_add_f32_e32 v11, v14, v15
	v_add_f32_e32 v8, v8, v10
	v_fmac_f32_e32 v18, v112, v112
	v_add_f32_e32 v12, v16, v17
	v_add_f32_e32 v8, v8, v11
	v_fmac_f32_e32 v19, v114, v114
	v_add_f32_e32 v8, v8, v12
	v_add_f32_e32 v9, v18, v19
	s_waitcnt vmcnt(10)
	v_and_b32_e32 v117, 0xffff0000, v22
	v_and_b32_e32 v119, 0xffff0000, v23
	v_add_f32_e32 v8, v8, v9
	v_lshlrev_b32_e32 v116, 16, v22
	v_lshlrev_b32_e32 v118, 16, v23
	v_mul_f32_e32 v9, v117, v117
	v_mul_f32_e32 v10, v119, v119
	v_fmac_f32_e32 v9, v116, v116
	v_fmac_f32_e32 v10, v118, v118
	v_add_f32_e32 v9, v9, v10
	s_waitcnt vmcnt(9)
	v_and_b32_e32 v121, 0xffff0000, v28
	v_and_b32_e32 v123, 0xffff0000, v29
	v_add_f32_e32 v8, v8, v9
	v_lshlrev_b32_e32 v120, 16, v28
	v_lshlrev_b32_e32 v122, 16, v29
	v_mul_f32_e32 v9, v121, v121
	v_mul_f32_e32 v10, v123, v123
	v_fmac_f32_e32 v9, v120, v120
	v_fmac_f32_e32 v10, v122, v122
	v_add_f32_e32 v9, v9, v10
	s_waitcnt vmcnt(8)
	v_and_b32_e32 v125, 0xffff0000, v36
	v_and_b32_e32 v91, 0xffff0000, v37
	v_add_f32_e32 v8, v8, v9
	v_lshlrev_b32_e32 v124, 16, v36
	v_lshlrev_b32_e32 v92, 16, v37
	v_mul_f32_e32 v9, v125, v125
	v_mul_f32_e32 v10, v91, v91
	v_fmac_f32_e32 v9, v124, v124
	v_fmac_f32_e32 v10, v92, v92
	v_add_f32_e32 v9, v9, v10
	s_waitcnt vmcnt(7)
	v_and_b32_e32 v89, 0xffff0000, v38
	v_and_b32_e32 v85, 0xffff0000, v39
	v_add_f32_e32 v8, v8, v9
	v_lshlrev_b32_e32 v90, 16, v38
	v_lshlrev_b32_e32 v87, 16, v39
	v_mul_f32_e32 v9, v89, v89
	v_mul_f32_e32 v10, v85, v85
	v_fmac_f32_e32 v9, v90, v90
	v_fmac_f32_e32 v10, v87, v87
	v_addc_co_u32_e32 v49, vcc, 0, v7, vcc
	v_add_f32_e32 v9, v9, v10
	s_waitcnt vmcnt(6)
	v_and_b32_e32 v81, 0xffff0000, v40
	v_and_b32_e32 v79, 0xffff0000, v41
	global_load_dwordx2 v[26:27], v[48:49], off nt
	v_add_f32_e32 v8, v8, v9
	v_lshlrev_b32_e32 v82, 16, v40
	v_lshlrev_b32_e32 v80, 16, v41
	v_mul_f32_e32 v9, v81, v81
	v_mul_f32_e32 v10, v79, v79
	v_fmac_f32_e32 v9, v82, v82
	v_fmac_f32_e32 v10, v80, v80
	v_add_f32_e32 v9, v9, v10
	s_waitcnt vmcnt(6)
	v_and_b32_e32 v75, 0xffff0000, v42
	v_and_b32_e32 v71, 0xffff0000, v43
	v_add_f32_e32 v8, v8, v9
	v_lshlrev_b32_e32 v77, 16, v42
	v_lshlrev_b32_e32 v73, 16, v43
	v_mul_f32_e32 v9, v75, v75
	v_mul_f32_e32 v10, v71, v71
	v_fmac_f32_e32 v9, v77, v77
	v_fmac_f32_e32 v10, v73, v73
	v_add_f32_e32 v9, v9, v10
	s_waitcnt vmcnt(5)
	v_and_b32_e32 v68, 0xffff0000, v44
	v_and_b32_e32 v63, 0xffff0000, v45
	v_add_f32_e32 v8, v8, v9
	v_lshlrev_b32_e32 v70, 16, v44
	v_lshlrev_b32_e32 v66, 16, v45
	v_mul_f32_e32 v9, v68, v68
	v_mul_f32_e32 v10, v63, v63
	v_fmac_f32_e32 v9, v70, v70
	v_fmac_f32_e32 v10, v66, v66
	v_add_f32_e32 v9, v9, v10
	s_waitcnt vmcnt(4)
	v_and_b32_e32 v56, 0xffff0000, v46
	v_and_b32_e32 v54, 0xffff0000, v47
	v_add_f32_e32 v8, v8, v9
	v_lshlrev_b32_e32 v57, 16, v46
	v_lshlrev_b32_e32 v55, 16, v47
	v_mul_f32_e32 v9, v56, v56
	v_mul_f32_e32 v10, v54, v54
	v_fmac_f32_e32 v9, v57, v57
	v_fmac_f32_e32 v10, v55, v55
	v_add_f32_e32 v9, v9, v10
	s_waitcnt vmcnt(3)
	v_and_b32_e32 v47, 0xffff0000, v52
	v_and_b32_e32 v42, 0xffff0000, v53
	v_add_f32_e32 v8, v8, v9
	v_lshlrev_b32_e32 v50, 16, v52
	v_lshlrev_b32_e32 v45, 16, v53
	v_mul_f32_e32 v9, v47, v47
	v_mul_f32_e32 v10, v42, v42
	v_fmac_f32_e32 v9, v50, v50
	v_fmac_f32_e32 v10, v45, v45
	s_waitcnt vmcnt(2)
	v_lshlrev_b32_e32 v41, 16, v58
	v_and_b32_e32 v40, 0xffff0000, v58
	v_lshlrev_b32_e32 v39, 16, v59
	v_and_b32_e32 v37, 0xffff0000, v59
	global_load_dwordx2 v[52:53], v[48:49], off offset:512 nt
	global_load_dwordx2 v[58:59], v[48:49], off offset:1024 nt
	global_load_dwordx2 v[64:65], v[48:49], off offset:1536 nt
	v_add_f32_e32 v9, v9, v10
	v_add_f32_e32 v8, v8, v9
	v_mul_f32_e32 v9, v40, v40
	v_mul_f32_e32 v10, v37, v37
	v_fmac_f32_e32 v9, v41, v41
	v_fmac_f32_e32 v10, v39, v39
	v_add_f32_e32 v9, v9, v10
	v_add_f32_e32 v8, v8, v9
	ds_swizzle_b32 v9, v8 offset:swizzle(SWAP,1)
	global_load_dwordx2 v[102:103], v[48:49], off offset:2048 nt
	global_load_dwordx2 v[28:29], v[48:49], off offset:2560 nt
	global_load_dwordx2 v[24:25], v[48:49], off offset:3072 nt
	global_load_dwordx2 v[22:23], v[48:49], off offset:3584 nt
	v_add_co_u32_e32 v48, vcc, s28, v6
	s_waitcnt lgkmcnt(0)
	v_add_f32_e32 v8, v8, v9
	ds_swizzle_b32 v9, v8 offset:swizzle(SWAP,2)
	v_addc_co_u32_e32 v49, vcc, 0, v7, vcc
	global_load_dwordx2 v[20:21], v[48:49], off nt
	global_load_dwordx2 v[18:19], v[48:49], off offset:512 nt
	global_load_dwordx2 v[16:17], v[48:49], off offset:1024 nt
	global_load_dwordx2 v[14:15], v[48:49], off offset:1536 nt
	s_waitcnt lgkmcnt(0)
	v_add_f32_e32 v8, v8, v9
	ds_swizzle_b32 v9, v8 offset:swizzle(SWAP,4)
	s_waitcnt lgkmcnt(0)
	v_add_f32_e32 v8, v8, v9
	ds_swizzle_b32 v9, v8 offset:swizzle(SWAP,8)
	s_waitcnt lgkmcnt(0)
	v_add_f32_e32 v8, v8, v9
	ds_swizzle_b32 v9, v8 offset:swizzle(SWAP,16)
	s_waitcnt lgkmcnt(0)
	v_add_f32_e32 v6, v8, v9
	v_mov_b32_e32 v7, v6
	s_nop 1
	v_permlane32_swap_b32_e32 v6, v7
	v_add_f32_e32 v6, v6, v7
	v_fmamk_f32 v6, v6, 0x39800000, v32
	v_mul_f32_e32 v7, 0x4f800000, v6
	v_cmp_gt_f32_e32 vcc, s29, v6
	s_nop 1
	v_cndmask_b32_e32 v6, v6, v7, vcc
	v_sqrt_f32_e32 v7, v6
	s_nop 0
	v_add_u32_e32 v8, -1, v7
	v_fma_f32 v9, -v8, v7, v6
	v_cmp_ge_f32_e64 s[8:9], 0, v9
	v_add_u32_e32 v9, 1, v7
	s_nop 0
	v_cndmask_b32_e64 v8, v7, v8, s[8:9]
	v_fma_f32 v7, -v9, v7, v6
	v_cmp_lt_f32_e64 s[8:9], 0, v7
	s_nop 1
	v_cndmask_b32_e64 v7, v8, v9, s[8:9]
	v_mul_f32_e32 v8, 0x37800000, v7
	v_cndmask_b32_e32 v7, v7, v8, vcc
	v_cmp_class_f32_e32 vcc, v6, v33
	s_nop 1
	v_cndmask_b32_e32 v36, v7, v6, vcc
	v_div_scale_f32 v38, s[8:9], v36, v36, 1.0
	v_rcp_f32_e32 v43, v38
	global_load_dwordx2 v[12:13], v[48:49], off offset:2048 nt
	global_load_dwordx2 v[10:11], v[48:49], off offset:2560 nt
	global_load_dwordx2 v[8:9], v[48:49], off offset:3072 nt
	global_load_dwordx2 v[6:7], v[48:49], off offset:3584 nt
	ds_read_b128 v[94:97], v30
	ds_read_b128 v[98:101], v30 offset:32768
	v_fma_f32 v44, -v38, v43, 1.0
	v_fmac_f32_e32 v43, v44, v43
	v_div_scale_f32 v44, vcc, 1.0, v36, 1.0
	v_mul_f32_e32 v46, v44, v43
	v_fma_f32 v48, -v38, v46, v44
	v_fmac_f32_e32 v46, v48, v43
	v_fma_f32 v38, -v38, v46, v44
	v_div_fmas_f32 v38, v38, v43, v46
	v_div_fixup_f32 v60, v38, v36, 1.0
	s_waitcnt vmcnt(15)
	v_lshlrev_b32_e32 v36, 16, v26
	v_mul_f32_e32 v36, v35, v36
	v_and_b32_e32 v26, 0xffff0000, v26
	s_waitcnt lgkmcnt(0)
	v_mul_f32_e32 v36, v98, v36
	v_mul_f32_e32 v38, v60, v51
	v_mul_f32_e32 v26, v35, v26
	v_fmac_f32_e32 v36, v94, v38
	v_mul_f32_e32 v26, v99, v26
	v_mul_f32_e32 v38, v60, v61
	v_fmac_f32_e32 v26, v95, v38
	v_lshlrev_b32_e32 v38, 16, v27
	v_mul_f32_e32 v38, v35, v38
	v_and_b32_e32 v27, 0xffff0000, v27
	v_mul_f32_e32 v38, v100, v38
	v_mul_f32_e32 v43, v60, v62
	v_mul_f32_e32 v27, v35, v27
	v_fmac_f32_e32 v38, v96, v43
	v_mul_f32_e32 v27, v101, v27
	v_mul_f32_e32 v43, v60, v67
	v_fmac_f32_e32 v27, v97, v43
	v_cvt_pk_bf16_f32 v48, v36, v26
	v_cvt_pk_bf16_f32 v49, v38, v27
	ds_read_b128 v[94:97], v30 offset:1024
	ds_read_b128 v[98:101], v30 offset:33792
	v_mul_f32_e32 v43, v26, v26
	v_mul_f32_e32 v44, v27, v27
	v_fmac_f32_e32 v43, v36, v36
	v_fmac_f32_e32 v44, v38, v38
	v_add_f32_e32 v51, v43, v44
	s_waitcnt vmcnt(14)
	v_lshlrev_b32_e32 v43, 16, v52
	v_mul_f32_e32 v43, v35, v43
	s_waitcnt lgkmcnt(0)
	v_mul_f32_e32 v43, v98, v43
	v_mul_f32_e32 v44, v60, v69
	v_fmac_f32_e32 v43, v94, v44
	v_and_b32_e32 v44, 0xffff0000, v52
	v_mul_f32_e32 v44, v35, v44
	v_mul_f32_e32 v44, v99, v44
	v_mul_f32_e32 v46, v60, v72
	v_add_co_u32_e32 v104, vcc, s30, v2
	v_fmac_f32_e32 v44, v95, v46
	v_lshlrev_b32_e32 v46, 16, v53
	v_addc_co_u32_e32 v105, vcc, -1, v3, vcc
	v_mul_f32_e32 v46, v35, v46
	global_store_dwordx2 v[104:105], v[48:49], off offset:-3584 sc1
	v_mul_f32_e32 v46, v100, v46
	v_mul_f32_e32 v48, v60, v74
	v_fmac_f32_e32 v46, v96, v48
	v_and_b32_e32 v48, 0xffff0000, v53
	v_mul_f32_e32 v48, v35, v48
	v_mul_f32_e32 v48, v101, v48
	v_mul_f32_e32 v49, v60, v76
	v_fmac_f32_e32 v48, v97, v49
	v_mul_f32_e32 v49, v44, v44
	v_mul_f32_e32 v52, v48, v48
	v_fmac_f32_e32 v49, v43, v43
	v_fmac_f32_e32 v52, v46, v46
	v_add_f32_e32 v49, v49, v52
	v_cvt_pk_bf16_f32 v52, v43, v44
	v_cvt_pk_bf16_f32 v53, v46, v48
	ds_read_b128 v[94:97], v30 offset:2048
	ds_read_b128 v[98:101], v30 offset:34816
	v_add_f32_e32 v61, v51, v49
	s_waitcnt vmcnt(14)
	v_lshlrev_b32_e32 v49, 16, v58
	v_mul_f32_e32 v49, v35, v49
	v_mul_f32_e32 v51, v60, v78
	s_waitcnt lgkmcnt(0)
	v_mul_f32_e32 v49, v98, v49
	v_fmac_f32_e32 v49, v94, v51
	v_and_b32_e32 v51, 0xffff0000, v58
	v_mul_f32_e32 v51, v35, v51
	global_store_dwordx2 v[104:105], v[52:53], off offset:-3072 sc1
	v_mul_f32_e32 v51, v99, v51
	v_mul_f32_e32 v52, v60, v83
	v_fmac_f32_e32 v51, v95, v52
	v_lshlrev_b32_e32 v52, 16, v59
	v_mul_f32_e32 v52, v35, v52
	v_mul_f32_e32 v52, v100, v52
	v_mul_f32_e32 v53, v60, v84
	v_fmac_f32_e32 v52, v96, v53
	v_and_b32_e32 v53, 0xffff0000, v59
	v_mul_f32_e32 v53, v35, v53
	v_mul_f32_e32 v53, v101, v53
	v_mul_f32_e32 v58, v60, v86
	v_fmac_f32_e32 v53, v97, v58
	v_mul_f32_e32 v58, v51, v51
	v_mul_f32_e32 v59, v53, v53
	v_fmac_f32_e32 v58, v49, v49
	v_fmac_f32_e32 v59, v52, v52
	v_add_f32_e32 v62, v58, v59
	v_cvt_pk_bf16_f32 v58, v49, v51
	v_cvt_pk_bf16_f32 v59, v52, v53
	ds_read_b128 v[94:97], v30 offset:3072
	ds_read_b128 v[98:101], v30 offset:35840
	global_store_dwordx2 v[104:105], v[58:59], off offset:-2560 sc1
	s_waitcnt vmcnt(15)
	v_lshlrev_b32_e32 v58, 16, v64
	v_mul_f32_e32 v58, v35, v58
	v_mul_f32_e32 v59, v60, v88
	s_waitcnt lgkmcnt(0)
	v_mul_f32_e32 v58, v98, v58
	v_fmac_f32_e32 v58, v94, v59
	v_and_b32_e32 v59, 0xffff0000, v64
	v_mul_f32_e32 v59, v35, v59
	v_add_f32_e32 v67, v61, v62
	v_mul_f32_e32 v59, v99, v59
	v_mul_f32_e32 v61, v60, v93
	v_fmac_f32_e32 v59, v95, v61
	v_lshlrev_b32_e32 v61, 16, v65
	v_mul_f32_e32 v61, v35, v61
	v_mul_f32_e32 v61, v100, v61
	v_mul_f32_e32 v62, v60, v106
	v_fmac_f32_e32 v61, v96, v62
	v_and_b32_e32 v62, 0xffff0000, v65
	v_mul_f32_e32 v62, v35, v62
	v_mul_f32_e32 v62, v101, v62
	v_mul_f32_e32 v64, v60, v107
	v_fmac_f32_e32 v62, v97, v64
	v_cvt_pk_bf16_f32 v64, v58, v59
	v_cvt_pk_bf16_f32 v65, v61, v62
	global_store_dwordx2 v[104:105], v[64:65], off offset:-2048 sc1
	v_mul_f32_e32 v69, v59, v59
	v_mul_f32_e32 v72, v62, v62
	ds_read_b128 v[94:97], v30 offset:4096
	ds_read_b128 v[98:101], v30 offset:36864
	v_fmac_f32_e32 v69, v58, v58
	v_fmac_f32_e32 v72, v61, v61
	v_add_f32_e32 v64, v69, v72
	v_add_f32_e32 v72, v67, v64
	s_waitcnt vmcnt(15)
	v_lshlrev_b32_e32 v64, 16, v102
	v_mul_f32_e32 v64, v35, v64
	s_waitcnt lgkmcnt(0)
	v_mul_f32_e32 v64, v98, v64
	v_mul_f32_e32 v65, v60, v108
	v_fmac_f32_e32 v64, v94, v65
	v_and_b32_e32 v65, 0xffff0000, v102
	v_mul_f32_e32 v65, v35, v65
	v_mul_f32_e32 v65, v99, v65
	v_mul_f32_e32 v67, v60, v109
	v_fmac_f32_e32 v65, v95, v67
	v_lshlrev_b32_e32 v67, 16, v103
	v_mul_f32_e32 v67, v35, v67
	v_mul_f32_e32 v67, v100, v67
	v_mul_f32_e32 v69, v60, v110
	v_fmac_f32_e32 v67, v96, v69
	v_and_b32_e32 v69, 0xffff0000, v103
	v_mul_f32_e32 v69, v35, v69
	v_mul_f32_e32 v69, v101, v69
	v_mul_f32_e32 v74, v60, v111
	v_fmac_f32_e32 v69, v97, v74
	v_mul_f32_e32 v74, v65, v65
	v_mul_f32_e32 v76, v69, v69
	v_cvt_pk_bf16_f32 v102, v64, v65
	v_cvt_pk_bf16_f32 v103, v67, v69
	ds_read_b128 v[94:97], v30 offset:5120
	ds_read_b128 v[98:101], v30 offset:37888
	v_fmac_f32_e32 v74, v64, v64
	v_fmac_f32_e32 v76, v67, v67
	v_add_f32_e32 v74, v74, v76
	v_add_f32_e32 v76, v72, v74
	s_waitcnt vmcnt(14)
	v_lshlrev_b32_e32 v72, 16, v28
	v_mul_f32_e32 v72, v35, v72
	v_and_b32_e32 v28, 0xffff0000, v28
	s_waitcnt lgkmcnt(0)
	v_mul_f32_e32 v72, v98, v72
	v_mul_f32_e32 v74, v60, v112
	v_mul_f32_e32 v28, v35, v28
	v_fmac_f32_e32 v72, v94, v74
	v_mul_f32_e32 v28, v99, v28
	v_mul_f32_e32 v74, v60, v113
	v_fmac_f32_e32 v28, v95, v74
	v_lshlrev_b32_e32 v74, 16, v29
	v_mul_f32_e32 v74, v35, v74
	v_and_b32_e32 v29, 0xffff0000, v29
	v_mul_f32_e32 v74, v100, v74
	v_mul_f32_e32 v78, v60, v114
	v_mul_f32_e32 v29, v35, v29
	v_fmac_f32_e32 v74, v96, v78
	v_mul_f32_e32 v29, v101, v29
	v_mul_f32_e32 v78, v60, v115
	v_fmac_f32_e32 v29, v97, v78
	global_store_dwordx2 v[104:105], v[102:103], off offset:-1536 sc1
	v_mul_f32_e32 v78, v28, v28
	v_mul_f32_e32 v83, v29, v29
	v_cvt_pk_bf16_f32 v102, v72, v28
	v_cvt_pk_bf16_f32 v103, v74, v29
	ds_read_b128 v[94:97], v30 offset:6144
	ds_read_b128 v[98:101], v30 offset:38912
	v_fmac_f32_e32 v78, v72, v72
	v_fmac_f32_e32 v83, v74, v74
	v_add_f32_e32 v78, v78, v83
	v_add_f32_e32 v83, v76, v78
	s_waitcnt vmcnt(14)
	v_lshlrev_b32_e32 v76, 16, v24
	v_mul_f32_e32 v76, v35, v76
	v_and_b32_e32 v24, 0xffff0000, v24
	s_waitcnt lgkmcnt(0)
	v_mul_f32_e32 v76, v98, v76
	v_mul_f32_e32 v78, v60, v116
	v_mul_f32_e32 v24, v35, v24
	v_fmac_f32_e32 v76, v94, v78
	v_mul_f32_e32 v24, v99, v24
	v_mul_f32_e32 v78, v60, v117
	v_fmac_f32_e32 v24, v95, v78
	v_lshlrev_b32_e32 v78, 16, v25
	v_mul_f32_e32 v78, v35, v78
	v_and_b32_e32 v25, 0xffff0000, v25
	v_mul_f32_e32 v78, v100, v78
	v_mul_f32_e32 v84, v60, v118
	v_mul_f32_e32 v25, v35, v25
	v_fmac_f32_e32 v78, v96, v84
	v_mul_f32_e32 v25, v101, v25
	v_mul_f32_e32 v84, v60, v119
	v_fmac_f32_e32 v25, v97, v84
	global_store_dwordx2 v[104:105], v[102:103], off offset:-1024 sc1
	v_mul_f32_e32 v84, v24, v24
	v_mul_f32_e32 v86, v25, v25
	v_cvt_pk_bf16_f32 v102, v76, v24
	v_cvt_pk_bf16_f32 v103, v78, v25
	ds_read_b128 v[94:97], v30 offset:7168
	ds_read_b128 v[98:101], v30 offset:39936
	v_fmac_f32_e32 v84, v76, v76
	v_fmac_f32_e32 v86, v78, v78
	v_add_f32_e32 v84, v84, v86
	v_add_f32_e32 v86, v83, v84
	s_waitcnt vmcnt(14)
	v_lshlrev_b32_e32 v83, 16, v22
	v_mul_f32_e32 v83, v35, v83
	v_and_b32_e32 v22, 0xffff0000, v22
	s_waitcnt lgkmcnt(0)
	v_mul_f32_e32 v83, v98, v83
	v_mul_f32_e32 v84, v60, v120
	v_mul_f32_e32 v22, v35, v22
	v_fmac_f32_e32 v83, v94, v84
	v_mul_f32_e32 v22, v99, v22
	v_mul_f32_e32 v84, v60, v121
	v_fmac_f32_e32 v22, v95, v84
	v_lshlrev_b32_e32 v84, 16, v23
	v_mul_f32_e32 v84, v35, v84
	v_and_b32_e32 v23, 0xffff0000, v23
	v_mul_f32_e32 v84, v100, v84
	v_mul_f32_e32 v88, v60, v122
	v_mul_f32_e32 v23, v35, v23
	v_fmac_f32_e32 v84, v96, v88
	v_mul_f32_e32 v23, v101, v23
	v_mul_f32_e32 v88, v60, v123
	global_store_dwordx2 v[104:105], v[102:103], off offset:-512 sc1
	v_fmac_f32_e32 v23, v97, v88
	v_cvt_pk_bf16_f32 v94, v83, v22
	v_cvt_pk_bf16_f32 v95, v84, v23
	global_store_dwordx2 v[2:3], v[94:95], off offset:-4096 sc1
	v_mul_f32_e32 v88, v22, v22
	v_mul_f32_e32 v93, v23, v23
	ds_read_b128 v[94:97], v30 offset:8192
	ds_read_b128 v[98:101], v30 offset:40960
	v_fmac_f32_e32 v88, v83, v83
	v_fmac_f32_e32 v93, v84, v84
	v_add_f32_e32 v88, v88, v93
	v_add_f32_e32 v102, v86, v88
	s_waitcnt vmcnt(15)
	v_lshlrev_b32_e32 v86, 16, v20
	v_mul_f32_e32 v86, v35, v86
	v_and_b32_e32 v20, 0xffff0000, v20
	s_waitcnt lgkmcnt(0)
	v_mul_f32_e32 v86, v98, v86
	v_mul_f32_e32 v88, v60, v124
	v_mul_f32_e32 v20, v35, v20
	v_fmac_f32_e32 v86, v94, v88
	v_mul_f32_e32 v20, v99, v20
	v_mul_f32_e32 v88, v60, v125
	v_fmac_f32_e32 v20, v95, v88
	v_lshlrev_b32_e32 v88, 16, v21
	v_and_b32_e32 v21, 0xffff0000, v21
	v_mul_f32_e32 v21, v35, v21
	v_mul_f32_e32 v88, v35, v88
	v_mul_f32_e32 v21, v101, v21
	v_mul_f32_e32 v91, v60, v91
	v_mul_f32_e32 v88, v100, v88
	v_mul_f32_e32 v92, v60, v92
	v_fmac_f32_e32 v21, v97, v91
	v_fmac_f32_e32 v88, v96, v92
	v_mul_f32_e32 v91, v20, v20
	v_mul_f32_e32 v92, v21, v21
	v_fmac_f32_e32 v91, v86, v86
	v_fmac_f32_e32 v92, v88, v88
	v_add_f32_e32 v91, v91, v92
	v_cvt_pk_bf16_f32 v100, v86, v20
	v_cvt_pk_bf16_f32 v101, v88, v21
	ds_read_b128 v[92:95], v30 offset:9216
	ds_read_b128 v[96:99], v30 offset:41984
	v_add_f32_e32 v102, v102, v91
	s_waitcnt vmcnt(14)
	v_lshlrev_b32_e32 v91, 16, v18
	v_and_b32_e32 v18, 0xffff0000, v18
	v_mul_f32_e32 v18, v35, v18
	s_waitcnt lgkmcnt(0)
	v_mul_f32_e32 v18, v97, v18
	v_mul_f32_e32 v89, v60, v89
	v_fmac_f32_e32 v18, v93, v89
	v_lshlrev_b32_e32 v89, 16, v19
	v_and_b32_e32 v19, 0xffff0000, v19
	v_mul_f32_e32 v91, v35, v91
	v_mul_f32_e32 v89, v35, v89
	v_mul_f32_e32 v19, v35, v19
	v_mul_f32_e32 v91, v96, v91
	v_mul_f32_e32 v90, v60, v90
	v_mul_f32_e32 v89, v98, v89
	v_mul_f32_e32 v87, v60, v87
	v_mul_f32_e32 v19, v99, v19
	v_mul_f32_e32 v85, v60, v85
	global_store_dwordx2 v[2:3], v[100:101], off offset:-3584 sc1
	v_fmac_f32_e32 v91, v92, v90
	v_fmac_f32_e32 v89, v94, v87
	v_fmac_f32_e32 v19, v95, v85
	v_cvt_pk_bf16_f32 v100, v91, v18
	v_cvt_pk_bf16_f32 v101, v89, v19
	ds_read_b128 v[92:95], v30 offset:10240
	ds_read_b128 v[96:99], v30 offset:43008
	v_mul_f32_e32 v85, v18, v18
	v_mul_f32_e32 v87, v19, v19
	v_fmac_f32_e32 v85, v91, v91
	v_fmac_f32_e32 v87, v89, v89
	v_add_f32_e32 v85, v85, v87
	s_waitcnt vmcnt(14)
	v_lshlrev_b32_e32 v87, 16, v16
	v_mul_f32_e32 v87, v35, v87
	v_and_b32_e32 v16, 0xffff0000, v16
	s_waitcnt lgkmcnt(0)
	v_mul_f32_e32 v87, v96, v87
	v_mul_f32_e32 v82, v60, v82
	v_mul_f32_e32 v16, v35, v16
	v_fmac_f32_e32 v87, v92, v82
	v_mul_f32_e32 v82, v97, v16
	v_mul_f32_e32 v16, v60, v81
	v_fmac_f32_e32 v82, v93, v16
	v_lshlrev_b32_e32 v16, 16, v17
	v_mul_f32_e32 v16, v35, v16
	v_mul_f32_e32 v81, v98, v16
	v_mul_f32_e32 v16, v60, v80
	v_fmac_f32_e32 v81, v94, v16
	v_and_b32_e32 v16, 0xffff0000, v17
	v_mul_f32_e32 v16, v35, v16
	v_mul_f32_e32 v80, v99, v16
	v_mul_f32_e32 v16, v60, v79
	v_fmac_f32_e32 v80, v95, v16
	v_mul_f32_e32 v16, v82, v82
	v_mul_f32_e32 v17, v80, v80
	v_fmac_f32_e32 v16, v87, v87
	v_fmac_f32_e32 v17, v81, v81
	global_store_dwordx2 v[2:3], v[100:101], off offset:-3072 sc1
	v_add_f32_e32 v79, v16, v17
	v_cvt_pk_bf16_f32 v16, v87, v82
	v_cvt_pk_bf16_f32 v17, v81, v80
	ds_read_b128 v[92:95], v30 offset:11264
	ds_read_b128 v[96:99], v30 offset:44032
	global_store_dwordx2 v[2:3], v[16:17], off offset:-2560 sc1
	s_waitcnt vmcnt(15)
	v_lshlrev_b32_e32 v16, 16, v14
	v_and_b32_e32 v14, 0xffff0000, v14
	v_add_f32_e32 v85, v102, v85
	v_mul_f32_e32 v16, v35, v16
	v_mul_f32_e32 v14, v35, v14
	v_add_f32_e32 v79, v85, v79
	s_waitcnt lgkmcnt(0)
	v_mul_f32_e32 v85, v96, v16
	v_mul_f32_e32 v16, v60, v77
	v_mul_f32_e32 v77, v97, v14
	v_mul_f32_e32 v14, v60, v75
	v_fmac_f32_e32 v77, v93, v14
	v_lshlrev_b32_e32 v14, 16, v15
	v_mul_f32_e32 v14, v35, v14
	v_mul_f32_e32 v75, v98, v14
	v_mul_f32_e32 v14, v60, v73
	v_fmac_f32_e32 v75, v94, v14
	v_and_b32_e32 v14, 0xffff0000, v15
	v_mul_f32_e32 v14, v35, v14
	v_mul_f32_e32 v73, v99, v14
	v_mul_f32_e32 v14, v60, v71
	v_fmac_f32_e32 v85, v92, v16
	v_fmac_f32_e32 v73, v95, v14
	v_cvt_pk_bf16_f32 v14, v85, v77
	v_cvt_pk_bf16_f32 v15, v75, v73
	global_store_dwordx2 v[2:3], v[14:15], off offset:-2048 sc1
	v_mul_f32_e32 v71, v77, v77
	v_mul_f32_e32 v90, v73, v73
	ds_read_b128 v[14:17], v30 offset:12288
	ds_read_b128 v[92:95], v30 offset:45056
	v_fmac_f32_e32 v71, v85, v85
	v_fmac_f32_e32 v90, v75, v75
	v_add_f32_e32 v71, v71, v90
	v_add_f32_e32 v71, v79, v71
	s_waitcnt vmcnt(15)
	v_lshlrev_b32_e32 v79, 16, v12
	v_mul_f32_e32 v79, v35, v79
	v_and_b32_e32 v12, 0xffff0000, v12
	s_waitcnt lgkmcnt(0)
	v_mul_f32_e32 v79, v92, v79
	v_mul_f32_e32 v70, v60, v70
	v_mul_f32_e32 v12, v35, v12
	v_fmac_f32_e32 v79, v14, v70
	v_mul_f32_e32 v70, v93, v12
	v_mul_f32_e32 v12, v60, v68
	v_fmac_f32_e32 v70, v15, v12
	v_lshlrev_b32_e32 v12, 16, v13
	v_mul_f32_e32 v12, v35, v12
	v_mul_f32_e32 v68, v94, v12
	v_mul_f32_e32 v12, v60, v66
	v_fmac_f32_e32 v68, v16, v12
	v_and_b32_e32 v12, 0xffff0000, v13
	v_mul_f32_e32 v12, v35, v12
	v_mul_f32_e32 v66, v95, v12
	v_mul_f32_e32 v12, v60, v63
	v_fmac_f32_e32 v66, v17, v12
	v_mul_f32_e32 v12, v70, v70
	v_mul_f32_e32 v13, v66, v66
	v_fmac_f32_e32 v12, v79, v79
	v_fmac_f32_e32 v13, v68, v68
	v_add_f32_e32 v63, v12, v13
	v_cvt_pk_bf16_f32 v16, v79, v70
	v_cvt_pk_bf16_f32 v17, v68, v66
	ds_read_b128 v[12:15], v30 offset:13312
	ds_read_b128 v[92:95], v30 offset:46080
	global_store_dwordx2 v[2:3], v[16:17], off offset:-1536 sc1
	s_waitcnt vmcnt(15)
	v_lshlrev_b32_e32 v16, 16, v10
	v_and_b32_e32 v10, 0xffff0000, v10
	v_mul_f32_e32 v16, v35, v16
	v_mul_f32_e32 v10, v35, v10
	v_add_f32_e32 v63, v71, v63
	s_waitcnt lgkmcnt(0)
	v_mul_f32_e32 v71, v92, v16
	v_mul_f32_e32 v16, v60, v57
	v_mul_f32_e32 v57, v93, v10
	v_mul_f32_e32 v10, v60, v56
	v_fmac_f32_e32 v57, v13, v10
	v_lshlrev_b32_e32 v10, 16, v11
	v_mul_f32_e32 v10, v35, v10
	v_mul_f32_e32 v56, v94, v10
	v_mul_f32_e32 v10, v60, v55
	v_fmac_f32_e32 v56, v14, v10
	v_and_b32_e32 v10, 0xffff0000, v11
	v_mul_f32_e32 v10, v35, v10
	v_mul_f32_e32 v90, v95, v10
	v_mul_f32_e32 v10, v60, v54
	v_fmac_f32_e32 v90, v15, v10
	v_fmac_f32_e32 v71, v12, v16
	v_mul_f32_e32 v10, v57, v57
	v_mul_f32_e32 v11, v90, v90
	v_fmac_f32_e32 v10, v71, v71
	v_fmac_f32_e32 v11, v56, v56
	v_add_f32_e32 v92, v10, v11
	v_cvt_pk_bf16_f32 v54, v71, v57
	v_cvt_pk_bf16_f32 v55, v56, v90
	ds_read_b128 v[10:13], v30 offset:14336
	ds_read_b128 v[14:17], v30 offset:47104
	global_store_dwordx2 v[2:3], v[54:55], off offset:-1024 sc1
	s_waitcnt vmcnt(15)
	v_lshlrev_b32_e32 v54, 16, v8
	v_and_b32_e32 v8, 0xffff0000, v8
	v_mul_f32_e32 v54, v35, v54
	v_mul_f32_e32 v8, v35, v8
	s_waitcnt lgkmcnt(0)
	v_mul_f32_e32 v54, v14, v54
	v_mul_f32_e32 v14, v60, v50
	v_mul_f32_e32 v50, v15, v8
	v_mul_f32_e32 v8, v60, v47
	v_fmac_f32_e32 v50, v11, v8
	v_lshlrev_b32_e32 v8, 16, v9
	v_mul_f32_e32 v8, v35, v8
	v_mul_f32_e32 v47, v16, v8
	v_mul_f32_e32 v8, v60, v45
	v_fmac_f32_e32 v47, v12, v8
	v_and_b32_e32 v8, 0xffff0000, v9
	v_mul_f32_e32 v8, v35, v8
	v_mul_f32_e32 v45, v17, v8
	v_mul_f32_e32 v8, v60, v42
	v_fmac_f32_e32 v54, v10, v14
	v_fmac_f32_e32 v45, v13, v8
	v_cvt_pk_bf16_f32 v16, v54, v50
	v_cvt_pk_bf16_f32 v17, v47, v45
	ds_read_b128 v[8:11], v30 offset:15360
	ds_read_b128 v[12:15], v30 offset:48128
	v_mul_f32_e32 v42, v50, v50
	v_mul_f32_e32 v55, v45, v45
	v_fmac_f32_e32 v42, v54, v54
	v_fmac_f32_e32 v55, v47, v47
	v_add_f32_e32 v42, v42, v55
	s_waitcnt vmcnt(14)
	v_lshlrev_b32_e32 v55, 16, v6
	v_and_b32_e32 v6, 0xffff0000, v6
	v_mul_f32_e32 v55, v35, v55
	v_mul_f32_e32 v6, v35, v6
	s_waitcnt lgkmcnt(0)
	v_mul_f32_e32 v55, v12, v55
	v_mul_f32_e32 v12, v60, v41
	v_mul_f32_e32 v41, v13, v6
	v_mul_f32_e32 v6, v60, v40
	v_fmac_f32_e32 v41, v9, v6
	v_lshlrev_b32_e32 v6, 16, v7
	v_mul_f32_e32 v6, v35, v6
	v_mul_f32_e32 v14, v14, v6
	v_mul_f32_e32 v6, v60, v39
	v_fmac_f32_e32 v14, v10, v6
	v_and_b32_e32 v6, 0xffff0000, v7
	v_mul_f32_e32 v6, v35, v6
	v_mul_f32_e32 v15, v15, v6
	v_mul_f32_e32 v6, v60, v37
	v_fmac_f32_e32 v15, v11, v6
	v_fmac_f32_e32 v55, v8, v12
	v_mul_f32_e32 v6, v41, v41
	v_mul_f32_e32 v7, v15, v15
	v_add_f32_e32 v63, v63, v92
	v_fmac_f32_e32 v6, v55, v55
	v_fmac_f32_e32 v7, v14, v14
	v_add_f32_e32 v42, v63, v42
	v_add_f32_e32 v6, v6, v7
	v_add_f32_e32 v6, v42, v6
	ds_swizzle_b32 v7, v6 offset:swizzle(SWAP,1)
	global_store_dwordx2 v[2:3], v[16:17], off offset:-512 sc1
	s_waitcnt lgkmcnt(0)
	v_add_f32_e32 v6, v6, v7
	ds_swizzle_b32 v7, v6 offset:swizzle(SWAP,2)
	s_waitcnt lgkmcnt(0)
	v_add_f32_e32 v6, v6, v7
	ds_swizzle_b32 v7, v6 offset:swizzle(SWAP,4)
	s_waitcnt lgkmcnt(0)
	v_add_f32_e32 v6, v6, v7
	ds_swizzle_b32 v7, v6 offset:swizzle(SWAP,8)
	s_waitcnt lgkmcnt(0)
	v_add_f32_e32 v6, v6, v7
	ds_swizzle_b32 v7, v6 offset:swizzle(SWAP,16)
	s_waitcnt lgkmcnt(0)
	v_add_f32_e32 v6, v6, v7
	v_mov_b32_e32 v7, v6
	s_nop 1
	v_permlane32_swap_b32_e32 v6, v7
	v_add_f32_e32 v6, v6, v7
	v_fmamk_f32 v6, v6, 0x39800000, v32
	v_mul_f32_e32 v7, 0x4f800000, v6
	v_cmp_gt_f32_e32 vcc, s29, v6
	s_nop 1
	v_cndmask_b32_e32 v7, v6, v7, vcc
	v_sqrt_f32_e32 v8, v7
	v_cvt_pk_bf16_f32 v6, v55, v41
	s_nop 0
	v_add_u32_e32 v9, -1, v8
	v_fma_f32 v10, -v9, v8, v7
	v_cmp_ge_f32_e64 s[8:9], 0, v10
	v_add_u32_e32 v10, 1, v8
	s_nop 0
	v_cndmask_b32_e64 v9, v8, v9, s[8:9]
	v_fma_f32 v8, -v10, v8, v7
	v_cmp_lt_f32_e64 s[8:9], 0, v8
	s_nop 1
	v_cndmask_b32_e64 v8, v9, v10, s[8:9]
	v_mul_f32_e32 v9, 0x37800000, v8
	v_cndmask_b32_e32 v8, v8, v9, vcc
	v_cmp_class_f32_e32 vcc, v7, v33
	s_nop 1
	v_cndmask_b32_e32 v10, v8, v7, vcc
	v_div_scale_f32 v8, s[8:9], v10, v10, 1.0
	v_rcp_f32_e32 v11, v8
	v_cvt_pk_bf16_f32 v7, v14, v15
	global_store_dwordx2 v[2:3], v[6:7], off sc1
	v_fma_f32 v6, -v8, v11, 1.0
	v_fmac_f32_e32 v11, v6, v11
	v_div_scale_f32 v6, vcc, 1.0, v10, 1.0
	v_mul_f32_e32 v12, v6, v11
	v_fma_f32 v7, -v8, v12, v6
	v_fmac_f32_e32 v12, v7, v11
	v_fma_f32 v13, -v8, v12, v6
	ds_read_b128 v[6:9], v30 offset:16384
	v_div_fmas_f32 v11, v13, v11, v12
	v_div_fixup_f32 v16, v11, v10, 1.0
	ds_read_b128 v[10:13], v30 offset:17408
	s_waitcnt lgkmcnt(1)
	v_mul_f32_e32 v6, v16, v6
	v_mul_f32_e32 v17, v36, v6
	v_mul_f32_e32 v6, v16, v7
	v_mul_f32_e32 v26, v26, v6
	v_mul_f32_e32 v6, v16, v8
	v_mul_f32_e32 v35, v38, v6
	v_mul_f32_e32 v6, v16, v9
	v_mul_f32_e32 v27, v27, v6
	v_max_f32_e64 v6, |v17|, |v26|
	v_max_f32_e64 v7, |v35|, |v27|
	v_max3_f32 v36, v6, 0, v7
	s_waitcnt lgkmcnt(0)
	v_mul_f32_e32 v6, v16, v10
	v_mul_f32_e32 v37, v43, v6
	v_mul_f32_e32 v6, v16, v11
	v_mul_f32_e32 v38, v44, v6
	v_mul_f32_e32 v6, v16, v12
	v_mul_f32_e32 v39, v46, v6
	v_mul_f32_e32 v6, v16, v13
	v_mul_f32_e32 v40, v48, v6
	ds_read_b128 v[6:9], v30 offset:18432
	v_max_f32_e64 v10, |v37|, |v38|
	v_max_f32_e64 v11, |v39|, |v40|
	v_max3_f32 v36, v36, v10, v11
	ds_read_b128 v[10:13], v30 offset:19456
	s_waitcnt lgkmcnt(1)
	v_mul_f32_e32 v6, v16, v6
	v_mul_f32_e32 v42, v49, v6
	v_mul_f32_e32 v6, v16, v7
	v_mul_f32_e32 v43, v51, v6
	v_mul_f32_e32 v6, v16, v8
	v_mul_f32_e32 v44, v52, v6
	v_mul_f32_e32 v6, v16, v9
	v_mul_f32_e32 v46, v53, v6
	v_max_f32_e64 v6, |v42|, |v43|
	v_max_f32_e64 v7, |v44|, |v46|
	v_max3_f32 v36, v36, v6, v7
	s_waitcnt lgkmcnt(0)
	v_mul_f32_e32 v6, v16, v10
	v_mul_f32_e32 v48, v58, v6
	v_mul_f32_e32 v6, v16, v11
	v_mul_f32_e32 v49, v59, v6
	v_mul_f32_e32 v6, v16, v12
	v_mul_f32_e32 v51, v61, v6
	v_mul_f32_e32 v6, v16, v13
	v_mul_f32_e32 v52, v62, v6
	ds_read_b128 v[6:9], v30 offset:20480
	v_max_f32_e64 v10, |v48|, |v49|
	v_max_f32_e64 v11, |v51|, |v52|
	v_max3_f32 v36, v36, v10, v11
	ds_read_b128 v[10:13], v30 offset:21504
	s_waitcnt lgkmcnt(1)
	v_mul_f32_e32 v6, v16, v6
	v_mul_f32_e32 v53, v64, v6
	v_mul_f32_e32 v6, v16, v7
	v_mul_f32_e32 v58, v65, v6
	v_mul_f32_e32 v6, v16, v8
	v_mul_f32_e32 v59, v67, v6
	v_mul_f32_e32 v6, v16, v9
	v_mul_f32_e32 v60, v69, v6
	v_max_f32_e64 v6, |v53|, |v58|
	v_max_f32_e64 v7, |v59|, |v60|
	v_max3_f32 v36, v36, v6, v7
	s_waitcnt lgkmcnt(0)
	v_mul_f32_e32 v6, v16, v10
	v_mul_f32_e32 v61, v72, v6
	v_mul_f32_e32 v6, v16, v11
	v_mul_f32_e32 v28, v28, v6
	v_mul_f32_e32 v6, v16, v12
	v_mul_f32_e32 v62, v74, v6
	v_mul_f32_e32 v6, v16, v13
	v_mul_f32_e32 v29, v29, v6
	ds_read_b128 v[6:9], v30 offset:22528
	v_max_f32_e64 v10, |v61|, |v28|
	v_max_f32_e64 v11, |v62|, |v29|
	v_max3_f32 v36, v36, v10, v11
	ds_read_b128 v[10:13], v30 offset:23552
	s_waitcnt lgkmcnt(1)
	v_mul_f32_e32 v6, v16, v6
	v_mul_f32_e32 v63, v76, v6
	v_mul_f32_e32 v6, v16, v7
	v_mul_f32_e32 v24, v24, v6
	v_mul_f32_e32 v6, v16, v8
	v_mul_f32_e32 v64, v78, v6
	v_mul_f32_e32 v6, v16, v9
	v_mul_f32_e32 v25, v25, v6
	v_max_f32_e64 v6, |v63|, |v24|
	v_max_f32_e64 v7, |v64|, |v25|
	v_max3_f32 v36, v36, v6, v7
	s_waitcnt lgkmcnt(0)
	v_mul_f32_e32 v6, v16, v10
	v_mul_f32_e32 v65, v83, v6
	v_mul_f32_e32 v6, v16, v11
	v_mul_f32_e32 v22, v22, v6
	v_mul_f32_e32 v6, v16, v12
	v_mul_f32_e32 v67, v84, v6
	v_mul_f32_e32 v6, v16, v13
	v_mul_f32_e32 v23, v23, v6
	ds_read_b128 v[6:9], v30 offset:24576
	v_max_f32_e64 v10, |v65|, |v22|
	v_max_f32_e64 v11, |v67|, |v23|
	v_max3_f32 v36, v36, v10, v11
	ds_read_b128 v[10:13], v30 offset:25600
	s_waitcnt lgkmcnt(1)
	v_mul_f32_e32 v6, v16, v6
	v_mul_f32_e32 v69, v86, v6
	v_mul_f32_e32 v6, v16, v7
	v_mul_f32_e32 v20, v20, v6
	v_mul_f32_e32 v6, v16, v8
	v_mul_f32_e32 v72, v88, v6
	v_mul_f32_e32 v6, v16, v9
	v_mul_f32_e32 v21, v21, v6
	v_max_f32_e64 v6, |v69|, |v20|
	v_max_f32_e64 v7, |v72|, |v21|
	v_max3_f32 v36, v36, v6, v7
	s_waitcnt lgkmcnt(0)
	v_mul_f32_e32 v6, v16, v10
	v_mul_f32_e32 v74, v91, v6
	v_mul_f32_e32 v6, v16, v11
	v_mul_f32_e32 v18, v18, v6
	v_mul_f32_e32 v6, v16, v12
	v_mul_f32_e32 v76, v89, v6
	v_mul_f32_e32 v6, v16, v13
	v_mul_f32_e32 v19, v19, v6
	ds_read_b128 v[6:9], v30 offset:26624
	v_max_f32_e64 v10, |v74|, |v18|
	v_max_f32_e64 v11, |v76|, |v19|
	v_max3_f32 v36, v36, v10, v11
	ds_read_b128 v[10:13], v30 offset:27648
	s_waitcnt lgkmcnt(1)
	v_mul_f32_e32 v6, v16, v6
	v_mul_f32_e32 v78, v87, v6
	v_mul_f32_e32 v6, v16, v7
	v_mul_f32_e32 v82, v82, v6
	v_mul_f32_e32 v6, v16, v8
	v_mul_f32_e32 v81, v81, v6
	v_mul_f32_e32 v6, v16, v9
	v_mul_f32_e32 v80, v80, v6
	v_max_f32_e64 v6, |v78|, |v82|
	v_max_f32_e64 v7, |v81|, |v80|
	v_max3_f32 v36, v36, v6, v7
	s_waitcnt lgkmcnt(0)
	v_mul_f32_e32 v6, v16, v10
	v_mul_f32_e32 v83, v85, v6
	v_mul_f32_e32 v6, v16, v11
	v_mul_f32_e32 v77, v77, v6
	v_mul_f32_e32 v6, v16, v12
	v_mul_f32_e32 v75, v75, v6
	v_mul_f32_e32 v6, v16, v13
	v_mul_f32_e32 v73, v73, v6
	ds_read_b128 v[6:9], v30 offset:28672
	v_max_f32_e64 v10, |v83|, |v77|
	v_max_f32_e64 v11, |v75|, |v73|
	v_max3_f32 v36, v36, v10, v11
	ds_read_b128 v[10:13], v30 offset:29696
	s_waitcnt lgkmcnt(1)
	v_mul_f32_e32 v6, v16, v6
	v_mul_f32_e32 v79, v79, v6
	v_mul_f32_e32 v6, v16, v7
	v_mul_f32_e32 v70, v70, v6
	v_mul_f32_e32 v6, v16, v8
	v_mul_f32_e32 v68, v68, v6
	v_mul_f32_e32 v6, v16, v9
	v_mul_f32_e32 v66, v66, v6
	v_max_f32_e64 v6, |v79|, |v70|
	v_max_f32_e64 v7, |v68|, |v66|
	v_max3_f32 v36, v36, v6, v7
	s_waitcnt lgkmcnt(0)
	v_mul_f32_e32 v6, v16, v10
	v_mul_f32_e32 v71, v71, v6
	v_mul_f32_e32 v6, v16, v11
	v_mul_f32_e32 v57, v57, v6
	v_mul_f32_e32 v6, v16, v12
	v_mul_f32_e32 v56, v56, v6
	v_mul_f32_e32 v6, v16, v13
	v_mul_f32_e32 v84, v90, v6
	ds_read_b128 v[6:9], v30 offset:30720
	v_max_f32_e64 v10, |v71|, |v57|
	v_max_f32_e64 v11, |v56|, |v84|
	v_max3_f32 v36, v36, v10, v11
	ds_read_b128 v[10:13], v30 offset:31744
	s_waitcnt lgkmcnt(1)
	v_mul_f32_e32 v6, v16, v6
	v_mul_f32_e32 v54, v54, v6
	v_mul_f32_e32 v6, v16, v7
	v_mul_f32_e32 v50, v50, v6
	v_mul_f32_e32 v6, v16, v8
	v_mul_f32_e32 v47, v47, v6
	v_mul_f32_e32 v6, v16, v9
	v_mul_f32_e32 v9, v45, v6
	v_max_f32_e64 v6, |v54|, |v50|
	v_max_f32_e64 v7, |v47|, |v9|
	v_max3_f32 v6, v36, v6, v7
	s_waitcnt lgkmcnt(0)
	v_mul_f32_e32 v7, v16, v10
	v_mul_f32_e32 v10, v55, v7
	v_mul_f32_e32 v7, v16, v11
	v_mul_f32_e32 v11, v41, v7
	v_mul_f32_e32 v7, v16, v12
	v_mul_f32_e32 v12, v14, v7
	v_mul_f32_e32 v7, v16, v13
	v_mul_f32_e32 v13, v15, v7
	v_max_f32_e64 v7, |v10|, |v11|
	v_max_f32_e64 v8, |v12|, |v13|
	v_max3_f32 v6, v6, v7, v8
	ds_swizzle_b32 v7, v6 offset:swizzle(SWAP,1)
	s_waitcnt lgkmcnt(0)
	v_max_f32_e32 v7, v7, v7
	v_max_f32_e32 v6, v6, v7
	ds_swizzle_b32 v7, v6 offset:swizzle(SWAP,2)
	s_waitcnt lgkmcnt(0)
	v_max_f32_e32 v7, v7, v7
	v_max_f32_e32 v6, v6, v7
	ds_swizzle_b32 v7, v6 offset:swizzle(SWAP,4)
	s_waitcnt lgkmcnt(0)
	v_max_f32_e32 v7, v7, v7
	v_max_f32_e32 v6, v6, v7
	ds_swizzle_b32 v7, v6 offset:swizzle(SWAP,8)
	s_waitcnt lgkmcnt(0)
	v_max_f32_e32 v7, v7, v7
	v_max_f32_e32 v6, v6, v7
	ds_swizzle_b32 v7, v6 offset:swizzle(SWAP,16)
	s_waitcnt lgkmcnt(0)
	v_max_f32_e32 v7, v7, v7
	v_max_f32_e32 v6, v6, v7
	v_mov_b32_e32 v7, v6
	s_nop 1
	v_permlane32_swap_b32_e32 v6, v7
	v_max_f32_e32 v7, v7, v7
	v_max_f32_e32 v6, v6, v6
	v_max_f32_e32 v8, v6, v7
	v_div_scale_f32 v6, s[8:9], v8, v8, s31
	v_rcp_f32_e32 v7, v6
	s_nop 0
	v_fma_f32 v14, -v6, v7, 1.0
	v_fmac_f32_e32 v7, v14, v7
	v_div_scale_f32 v14, vcc, s31, v8, s31
	v_mul_f32_e32 v15, v14, v7
	v_fma_f32 v16, -v6, v15, v14
	v_fmac_f32_e32 v15, v16, v7
	v_fma_f32 v6, -v6, v15, v14
	v_div_fmas_f32 v6, v6, v7, v15
	v_div_fixup_f32 v6, v6, v8, s31
	v_cmp_lt_f32_e32 vcc, 0, v8
	s_nop 1
	v_cndmask_b32_e32 v14, 0, v6, vcc
	v_mul_f32_e32 v16, v14, v26
	v_mul_f32_e32 v15, v14, v17
	v_rndne_f32_e32 v16, v16
	v_mul_f32_e32 v17, v14, v35
	v_mul_f32_e32 v26, v14, v27
	v_rndne_f32_e32 v15, v15
	v_cvt_i32_f32_e32 v16, v16
	v_rndne_f32_e32 v17, v17
	v_rndne_f32_e32 v26, v26
	v_cvt_i32_f32_e32 v15, v15
	v_cvt_i32_f32_sdwa v17, v17 dst_sel:WORD_1 dst_unused:UNUSED_PAD src0_sel:DWORD
	v_cvt_i32_f32_e32 v26, v26
	v_lshl_add_u64 v[6:7], s[18:19], 0, v[0:1]
	v_lshlrev_b32_e32 v16, 8, v16
	v_and_b32_e32 v16, 0xff00, v16
	v_and_b32_e32 v17, 0xff0000, v17
	v_perm_b32 v15, v26, v15, s34
	v_add_co_u32_e32 v6, vcc, s35, v6
	v_or3_b32 v15, v15, v16, v17
	s_nop 0
	v_addc_co_u32_e32 v7, vcc, 0, v7, vcc
	v_mul_f32_e32 v16, v14, v38
	global_store_dword v[6:7], v15, off sc1
	v_mul_f32_e32 v15, v14, v37
	v_rndne_f32_e32 v16, v16
	v_mul_f32_e32 v17, v14, v39
	v_mul_f32_e32 v26, v14, v40
	v_rndne_f32_e32 v15, v15
	v_cvt_i32_f32_e32 v16, v16
	v_rndne_f32_e32 v17, v17
	v_rndne_f32_e32 v26, v26
	v_cvt_i32_f32_e32 v15, v15
	v_cvt_i32_f32_sdwa v17, v17 dst_sel:WORD_1 dst_unused:UNUSED_PAD src0_sel:DWORD
	v_cvt_i32_f32_e32 v26, v26
	v_lshlrev_b32_e32 v16, 8, v16
	v_and_b32_e32 v16, 0xff00, v16
	v_and_b32_e32 v17, 0xff0000, v17
	v_perm_b32 v15, v26, v15, s34
	v_or3_b32 v15, v15, v16, v17
	v_mul_f32_e32 v16, v14, v43
	global_store_dword v[6:7], v15, off offset:256 sc1
	v_mul_f32_e32 v15, v14, v42
	v_rndne_f32_e32 v16, v16
	v_mul_f32_e32 v17, v14, v44
	v_mul_f32_e32 v26, v14, v46
	v_rndne_f32_e32 v15, v15
	v_cvt_i32_f32_e32 v16, v16
	v_rndne_f32_e32 v17, v17
	v_rndne_f32_e32 v26, v26
	v_cvt_i32_f32_e32 v15, v15
	v_cvt_i32_f32_sdwa v17, v17 dst_sel:WORD_1 dst_unused:UNUSED_PAD src0_sel:DWORD
	v_cvt_i32_f32_e32 v26, v26
	v_lshlrev_b32_e32 v16, 8, v16
	v_and_b32_e32 v16, 0xff00, v16
	v_and_b32_e32 v17, 0xff0000, v17
	v_perm_b32 v15, v26, v15, s34
	v_or3_b32 v15, v15, v16, v17
	v_mul_f32_e32 v16, v14, v49
	global_store_dword v[6:7], v15, off offset:512 sc1
	v_mul_f32_e32 v15, v14, v48
	v_rndne_f32_e32 v16, v16
	v_mul_f32_e32 v17, v14, v51
	v_mul_f32_e32 v26, v14, v52
	v_rndne_f32_e32 v15, v15
	v_cvt_i32_f32_e32 v16, v16
	v_rndne_f32_e32 v17, v17
	v_rndne_f32_e32 v26, v26
	v_cvt_i32_f32_e32 v15, v15
	v_cvt_i32_f32_sdwa v17, v17 dst_sel:WORD_1 dst_unused:UNUSED_PAD src0_sel:DWORD
	v_cvt_i32_f32_e32 v26, v26
	v_lshlrev_b32_e32 v16, 8, v16
	v_and_b32_e32 v16, 0xff00, v16
	v_and_b32_e32 v17, 0xff0000, v17
	v_perm_b32 v15, v26, v15, s34
	v_or3_b32 v15, v15, v16, v17
	v_mul_f32_e32 v16, v14, v58
	global_store_dword v[6:7], v15, off offset:768 sc1
	v_mul_f32_e32 v15, v14, v53
	v_rndne_f32_e32 v16, v16
	v_mul_f32_e32 v17, v14, v59
	v_mul_f32_e32 v26, v14, v60
	v_rndne_f32_e32 v15, v15
	v_cvt_i32_f32_e32 v16, v16
	v_rndne_f32_e32 v17, v17
	v_rndne_f32_e32 v26, v26
	v_cvt_i32_f32_e32 v15, v15
	v_cvt_i32_f32_sdwa v17, v17 dst_sel:WORD_1 dst_unused:UNUSED_PAD src0_sel:DWORD
	v_cvt_i32_f32_e32 v26, v26
	v_lshlrev_b32_e32 v16, 8, v16
	v_and_b32_e32 v16, 0xff00, v16
	v_and_b32_e32 v17, 0xff0000, v17
	v_perm_b32 v15, v26, v15, s34
	v_or3_b32 v15, v15, v16, v17
	v_mul_f32_e32 v16, v14, v28
	global_store_dword v[6:7], v15, off offset:1024 sc1
	v_mul_f32_e32 v15, v14, v61
	v_rndne_f32_e32 v16, v16
	v_mul_f32_e32 v17, v14, v62
	v_mul_f32_e32 v26, v14, v29
	v_rndne_f32_e32 v15, v15
	v_cvt_i32_f32_e32 v16, v16
	v_rndne_f32_e32 v17, v17
	v_rndne_f32_e32 v26, v26
	v_cvt_i32_f32_e32 v15, v15
	v_cvt_i32_f32_sdwa v17, v17 dst_sel:WORD_1 dst_unused:UNUSED_PAD src0_sel:DWORD
	v_cvt_i32_f32_e32 v26, v26
	v_lshlrev_b32_e32 v16, 8, v16
	v_and_b32_e32 v16, 0xff00, v16
	v_and_b32_e32 v17, 0xff0000, v17
	v_perm_b32 v15, v26, v15, s34
	v_or3_b32 v15, v15, v16, v17
	v_mul_f32_e32 v16, v14, v24
	global_store_dword v[6:7], v15, off offset:1280 sc1
	v_mul_f32_e32 v15, v14, v63
	v_rndne_f32_e32 v16, v16
	v_mul_f32_e32 v17, v14, v64
	v_mul_f32_e32 v24, v14, v25
	v_rndne_f32_e32 v15, v15
	v_cvt_i32_f32_e32 v16, v16
	v_rndne_f32_e32 v17, v17
	v_rndne_f32_e32 v24, v24
	v_cvt_i32_f32_e32 v15, v15
	v_cvt_i32_f32_sdwa v17, v17 dst_sel:WORD_1 dst_unused:UNUSED_PAD src0_sel:DWORD
	v_cvt_i32_f32_e32 v24, v24
	v_lshlrev_b32_e32 v16, 8, v16
	v_and_b32_e32 v16, 0xff00, v16
	v_and_b32_e32 v17, 0xff0000, v17
	v_perm_b32 v15, v24, v15, s34
	v_or3_b32 v15, v15, v16, v17
	v_mul_f32_e32 v16, v14, v22
	global_store_dword v[6:7], v15, off offset:1536 sc1
	v_mul_f32_e32 v15, v14, v65
	v_rndne_f32_e32 v16, v16
	v_mul_f32_e32 v17, v14, v67
	v_mul_f32_e32 v22, v14, v23
	v_rndne_f32_e32 v15, v15
	v_cvt_i32_f32_e32 v16, v16
	v_rndne_f32_e32 v17, v17
	v_rndne_f32_e32 v22, v22
	v_cvt_i32_f32_e32 v15, v15
	v_cvt_i32_f32_sdwa v17, v17 dst_sel:WORD_1 dst_unused:UNUSED_PAD src0_sel:DWORD
	v_cvt_i32_f32_e32 v22, v22
	v_lshlrev_b32_e32 v16, 8, v16
	v_and_b32_e32 v16, 0xff00, v16
	v_and_b32_e32 v17, 0xff0000, v17
	v_perm_b32 v15, v22, v15, s34
	v_or3_b32 v15, v15, v16, v17
	v_mul_f32_e32 v16, v14, v20
	global_store_dword v[6:7], v15, off offset:1792 sc1
	v_mul_f32_e32 v15, v14, v69
	v_rndne_f32_e32 v16, v16
	v_mul_f32_e32 v17, v14, v72
	v_mul_f32_e32 v20, v14, v21
	v_rndne_f32_e32 v15, v15
	v_cvt_i32_f32_e32 v16, v16
	v_rndne_f32_e32 v17, v17
	v_rndne_f32_e32 v20, v20
	v_cvt_i32_f32_e32 v15, v15
	v_cvt_i32_f32_sdwa v17, v17 dst_sel:WORD_1 dst_unused:UNUSED_PAD src0_sel:DWORD
	v_cvt_i32_f32_e32 v20, v20
	v_lshlrev_b32_e32 v16, 8, v16
	v_and_b32_e32 v16, 0xff00, v16
	v_and_b32_e32 v17, 0xff0000, v17
	v_perm_b32 v15, v20, v15, s34
	v_or3_b32 v15, v15, v16, v17
	v_mul_f32_e32 v16, v14, v18
	global_store_dword v[6:7], v15, off offset:2048 sc1
	v_mul_f32_e32 v15, v14, v74
	v_rndne_f32_e32 v16, v16
	v_mul_f32_e32 v17, v14, v76
	v_mul_f32_e32 v18, v14, v19
	v_rndne_f32_e32 v15, v15
	v_cvt_i32_f32_e32 v16, v16
	v_rndne_f32_e32 v17, v17
	v_rndne_f32_e32 v18, v18
	v_cvt_i32_f32_e32 v15, v15
	v_cvt_i32_f32_sdwa v17, v17 dst_sel:WORD_1 dst_unused:UNUSED_PAD src0_sel:DWORD
	v_cvt_i32_f32_e32 v18, v18
	v_lshlrev_b32_e32 v16, 8, v16
	v_and_b32_e32 v16, 0xff00, v16
	v_and_b32_e32 v17, 0xff0000, v17
	v_perm_b32 v15, v18, v15, s34
	v_or3_b32 v15, v15, v16, v17
	v_mul_f32_e32 v16, v14, v82
	global_store_dword v[6:7], v15, off offset:2304 sc1
	v_mul_f32_e32 v15, v14, v78
	v_rndne_f32_e32 v16, v16
	v_mul_f32_e32 v17, v14, v81
	v_mul_f32_e32 v18, v14, v80
	v_rndne_f32_e32 v15, v15
	v_cvt_i32_f32_e32 v16, v16
	v_rndne_f32_e32 v17, v17
	v_rndne_f32_e32 v18, v18
	v_cvt_i32_f32_e32 v15, v15
	v_cvt_i32_f32_sdwa v17, v17 dst_sel:WORD_1 dst_unused:UNUSED_PAD src0_sel:DWORD
	v_cvt_i32_f32_e32 v18, v18
	v_lshlrev_b32_e32 v16, 8, v16
	v_and_b32_e32 v16, 0xff00, v16
	v_and_b32_e32 v17, 0xff0000, v17
	v_perm_b32 v15, v18, v15, s34
	v_or3_b32 v15, v15, v16, v17
	v_mul_f32_e32 v16, v14, v77
	global_store_dword v[6:7], v15, off offset:2560 sc1
	v_mul_f32_e32 v15, v14, v83
	v_rndne_f32_e32 v16, v16
	v_mul_f32_e32 v17, v14, v75
	v_mul_f32_e32 v18, v14, v73
	v_rndne_f32_e32 v15, v15
	v_cvt_i32_f32_e32 v16, v16
	v_rndne_f32_e32 v17, v17
	v_rndne_f32_e32 v18, v18
	v_cvt_i32_f32_e32 v15, v15
	v_cvt_i32_f32_sdwa v17, v17 dst_sel:WORD_1 dst_unused:UNUSED_PAD src0_sel:DWORD
	v_cvt_i32_f32_e32 v18, v18
	v_lshlrev_b32_e32 v16, 8, v16
	v_and_b32_e32 v16, 0xff00, v16
	v_and_b32_e32 v17, 0xff0000, v17
	v_perm_b32 v15, v18, v15, s34
	v_or3_b32 v15, v15, v16, v17
	v_mul_f32_e32 v16, v14, v70
	global_store_dword v[6:7], v15, off offset:2816 sc1
	v_mul_f32_e32 v15, v14, v79
	v_rndne_f32_e32 v16, v16
	v_mul_f32_e32 v17, v14, v68
	v_mul_f32_e32 v18, v14, v66
	v_rndne_f32_e32 v15, v15
	v_cvt_i32_f32_e32 v16, v16
	v_rndne_f32_e32 v17, v17
	v_rndne_f32_e32 v18, v18
	v_cvt_i32_f32_e32 v15, v15
	v_cvt_i32_f32_sdwa v17, v17 dst_sel:WORD_1 dst_unused:UNUSED_PAD src0_sel:DWORD
	v_cvt_i32_f32_e32 v18, v18
	v_lshlrev_b32_e32 v16, 8, v16
	v_and_b32_e32 v16, 0xff00, v16
	v_and_b32_e32 v17, 0xff0000, v17
	v_perm_b32 v15, v18, v15, s34
	v_or3_b32 v15, v15, v16, v17
	v_mul_f32_e32 v16, v14, v57
	global_store_dword v[6:7], v15, off offset:3072 sc1
	v_mul_f32_e32 v15, v14, v71
	v_rndne_f32_e32 v16, v16
	v_mul_f32_e32 v17, v14, v56
	v_mul_f32_e32 v18, v14, v84
	v_rndne_f32_e32 v15, v15
	v_cvt_i32_f32_e32 v16, v16
	v_rndne_f32_e32 v17, v17
	v_rndne_f32_e32 v18, v18
	v_cvt_i32_f32_e32 v15, v15
	v_cvt_i32_f32_sdwa v17, v17 dst_sel:WORD_1 dst_unused:UNUSED_PAD src0_sel:DWORD
	v_cvt_i32_f32_e32 v18, v18
	v_lshlrev_b32_e32 v16, 8, v16
	v_and_b32_e32 v16, 0xff00, v16
	v_and_b32_e32 v17, 0xff0000, v17
	v_perm_b32 v15, v18, v15, s34
	v_or3_b32 v15, v15, v16, v17
	v_mul_f32_e32 v16, v14, v50
	global_store_dword v[6:7], v15, off offset:3328 sc1
	v_mul_f32_e32 v15, v14, v54
	v_rndne_f32_e32 v16, v16
	v_mul_f32_e32 v17, v14, v47
	v_mul_f32_e32 v9, v14, v9
	v_rndne_f32_e32 v15, v15
	v_cvt_i32_f32_e32 v16, v16
	v_rndne_f32_e32 v17, v17
	v_rndne_f32_e32 v9, v9
	v_cvt_i32_f32_e32 v15, v15
	v_cvt_i32_f32_sdwa v17, v17 dst_sel:WORD_1 dst_unused:UNUSED_PAD src0_sel:DWORD
	v_cvt_i32_f32_e32 v9, v9
	v_lshlrev_b32_e32 v16, 8, v16
	v_and_b32_e32 v16, 0xff00, v16
	v_and_b32_e32 v17, 0xff0000, v17
	v_perm_b32 v9, v9, v15, s34
	v_or3_b32 v9, v9, v16, v17
	global_store_dword v[6:7], v9, off offset:3584 sc1
	v_mul_f32_e32 v9, v14, v10
	v_mul_f32_e32 v10, v14, v11
	v_rndne_f32_e32 v10, v10
	v_mul_f32_e32 v11, v14, v12
	v_mul_f32_e32 v12, v14, v13
	v_rndne_f32_e32 v9, v9
	v_cvt_i32_f32_e32 v10, v10
	v_rndne_f32_e32 v11, v11
	v_rndne_f32_e32 v12, v12
	v_cvt_i32_f32_e32 v9, v9
	v_cvt_i32_f32_sdwa v11, v11 dst_sel:WORD_1 dst_unused:UNUSED_PAD src0_sel:DWORD
	v_cvt_i32_f32_e32 v12, v12
	v_lshlrev_b32_e32 v10, 8, v10
	v_and_b32_e32 v10, 0xff00, v10
	v_and_b32_e32 v11, 0xff0000, v11
	v_perm_b32 v9, v12, v9, s34
	v_or3_b32 v9, v9, v10, v11
	global_store_dword v[6:7], v9, off offset:3840 sc1
	s_and_saveexec_b64 s[8:9], s[6:7]
	s_cbranch_execz .LBB0_705
	v_mul_f32_e32 v6, 0x3c010204, v8
	global_store_dword v34, v6, s[26:27] sc1
	s_branch .LBB0_705

.LBB0_909:
	s_waitcnt lgkmcnt(0)
	v_lshl_add_u64 v[4:5], s[8:9], 0, v[2:3]
	v_add_co_u32_e32 v24, vcc, 0x23000000, v4
	s_nop 1
	v_addc_co_u32_e32 v25, vcc, 0, v5, vcc
	global_load_dwordx2 v[86:87], v[24:25], off nt
	v_add_co_u32_e32 v54, vcc, s24, v4
	s_nop 1
	v_addc_co_u32_e32 v55, vcc, 0, v5, vcc
	v_add_co_u32_e32 v88, vcc, s25, v4
	s_nop 1
	v_addc_co_u32_e32 v89, vcc, 0, v5, vcc
	v_add_co_u32_e32 v90, vcc, s26, v4
	s_nop 1
	v_addc_co_u32_e32 v91, vcc, 0, v5, vcc
	global_load_dwordx2 v[36:37], v[54:55], off offset:1024 nt
	global_load_dwordx2 v[34:35], v[54:55], off offset:1536 nt
	global_load_dwordx2 v[32:33], v[54:55], off offset:2048 nt
	global_load_dwordx2 v[30:31], v[54:55], off offset:2560 nt
	global_load_dwordx2 v[22:23], v[88:89], off offset:512 nt
	global_load_dwordx2 v[20:21], v[88:89], off offset:1024 nt
	global_load_dwordx2 v[18:19], v[88:89], off offset:1536 nt
	global_load_dwordx2 v[16:17], v[88:89], off offset:2048 nt
	global_load_dwordx2 v[14:15], v[88:89], off offset:2560 nt
	global_load_dwordx2 v[12:13], v[88:89], off offset:3072 nt
	global_load_dwordx2 v[10:11], v[88:89], off offset:3584 nt
	global_load_dwordx2 v[28:29], v[54:55], off offset:3072 nt
	global_load_dwordx2 v[26:27], v[54:55], off offset:3584 nt
	global_load_dwordx2 v[8:9], v[90:91], off nt
	global_load_dwordx2 v[6:7], v[90:91], off offset:512 nt
	global_load_dwordx2 v[92:93], v[24:25], off offset:512 nt
	global_load_dwordx2 v[94:95], v[24:25], off offset:1024 nt
	global_load_dwordx2 v[96:97], v[24:25], off offset:1536 nt
	global_load_dwordx2 v[80:81], v[24:25], off offset:2048 nt
	global_load_dwordx2 v[78:79], v[24:25], off offset:2560 nt
	global_load_dwordx2 v[76:77], v[24:25], off offset:3072 nt
	global_load_dwordx2 v[74:75], v[24:25], off offset:3584 nt
	v_add_co_u32_e32 v56, vcc, s22, v4
	s_nop 1
	v_addc_co_u32_e32 v57, vcc, 0, v5, vcc
	v_add_co_u32_e32 v98, vcc, s23, v4
	s_nop 1
	v_addc_co_u32_e32 v99, vcc, 0, v5, vcc
	global_load_dwordx2 v[70:71], v[56:57], off offset:512 nt
	global_load_dwordx2 v[68:69], v[56:57], off offset:1024 nt
	global_load_dwordx2 v[66:67], v[56:57], off offset:1536 nt
	global_load_dwordx2 v[64:65], v[56:57], off offset:2048 nt
	global_load_dwordx2 v[62:63], v[56:57], off offset:2560 nt
	global_load_dwordx2 v[60:61], v[56:57], off offset:3072 nt
	global_load_dwordx2 v[58:59], v[56:57], off offset:3584 nt
	global_load_dwordx2 v[38:39], v[54:55], off offset:512 nt
	global_load_dwordx2 v[52:53], v[98:99], off offset:1024 nt
	global_load_dwordx2 v[50:51], v[98:99], off offset:1536 nt
	global_load_dwordx2 v[48:49], v[98:99], off offset:2048 nt
	global_load_dwordx2 v[46:47], v[98:99], off offset:2560 nt
	global_load_dwordx2 v[44:45], v[98:99], off offset:3072 nt
	global_load_dwordx2 v[42:43], v[98:99], off offset:3584 nt
	global_load_dwordx2 v[40:41], v[88:89], off offset:-4096 nt
	global_load_dwordx2 v[24:25], v[88:89], off nt
	global_load_dwordx2 v[72:73], v[98:99], off offset:-4096 nt
	global_load_dwordx2 v[56:57], v[98:99], off nt
	global_load_dwordx2 v[54:55], v[98:99], off offset:512 nt
	global_load_dwordx2 v[4:5], v[90:91], off offset:1024 nt
	s_waitcnt vmcnt(42)
	v_lshlrev_b32_e32 v88, 16, v86
	v_and_b32_e32 v86, 0xffff0000, v86
	v_lshlrev_b32_e32 v89, 16, v87
	v_and_b32_e32 v87, 0xffff0000, v87
	v_add_f32_e32 v90, v88, v86
	v_sub_f32_e32 v86, v88, v86
	v_add_f32_e32 v88, v89, v87
	v_sub_f32_e32 v87, v89, v87
	v_add_f32_e32 v89, v90, v88
	v_add_f32_e32 v91, v86, v87
	v_sub_f32_e32 v88, v90, v88
	v_sub_f32_e32 v86, v86, v87
	v_xor_b32_e32 v87, v82, v89
	v_xor_b32_e32 v90, v82, v91
	v_xor_b32_e32 v98, v82, v88
	v_add_f32_dpp v87, v89, v87 quad_perm:[1,0,3,2] row_mask:0xf bank_mask:0xf bound_ctrl:1
	v_add_f32_dpp v89, v91, v90 quad_perm:[1,0,3,2] row_mask:0xf bank_mask:0xf bound_ctrl:1
	v_xor_b32_e32 v90, v82, v86
	v_add_f32_dpp v88, v88, v98 quad_perm:[1,0,3,2] row_mask:0xf bank_mask:0xf bound_ctrl:1
	s_nop 0
	v_add_f32_dpp v86, v86, v90 quad_perm:[1,0,3,2] row_mask:0xf bank_mask:0xf bound_ctrl:1
	v_xor_b32_e32 v200, v83, v87
	v_xor_b32_e32 v201, v83, v89
	v_xor_b32_e32 v202, v83, v88
	v_xor_b32_e32 v203, v83, v86
	v_add_f32_dpp v204, v87, v200 quad_perm:[2,3,0,1] row_mask:0xf bank_mask:0xf bound_ctrl:1
	v_add_f32_dpp v205, v89, v201 quad_perm:[2,3,0,1] row_mask:0xf bank_mask:0xf bound_ctrl:1
	v_add_f32_dpp v206, v88, v202 quad_perm:[2,3,0,1] row_mask:0xf bank_mask:0xf bound_ctrl:1
	v_add_f32_dpp v207, v86, v203 quad_perm:[2,3,0,1] row_mask:0xf bank_mask:0xf bound_ctrl:1
	v_xor_b32_e32 v200, v84, v204
	v_xor_b32_e32 v201, v84, v205
	v_xor_b32_e32 v202, v84, v206
	v_xor_b32_e32 v203, v84, v207
	v_add_f32_dpp v87, v204, v200 row_shl:4 row_mask:0xf bank_mask:0x5
	v_add_f32_dpp v89, v205, v201 row_shl:4 row_mask:0xf bank_mask:0x5
	v_add_f32_dpp v88, v206, v202 row_shl:4 row_mask:0xf bank_mask:0x5
	v_add_f32_dpp v90, v207, v203 row_shl:4 row_mask:0xf bank_mask:0x5
	v_add_f32_dpp v87, v204, v200 row_shr:4 row_mask:0xf bank_mask:0xa
	v_add_f32_dpp v89, v205, v201 row_shr:4 row_mask:0xf bank_mask:0xa
	v_add_f32_dpp v88, v206, v202 row_shr:4 row_mask:0xf bank_mask:0xa
	v_add_f32_dpp v90, v207, v203 row_shr:4 row_mask:0xf bank_mask:0xa
	v_max_f32_e64 v86, |v87|, |v89|
	v_max_f32_e64 v91, |v88|, |v90|
	v_max3_f32 v91, v86, 0, v91
	v_cvt_pk_bf16_f32 v86, v87, v89
	v_cvt_pk_bf16_f32 v87, v88, v90
	s_waitcnt vmcnt(26)
	v_lshlrev_b32_e32 v88, 16, v92
	v_and_b32_e32 v89, 0xffff0000, v92
	v_lshlrev_b32_e32 v90, 16, v93
	v_and_b32_e32 v92, 0xffff0000, v93
	v_add_f32_e32 v93, v88, v89
	v_sub_f32_e32 v88, v88, v89
	v_add_f32_e32 v89, v90, v92
	v_sub_f32_e32 v90, v90, v92
	v_add_f32_e32 v92, v93, v89
	v_sub_f32_e32 v89, v93, v89
	v_add_f32_e32 v98, v88, v90
	v_sub_f32_e32 v88, v88, v90
	v_xor_b32_e32 v90, v82, v92
	v_xor_b32_e32 v93, v82, v89
	s_nop 0
	v_add_f32_dpp v90, v92, v90 quad_perm:[1,0,3,2] row_mask:0xf bank_mask:0xf bound_ctrl:1
	v_xor_b32_e32 v92, v82, v98
	v_add_f32_dpp v89, v89, v93 quad_perm:[1,0,3,2] row_mask:0xf bank_mask:0xf bound_ctrl:1
	v_xor_b32_e32 v93, v82, v88
	v_add_f32_dpp v92, v98, v92 quad_perm:[1,0,3,2] row_mask:0xf bank_mask:0xf bound_ctrl:1
	s_nop 0
	v_add_f32_dpp v88, v88, v93 quad_perm:[1,0,3,2] row_mask:0xf bank_mask:0xf bound_ctrl:1
	v_xor_b32_e32 v200, v83, v90
	v_xor_b32_e32 v201, v83, v92
	v_xor_b32_e32 v202, v83, v89
	v_xor_b32_e32 v203, v83, v88
	v_add_f32_dpp v204, v90, v200 quad_perm:[2,3,0,1] row_mask:0xf bank_mask:0xf bound_ctrl:1
	v_add_f32_dpp v205, v92, v201 quad_perm:[2,3,0,1] row_mask:0xf bank_mask:0xf bound_ctrl:1
	v_add_f32_dpp v206, v89, v202 quad_perm:[2,3,0,1] row_mask:0xf bank_mask:0xf bound_ctrl:1
	v_add_f32_dpp v207, v88, v203 quad_perm:[2,3,0,1] row_mask:0xf bank_mask:0xf bound_ctrl:1
	v_xor_b32_e32 v200, v84, v204
	v_xor_b32_e32 v201, v84, v205
	v_xor_b32_e32 v202, v84, v206
	v_xor_b32_e32 v203, v84, v207
	v_add_f32_dpp v90, v204, v200 row_shl:4 row_mask:0xf bank_mask:0x5
	v_add_f32_dpp v92, v205, v201 row_shl:4 row_mask:0xf bank_mask:0x5
	v_add_f32_dpp v89, v206, v202 row_shl:4 row_mask:0xf bank_mask:0x5
	v_add_f32_dpp v93, v207, v203 row_shl:4 row_mask:0xf bank_mask:0x5
	v_add_f32_dpp v90, v204, v200 row_shr:4 row_mask:0xf bank_mask:0xa
	v_add_f32_dpp v92, v205, v201 row_shr:4 row_mask:0xf bank_mask:0xa
	v_add_f32_dpp v89, v206, v202 row_shr:4 row_mask:0xf bank_mask:0xa
	v_add_f32_dpp v93, v207, v203 row_shr:4 row_mask:0xf bank_mask:0xa
	v_max_f32_e64 v88, |v90|, |v92|
	v_max_f32_e64 v98, |v89|, |v93|
	v_max3_f32 v91, v91, v88, v98
	v_cvt_pk_bf16_f32 v88, v90, v92
	v_cvt_pk_bf16_f32 v89, v89, v93
	s_waitcnt vmcnt(25)
	v_lshlrev_b32_e32 v90, 16, v94
	v_and_b32_e32 v92, 0xffff0000, v94
	v_lshlrev_b32_e32 v93, 16, v95
	v_and_b32_e32 v94, 0xffff0000, v95
	v_add_f32_e32 v95, v90, v92
	v_sub_f32_e32 v90, v90, v92
	v_add_f32_e32 v92, v93, v94
	v_sub_f32_e32 v93, v93, v94
	v_add_f32_e32 v94, v95, v92
	v_sub_f32_e32 v92, v95, v92
	v_add_f32_e32 v98, v90, v93
	v_sub_f32_e32 v90, v90, v93
	v_xor_b32_e32 v93, v82, v94
	v_xor_b32_e32 v95, v82, v92
	s_nop 0
	v_add_f32_dpp v93, v94, v93 quad_perm:[1,0,3,2] row_mask:0xf bank_mask:0xf bound_ctrl:1
	v_xor_b32_e32 v94, v82, v98
	v_add_f32_dpp v92, v92, v95 quad_perm:[1,0,3,2] row_mask:0xf bank_mask:0xf bound_ctrl:1
	v_xor_b32_e32 v95, v82, v90
	v_add_f32_dpp v94, v98, v94 quad_perm:[1,0,3,2] row_mask:0xf bank_mask:0xf bound_ctrl:1
	s_nop 0
	v_add_f32_dpp v90, v90, v95 quad_perm:[1,0,3,2] row_mask:0xf bank_mask:0xf bound_ctrl:1
	v_xor_b32_e32 v200, v83, v93
	v_xor_b32_e32 v201, v83, v94
	v_xor_b32_e32 v202, v83, v92
	v_xor_b32_e32 v203, v83, v90
	v_add_f32_dpp v204, v93, v200 quad_perm:[2,3,0,1] row_mask:0xf bank_mask:0xf bound_ctrl:1
	v_add_f32_dpp v205, v94, v201 quad_perm:[2,3,0,1] row_mask:0xf bank_mask:0xf bound_ctrl:1
	v_add_f32_dpp v206, v92, v202 quad_perm:[2,3,0,1] row_mask:0xf bank_mask:0xf bound_ctrl:1
	v_add_f32_dpp v207, v90, v203 quad_perm:[2,3,0,1] row_mask:0xf bank_mask:0xf bound_ctrl:1
	v_xor_b32_e32 v200, v84, v204
	v_xor_b32_e32 v201, v84, v205
	v_xor_b32_e32 v202, v84, v206
	v_xor_b32_e32 v203, v84, v207
	v_add_f32_dpp v93, v204, v200 row_shl:4 row_mask:0xf bank_mask:0x5
	v_add_f32_dpp v94, v205, v201 row_shl:4 row_mask:0xf bank_mask:0x5
	v_add_f32_dpp v92, v206, v202 row_shl:4 row_mask:0xf bank_mask:0x5
	v_add_f32_dpp v95, v207, v203 row_shl:4 row_mask:0xf bank_mask:0x5
	v_add_f32_dpp v93, v204, v200 row_shr:4 row_mask:0xf bank_mask:0xa
	v_add_f32_dpp v94, v205, v201 row_shr:4 row_mask:0xf bank_mask:0xa
	v_add_f32_dpp v92, v206, v202 row_shr:4 row_mask:0xf bank_mask:0xa
	v_add_f32_dpp v95, v207, v203 row_shr:4 row_mask:0xf bank_mask:0xa
	v_max_f32_e64 v90, |v93|, |v94|
	v_max_f32_e64 v98, |v92|, |v95|
	v_max3_f32 v98, v91, v90, v98
	v_cvt_pk_bf16_f32 v90, v93, v94
	v_cvt_pk_bf16_f32 v91, v92, v95
	s_waitcnt vmcnt(24)
	v_lshlrev_b32_e32 v92, 16, v96
	v_and_b32_e32 v93, 0xffff0000, v96
	v_lshlrev_b32_e32 v94, 16, v97
	v_and_b32_e32 v95, 0xffff0000, v97
	v_add_f32_e32 v96, v92, v93
	v_sub_f32_e32 v92, v92, v93
	v_add_f32_e32 v93, v94, v95
	v_sub_f32_e32 v94, v94, v95
	v_add_f32_e32 v95, v96, v93
	v_sub_f32_e32 v93, v96, v93
	v_add_f32_e32 v97, v92, v94
	v_sub_f32_e32 v92, v92, v94
	v_xor_b32_e32 v94, v82, v95
	v_xor_b32_e32 v96, v82, v93
	s_nop 0
	v_add_f32_dpp v94, v95, v94 quad_perm:[1,0,3,2] row_mask:0xf bank_mask:0xf bound_ctrl:1
	v_xor_b32_e32 v95, v82, v97
	v_add_f32_dpp v93, v93, v96 quad_perm:[1,0,3,2] row_mask:0xf bank_mask:0xf bound_ctrl:1
	v_xor_b32_e32 v96, v82, v92
	v_add_f32_dpp v95, v97, v95 quad_perm:[1,0,3,2] row_mask:0xf bank_mask:0xf bound_ctrl:1
	s_nop 0
	v_add_f32_dpp v92, v92, v96 quad_perm:[1,0,3,2] row_mask:0xf bank_mask:0xf bound_ctrl:1
	v_xor_b32_e32 v200, v83, v94
	v_xor_b32_e32 v201, v83, v95
	v_xor_b32_e32 v202, v83, v93
	v_xor_b32_e32 v203, v83, v92
	v_add_f32_dpp v204, v94, v200 quad_perm:[2,3,0,1] row_mask:0xf bank_mask:0xf bound_ctrl:1
	v_add_f32_dpp v205, v95, v201 quad_perm:[2,3,0,1] row_mask:0xf bank_mask:0xf bound_ctrl:1
	v_add_f32_dpp v206, v93, v202 quad_perm:[2,3,0,1] row_mask:0xf bank_mask:0xf bound_ctrl:1
	v_add_f32_dpp v207, v92, v203 quad_perm:[2,3,0,1] row_mask:0xf bank_mask:0xf bound_ctrl:1
	v_xor_b32_e32 v200, v84, v204
	v_xor_b32_e32 v201, v84, v205
	v_xor_b32_e32 v202, v84, v206
	v_xor_b32_e32 v203, v84, v207
	v_add_f32_dpp v94, v204, v200 row_shl:4 row_mask:0xf bank_mask:0x5
	v_add_f32_dpp v95, v205, v201 row_shl:4 row_mask:0xf bank_mask:0x5
	v_add_f32_dpp v93, v206, v202 row_shl:4 row_mask:0xf bank_mask:0x5
	v_add_f32_dpp v96, v207, v203 row_shl:4 row_mask:0xf bank_mask:0x5
	v_add_f32_dpp v94, v204, v200 row_shr:4 row_mask:0xf bank_mask:0xa
	v_add_f32_dpp v95, v205, v201 row_shr:4 row_mask:0xf bank_mask:0xa
	v_add_f32_dpp v93, v206, v202 row_shr:4 row_mask:0xf bank_mask:0xa
	v_add_f32_dpp v96, v207, v203 row_shr:4 row_mask:0xf bank_mask:0xa
	v_max_f32_e64 v92, |v94|, |v95|
	v_max_f32_e64 v97, |v93|, |v96|
	v_max3_f32 v97, v98, v92, v97
	v_cvt_pk_bf16_f32 v92, v94, v95
	s_waitcnt vmcnt(23)
	v_lshlrev_b32_e32 v94, 16, v80
	v_and_b32_e32 v80, 0xffff0000, v80
	v_lshlrev_b32_e32 v95, 16, v81
	v_and_b32_e32 v81, 0xffff0000, v81
	v_cvt_pk_bf16_f32 v93, v93, v96
	v_add_f32_e32 v96, v94, v80
	v_sub_f32_e32 v80, v94, v80
	v_add_f32_e32 v94, v95, v81
	v_sub_f32_e32 v81, v95, v81
	v_add_f32_e32 v95, v96, v94
	v_sub_f32_e32 v94, v96, v94
	v_add_f32_e32 v98, v80, v81
	v_sub_f32_e32 v80, v80, v81
	v_xor_b32_e32 v81, v82, v95
	v_xor_b32_e32 v96, v82, v94
	s_nop 0
	v_add_f32_dpp v81, v95, v81 quad_perm:[1,0,3,2] row_mask:0xf bank_mask:0xf bound_ctrl:1
	v_xor_b32_e32 v95, v82, v98
	v_add_f32_dpp v94, v94, v96 quad_perm:[1,0,3,2] row_mask:0xf bank_mask:0xf bound_ctrl:1
	v_xor_b32_e32 v96, v82, v80
	v_add_f32_dpp v95, v98, v95 quad_perm:[1,0,3,2] row_mask:0xf bank_mask:0xf bound_ctrl:1
	s_nop 0
	v_add_f32_dpp v80, v80, v96 quad_perm:[1,0,3,2] row_mask:0xf bank_mask:0xf bound_ctrl:1
	v_xor_b32_e32 v200, v83, v81
	v_xor_b32_e32 v201, v83, v95
	v_xor_b32_e32 v202, v83, v94
	v_xor_b32_e32 v203, v83, v80
	v_add_f32_dpp v204, v81, v200 quad_perm:[2,3,0,1] row_mask:0xf bank_mask:0xf bound_ctrl:1
	v_add_f32_dpp v205, v95, v201 quad_perm:[2,3,0,1] row_mask:0xf bank_mask:0xf bound_ctrl:1
	v_add_f32_dpp v206, v94, v202 quad_perm:[2,3,0,1] row_mask:0xf bank_mask:0xf bound_ctrl:1
	v_add_f32_dpp v207, v80, v203 quad_perm:[2,3,0,1] row_mask:0xf bank_mask:0xf bound_ctrl:1
	v_xor_b32_e32 v200, v84, v204
	v_xor_b32_e32 v201, v84, v205
	v_xor_b32_e32 v202, v84, v206
	v_xor_b32_e32 v203, v84, v207
	v_add_f32_dpp v81, v204, v200 row_shl:4 row_mask:0xf bank_mask:0x5
	v_add_f32_dpp v95, v205, v201 row_shl:4 row_mask:0xf bank_mask:0x5
	v_add_f32_dpp v94, v206, v202 row_shl:4 row_mask:0xf bank_mask:0x5
	v_add_f32_dpp v96, v207, v203 row_shl:4 row_mask:0xf bank_mask:0x5
	v_add_f32_dpp v81, v204, v200 row_shr:4 row_mask:0xf bank_mask:0xa
	v_add_f32_dpp v95, v205, v201 row_shr:4 row_mask:0xf bank_mask:0xa
	v_add_f32_dpp v94, v206, v202 row_shr:4 row_mask:0xf bank_mask:0xa
	v_add_f32_dpp v96, v207, v203 row_shr:4 row_mask:0xf bank_mask:0xa
	v_max_f32_e64 v80, |v81|, |v95|
	v_max_f32_e64 v98, |v94|, |v96|
	v_max3_f32 v97, v97, v80, v98
	v_cvt_pk_bf16_f32 v80, v81, v95
	v_cvt_pk_bf16_f32 v81, v94, v96
	s_waitcnt vmcnt(22)
	v_lshlrev_b32_e32 v94, 16, v78
	v_and_b32_e32 v78, 0xffff0000, v78
	v_lshlrev_b32_e32 v95, 16, v79
	v_and_b32_e32 v79, 0xffff0000, v79
	v_add_f32_e32 v96, v94, v78
	v_sub_f32_e32 v78, v94, v78
	v_add_f32_e32 v94, v95, v79
	v_sub_f32_e32 v79, v95, v79
	v_add_f32_e32 v95, v96, v94
	v_sub_f32_e32 v94, v96, v94
	v_add_f32_e32 v98, v78, v79
	v_sub_f32_e32 v78, v78, v79
	v_xor_b32_e32 v79, v82, v95
	v_xor_b32_e32 v96, v82, v94
	s_nop 0
	v_add_f32_dpp v79, v95, v79 quad_perm:[1,0,3,2] row_mask:0xf bank_mask:0xf bound_ctrl:1
	v_xor_b32_e32 v95, v82, v98
	v_add_f32_dpp v94, v94, v96 quad_perm:[1,0,3,2] row_mask:0xf bank_mask:0xf bound_ctrl:1
	v_xor_b32_e32 v96, v82, v78
	v_add_f32_dpp v95, v98, v95 quad_perm:[1,0,3,2] row_mask:0xf bank_mask:0xf bound_ctrl:1
	s_nop 0
	v_add_f32_dpp v78, v78, v96 quad_perm:[1,0,3,2] row_mask:0xf bank_mask:0xf bound_ctrl:1
	v_xor_b32_e32 v200, v83, v79
	v_xor_b32_e32 v201, v83, v95
	v_xor_b32_e32 v202, v83, v94
	v_xor_b32_e32 v203, v83, v78
	v_add_f32_dpp v204, v79, v200 quad_perm:[2,3,0,1] row_mask:0xf bank_mask:0xf bound_ctrl:1
	v_add_f32_dpp v205, v95, v201 quad_perm:[2,3,0,1] row_mask:0xf bank_mask:0xf bound_ctrl:1
	v_add_f32_dpp v206, v94, v202 quad_perm:[2,3,0,1] row_mask:0xf bank_mask:0xf bound_ctrl:1
	v_add_f32_dpp v207, v78, v203 quad_perm:[2,3,0,1] row_mask:0xf bank_mask:0xf bound_ctrl:1
	v_xor_b32_e32 v200, v84, v204
	v_xor_b32_e32 v201, v84, v205
	v_xor_b32_e32 v202, v84, v206
	v_xor_b32_e32 v203, v84, v207
	v_add_f32_dpp v79, v204, v200 row_shl:4 row_mask:0xf bank_mask:0x5
	v_add_f32_dpp v95, v205, v201 row_shl:4 row_mask:0xf bank_mask:0x5
	v_add_f32_dpp v94, v206, v202 row_shl:4 row_mask:0xf bank_mask:0x5
	v_add_f32_dpp v96, v207, v203 row_shl:4 row_mask:0xf bank_mask:0x5
	v_add_f32_dpp v79, v204, v200 row_shr:4 row_mask:0xf bank_mask:0xa
	v_add_f32_dpp v95, v205, v201 row_shr:4 row_mask:0xf bank_mask:0xa
	v_add_f32_dpp v94, v206, v202 row_shr:4 row_mask:0xf bank_mask:0xa
	v_add_f32_dpp v96, v207, v203 row_shr:4 row_mask:0xf bank_mask:0xa
	v_max_f32_e64 v78, |v79|, |v95|
	v_max_f32_e64 v98, |v94|, |v96|
	v_max3_f32 v97, v97, v78, v98
	v_cvt_pk_bf16_f32 v78, v79, v95
	v_cvt_pk_bf16_f32 v79, v94, v96
	s_waitcnt vmcnt(21)
	v_lshlrev_b32_e32 v94, 16, v76
	v_and_b32_e32 v76, 0xffff0000, v76
	v_lshlrev_b32_e32 v95, 16, v77
	v_and_b32_e32 v77, 0xffff0000, v77
	v_add_f32_e32 v96, v94, v76
	v_sub_f32_e32 v76, v94, v76
	v_add_f32_e32 v94, v95, v77
	v_sub_f32_e32 v77, v95, v77
	v_add_f32_e32 v95, v96, v94
	v_sub_f32_e32 v94, v96, v94
	v_add_f32_e32 v98, v76, v77
	v_sub_f32_e32 v76, v76, v77
	v_xor_b32_e32 v77, v82, v95
	v_xor_b32_e32 v96, v82, v94
	s_nop 0
	v_add_f32_dpp v77, v95, v77 quad_perm:[1,0,3,2] row_mask:0xf bank_mask:0xf bound_ctrl:1
	v_xor_b32_e32 v95, v82, v98
	v_add_f32_dpp v94, v94, v96 quad_perm:[1,0,3,2] row_mask:0xf bank_mask:0xf bound_ctrl:1
	v_xor_b32_e32 v96, v82, v76
	v_add_f32_dpp v95, v98, v95 quad_perm:[1,0,3,2] row_mask:0xf bank_mask:0xf bound_ctrl:1
	s_nop 0
	v_add_f32_dpp v76, v76, v96 quad_perm:[1,0,3,2] row_mask:0xf bank_mask:0xf bound_ctrl:1
	v_xor_b32_e32 v200, v83, v77
	v_xor_b32_e32 v201, v83, v95
	v_xor_b32_e32 v202, v83, v94
	v_xor_b32_e32 v203, v83, v76
	v_add_f32_dpp v204, v77, v200 quad_perm:[2,3,0,1] row_mask:0xf bank_mask:0xf bound_ctrl:1
	v_add_f32_dpp v205, v95, v201 quad_perm:[2,3,0,1] row_mask:0xf bank_mask:0xf bound_ctrl:1
	v_add_f32_dpp v206, v94, v202 quad_perm:[2,3,0,1] row_mask:0xf bank_mask:0xf bound_ctrl:1
	v_add_f32_dpp v207, v76, v203 quad_perm:[2,3,0,1] row_mask:0xf bank_mask:0xf bound_ctrl:1
	v_xor_b32_e32 v200, v84, v204
	v_xor_b32_e32 v201, v84, v205
	v_xor_b32_e32 v202, v84, v206
	v_xor_b32_e32 v203, v84, v207
	v_add_f32_dpp v77, v204, v200 row_shl:4 row_mask:0xf bank_mask:0x5
	v_add_f32_dpp v95, v205, v201 row_shl:4 row_mask:0xf bank_mask:0x5
	v_add_f32_dpp v94, v206, v202 row_shl:4 row_mask:0xf bank_mask:0x5
	v_add_f32_dpp v96, v207, v203 row_shl:4 row_mask:0xf bank_mask:0x5
	v_add_f32_dpp v77, v204, v200 row_shr:4 row_mask:0xf bank_mask:0xa
	v_add_f32_dpp v95, v205, v201 row_shr:4 row_mask:0xf bank_mask:0xa
	v_add_f32_dpp v94, v206, v202 row_shr:4 row_mask:0xf bank_mask:0xa
	v_add_f32_dpp v96, v207, v203 row_shr:4 row_mask:0xf bank_mask:0xa
	v_max_f32_e64 v76, |v77|, |v95|
	v_max_f32_e64 v98, |v94|, |v96|
	v_max3_f32 v97, v97, v76, v98
	v_cvt_pk_bf16_f32 v76, v77, v95
	v_cvt_pk_bf16_f32 v77, v94, v96
	s_waitcnt vmcnt(20)
	v_lshlrev_b32_e32 v94, 16, v74
	v_and_b32_e32 v74, 0xffff0000, v74
	v_lshlrev_b32_e32 v95, 16, v75
	v_and_b32_e32 v75, 0xffff0000, v75
	v_add_f32_e32 v96, v94, v74
	v_sub_f32_e32 v74, v94, v74
	v_add_f32_e32 v94, v95, v75
	v_sub_f32_e32 v75, v95, v75
	v_add_f32_e32 v95, v96, v94
	v_sub_f32_e32 v94, v96, v94
	v_add_f32_e32 v98, v74, v75
	v_sub_f32_e32 v74, v74, v75
	v_xor_b32_e32 v75, v82, v95
	v_xor_b32_e32 v96, v82, v94
	s_nop 0
	v_add_f32_dpp v75, v95, v75 quad_perm:[1,0,3,2] row_mask:0xf bank_mask:0xf bound_ctrl:1
	v_xor_b32_e32 v95, v82, v98
	v_add_f32_dpp v94, v94, v96 quad_perm:[1,0,3,2] row_mask:0xf bank_mask:0xf bound_ctrl:1
	v_xor_b32_e32 v96, v82, v74
	v_add_f32_dpp v95, v98, v95 quad_perm:[1,0,3,2] row_mask:0xf bank_mask:0xf bound_ctrl:1
	s_nop 0
	v_add_f32_dpp v74, v74, v96 quad_perm:[1,0,3,2] row_mask:0xf bank_mask:0xf bound_ctrl:1
	v_xor_b32_e32 v200, v83, v75
	v_xor_b32_e32 v201, v83, v95
	v_xor_b32_e32 v202, v83, v94
	v_xor_b32_e32 v203, v83, v74
	v_add_f32_dpp v204, v75, v200 quad_perm:[2,3,0,1] row_mask:0xf bank_mask:0xf bound_ctrl:1
	v_add_f32_dpp v205, v95, v201 quad_perm:[2,3,0,1] row_mask:0xf bank_mask:0xf bound_ctrl:1
	v_add_f32_dpp v206, v94, v202 quad_perm:[2,3,0,1] row_mask:0xf bank_mask:0xf bound_ctrl:1
	v_add_f32_dpp v207, v74, v203 quad_perm:[2,3,0,1] row_mask:0xf bank_mask:0xf bound_ctrl:1
	v_xor_b32_e32 v200, v84, v204
	v_xor_b32_e32 v201, v84, v205
	v_xor_b32_e32 v202, v84, v206
	v_xor_b32_e32 v203, v84, v207
	v_add_f32_dpp v75, v204, v200 row_shl:4 row_mask:0xf bank_mask:0x5
	v_add_f32_dpp v95, v205, v201 row_shl:4 row_mask:0xf bank_mask:0x5
	v_add_f32_dpp v94, v206, v202 row_shl:4 row_mask:0xf bank_mask:0x5
	v_add_f32_dpp v96, v207, v203 row_shl:4 row_mask:0xf bank_mask:0x5
	v_add_f32_dpp v75, v204, v200 row_shr:4 row_mask:0xf bank_mask:0xa
	v_add_f32_dpp v95, v205, v201 row_shr:4 row_mask:0xf bank_mask:0xa
	v_add_f32_dpp v94, v206, v202 row_shr:4 row_mask:0xf bank_mask:0xa
	v_add_f32_dpp v96, v207, v203 row_shr:4 row_mask:0xf bank_mask:0xa
	v_max_f32_e64 v74, |v75|, |v95|
	v_max_f32_e64 v98, |v94|, |v96|
	v_max3_f32 v97, v97, v74, v98
	v_cvt_pk_bf16_f32 v74, v75, v95
	v_cvt_pk_bf16_f32 v75, v94, v96
	s_waitcnt vmcnt(3)
	v_lshlrev_b32_e32 v94, 16, v72
	v_and_b32_e32 v72, 0xffff0000, v72
	v_lshlrev_b32_e32 v95, 16, v73
	v_and_b32_e32 v73, 0xffff0000, v73
	v_add_f32_e32 v96, v94, v72
	v_sub_f32_e32 v72, v94, v72
	v_add_f32_e32 v94, v95, v73
	v_sub_f32_e32 v73, v95, v73
	v_add_f32_e32 v95, v96, v94
	v_sub_f32_e32 v94, v96, v94
	v_add_f32_e32 v98, v72, v73
	v_sub_f32_e32 v72, v72, v73
	v_xor_b32_e32 v73, v82, v95
	v_xor_b32_e32 v96, v82, v94
	s_nop 0
	v_add_f32_dpp v73, v95, v73 quad_perm:[1,0,3,2] row_mask:0xf bank_mask:0xf bound_ctrl:1
	v_xor_b32_e32 v95, v82, v98
	v_add_f32_dpp v94, v94, v96 quad_perm:[1,0,3,2] row_mask:0xf bank_mask:0xf bound_ctrl:1
	v_xor_b32_e32 v96, v82, v72
	v_add_f32_dpp v95, v98, v95 quad_perm:[1,0,3,2] row_mask:0xf bank_mask:0xf bound_ctrl:1
	s_nop 0
	v_add_f32_dpp v72, v72, v96 quad_perm:[1,0,3,2] row_mask:0xf bank_mask:0xf bound_ctrl:1
	v_xor_b32_e32 v200, v83, v73
	v_xor_b32_e32 v201, v83, v95
	v_xor_b32_e32 v202, v83, v94
	v_xor_b32_e32 v203, v83, v72
	v_add_f32_dpp v204, v73, v200 quad_perm:[2,3,0,1] row_mask:0xf bank_mask:0xf bound_ctrl:1
	v_add_f32_dpp v205, v95, v201 quad_perm:[2,3,0,1] row_mask:0xf bank_mask:0xf bound_ctrl:1
	v_add_f32_dpp v206, v94, v202 quad_perm:[2,3,0,1] row_mask:0xf bank_mask:0xf bound_ctrl:1
	v_add_f32_dpp v207, v72, v203 quad_perm:[2,3,0,1] row_mask:0xf bank_mask:0xf bound_ctrl:1
	v_xor_b32_e32 v200, v84, v204
	v_xor_b32_e32 v201, v84, v205
	v_xor_b32_e32 v202, v84, v206
	v_xor_b32_e32 v203, v84, v207
	v_add_f32_dpp v73, v204, v200 row_shl:4 row_mask:0xf bank_mask:0x5
	v_add_f32_dpp v95, v205, v201 row_shl:4 row_mask:0xf bank_mask:0x5
	v_add_f32_dpp v94, v206, v202 row_shl:4 row_mask:0xf bank_mask:0x5
	v_add_f32_dpp v96, v207, v203 row_shl:4 row_mask:0xf bank_mask:0x5
	v_add_f32_dpp v73, v204, v200 row_shr:4 row_mask:0xf bank_mask:0xa
	v_add_f32_dpp v95, v205, v201 row_shr:4 row_mask:0xf bank_mask:0xa
	v_add_f32_dpp v94, v206, v202 row_shr:4 row_mask:0xf bank_mask:0xa
	v_add_f32_dpp v96, v207, v203 row_shr:4 row_mask:0xf bank_mask:0xa
	v_max_f32_e64 v72, |v73|, |v95|
	v_max_f32_e64 v98, |v94|, |v96|
	v_max3_f32 v97, v97, v72, v98
	v_cvt_pk_bf16_f32 v72, v73, v95
	v_cvt_pk_bf16_f32 v73, v94, v96
	v_lshlrev_b32_e32 v94, 16, v70
	v_and_b32_e32 v70, 0xffff0000, v70
	v_lshlrev_b32_e32 v95, 16, v71
	v_and_b32_e32 v71, 0xffff0000, v71
	v_add_f32_e32 v96, v94, v70
	v_sub_f32_e32 v70, v94, v70
	v_add_f32_e32 v94, v95, v71
	v_sub_f32_e32 v71, v95, v71
	v_add_f32_e32 v95, v96, v94
	v_sub_f32_e32 v94, v96, v94
	v_add_f32_e32 v98, v70, v71
	v_sub_f32_e32 v70, v70, v71
	v_xor_b32_e32 v71, v82, v95
	v_xor_b32_e32 v96, v82, v94
	s_nop 0
	v_add_f32_dpp v71, v95, v71 quad_perm:[1,0,3,2] row_mask:0xf bank_mask:0xf bound_ctrl:1
	v_xor_b32_e32 v95, v82, v98
	v_add_f32_dpp v94, v94, v96 quad_perm:[1,0,3,2] row_mask:0xf bank_mask:0xf bound_ctrl:1
	v_xor_b32_e32 v96, v82, v70
	v_add_f32_dpp v95, v98, v95 quad_perm:[1,0,3,2] row_mask:0xf bank_mask:0xf bound_ctrl:1
	s_nop 0
	v_add_f32_dpp v70, v70, v96 quad_perm:[1,0,3,2] row_mask:0xf bank_mask:0xf bound_ctrl:1
	v_xor_b32_e32 v200, v83, v71
	v_xor_b32_e32 v201, v83, v95
	v_xor_b32_e32 v202, v83, v94
	v_xor_b32_e32 v203, v83, v70
	v_add_f32_dpp v204, v71, v200 quad_perm:[2,3,0,1] row_mask:0xf bank_mask:0xf bound_ctrl:1
	v_add_f32_dpp v205, v95, v201 quad_perm:[2,3,0,1] row_mask:0xf bank_mask:0xf bound_ctrl:1
	v_add_f32_dpp v206, v94, v202 quad_perm:[2,3,0,1] row_mask:0xf bank_mask:0xf bound_ctrl:1
	v_add_f32_dpp v207, v70, v203 quad_perm:[2,3,0,1] row_mask:0xf bank_mask:0xf bound_ctrl:1
	v_xor_b32_e32 v200, v84, v204
	v_xor_b32_e32 v201, v84, v205
	v_xor_b32_e32 v202, v84, v206
	v_xor_b32_e32 v203, v84, v207
	v_add_f32_dpp v71, v204, v200 row_shl:4 row_mask:0xf bank_mask:0x5
	v_add_f32_dpp v95, v205, v201 row_shl:4 row_mask:0xf bank_mask:0x5
	v_add_f32_dpp v94, v206, v202 row_shl:4 row_mask:0xf bank_mask:0x5
	v_add_f32_dpp v96, v207, v203 row_shl:4 row_mask:0xf bank_mask:0x5
	v_add_f32_dpp v71, v204, v200 row_shr:4 row_mask:0xf bank_mask:0xa
	v_add_f32_dpp v95, v205, v201 row_shr:4 row_mask:0xf bank_mask:0xa
	v_add_f32_dpp v94, v206, v202 row_shr:4 row_mask:0xf bank_mask:0xa
	v_add_f32_dpp v96, v207, v203 row_shr:4 row_mask:0xf bank_mask:0xa
	v_max_f32_e64 v70, |v71|, |v95|
	v_max_f32_e64 v98, |v94|, |v96|
	v_max3_f32 v97, v97, v70, v98
	v_cvt_pk_bf16_f32 v70, v71, v95
	v_cvt_pk_bf16_f32 v71, v94, v96
	v_lshlrev_b32_e32 v94, 16, v68
	v_and_b32_e32 v68, 0xffff0000, v68
	v_lshlrev_b32_e32 v95, 16, v69
	v_and_b32_e32 v69, 0xffff0000, v69
	v_add_f32_e32 v96, v94, v68
	v_sub_f32_e32 v68, v94, v68
	v_add_f32_e32 v94, v95, v69
	v_sub_f32_e32 v69, v95, v69
	v_add_f32_e32 v95, v96, v94
	v_sub_f32_e32 v94, v96, v94
	v_add_f32_e32 v98, v68, v69
	v_sub_f32_e32 v68, v68, v69
	v_xor_b32_e32 v69, v82, v95
	v_xor_b32_e32 v96, v82, v94
	s_nop 0
	v_add_f32_dpp v69, v95, v69 quad_perm:[1,0,3,2] row_mask:0xf bank_mask:0xf bound_ctrl:1
	v_xor_b32_e32 v95, v82, v98
	v_add_f32_dpp v94, v94, v96 quad_perm:[1,0,3,2] row_mask:0xf bank_mask:0xf bound_ctrl:1
	v_xor_b32_e32 v96, v82, v68
	v_add_f32_dpp v95, v98, v95 quad_perm:[1,0,3,2] row_mask:0xf bank_mask:0xf bound_ctrl:1
	s_nop 0
	v_add_f32_dpp v68, v68, v96 quad_perm:[1,0,3,2] row_mask:0xf bank_mask:0xf bound_ctrl:1
	v_xor_b32_e32 v200, v83, v69
	v_xor_b32_e32 v201, v83, v95
	v_xor_b32_e32 v202, v83, v94
	v_xor_b32_e32 v203, v83, v68
	v_add_f32_dpp v204, v69, v200 quad_perm:[2,3,0,1] row_mask:0xf bank_mask:0xf bound_ctrl:1
	v_add_f32_dpp v205, v95, v201 quad_perm:[2,3,0,1] row_mask:0xf bank_mask:0xf bound_ctrl:1
	v_add_f32_dpp v206, v94, v202 quad_perm:[2,3,0,1] row_mask:0xf bank_mask:0xf bound_ctrl:1
	v_add_f32_dpp v207, v68, v203 quad_perm:[2,3,0,1] row_mask:0xf bank_mask:0xf bound_ctrl:1
	v_xor_b32_e32 v200, v84, v204
	v_xor_b32_e32 v201, v84, v205
	v_xor_b32_e32 v202, v84, v206
	v_xor_b32_e32 v203, v84, v207
	v_add_f32_dpp v69, v204, v200 row_shl:4 row_mask:0xf bank_mask:0x5
	v_add_f32_dpp v95, v205, v201 row_shl:4 row_mask:0xf bank_mask:0x5
	v_add_f32_dpp v94, v206, v202 row_shl:4 row_mask:0xf bank_mask:0x5
	v_add_f32_dpp v96, v207, v203 row_shl:4 row_mask:0xf bank_mask:0x5
	v_add_f32_dpp v69, v204, v200 row_shr:4 row_mask:0xf bank_mask:0xa
	v_add_f32_dpp v95, v205, v201 row_shr:4 row_mask:0xf bank_mask:0xa
	v_add_f32_dpp v94, v206, v202 row_shr:4 row_mask:0xf bank_mask:0xa
	v_add_f32_dpp v96, v207, v203 row_shr:4 row_mask:0xf bank_mask:0xa
	v_max_f32_e64 v68, |v69|, |v95|
	v_max_f32_e64 v98, |v94|, |v96|
	v_max3_f32 v97, v97, v68, v98
	v_cvt_pk_bf16_f32 v68, v69, v95
	v_cvt_pk_bf16_f32 v69, v94, v96
	v_lshlrev_b32_e32 v94, 16, v66
	v_and_b32_e32 v66, 0xffff0000, v66
	v_lshlrev_b32_e32 v95, 16, v67
	v_and_b32_e32 v67, 0xffff0000, v67
	v_add_f32_e32 v96, v94, v66
	v_sub_f32_e32 v66, v94, v66
	v_add_f32_e32 v94, v95, v67
	v_sub_f32_e32 v67, v95, v67
	v_add_f32_e32 v95, v96, v94
	v_sub_f32_e32 v94, v96, v94
	v_add_f32_e32 v98, v66, v67
	v_sub_f32_e32 v66, v66, v67
	v_xor_b32_e32 v67, v82, v95
	v_xor_b32_e32 v96, v82, v94
	s_nop 0
	v_add_f32_dpp v67, v95, v67 quad_perm:[1,0,3,2] row_mask:0xf bank_mask:0xf bound_ctrl:1
	v_xor_b32_e32 v95, v82, v98
	v_add_f32_dpp v94, v94, v96 quad_perm:[1,0,3,2] row_mask:0xf bank_mask:0xf bound_ctrl:1
	v_xor_b32_e32 v96, v82, v66
	v_add_f32_dpp v95, v98, v95 quad_perm:[1,0,3,2] row_mask:0xf bank_mask:0xf bound_ctrl:1
	s_nop 0
	v_add_f32_dpp v66, v66, v96 quad_perm:[1,0,3,2] row_mask:0xf bank_mask:0xf bound_ctrl:1
	v_xor_b32_e32 v200, v83, v67
	v_xor_b32_e32 v201, v83, v95
	v_xor_b32_e32 v202, v83, v94
	v_xor_b32_e32 v203, v83, v66
	v_add_f32_dpp v204, v67, v200 quad_perm:[2,3,0,1] row_mask:0xf bank_mask:0xf bound_ctrl:1
	v_add_f32_dpp v205, v95, v201 quad_perm:[2,3,0,1] row_mask:0xf bank_mask:0xf bound_ctrl:1
	v_add_f32_dpp v206, v94, v202 quad_perm:[2,3,0,1] row_mask:0xf bank_mask:0xf bound_ctrl:1
	v_add_f32_dpp v207, v66, v203 quad_perm:[2,3,0,1] row_mask:0xf bank_mask:0xf bound_ctrl:1
	v_xor_b32_e32 v200, v84, v204
	v_xor_b32_e32 v201, v84, v205
	v_xor_b32_e32 v202, v84, v206
	v_xor_b32_e32 v203, v84, v207
	v_add_f32_dpp v67, v204, v200 row_shl:4 row_mask:0xf bank_mask:0x5
	v_add_f32_dpp v95, v205, v201 row_shl:4 row_mask:0xf bank_mask:0x5
	v_add_f32_dpp v94, v206, v202 row_shl:4 row_mask:0xf bank_mask:0x5
	v_add_f32_dpp v96, v207, v203 row_shl:4 row_mask:0xf bank_mask:0x5
	v_add_f32_dpp v67, v204, v200 row_shr:4 row_mask:0xf bank_mask:0xa
	v_add_f32_dpp v95, v205, v201 row_shr:4 row_mask:0xf bank_mask:0xa
	v_add_f32_dpp v94, v206, v202 row_shr:4 row_mask:0xf bank_mask:0xa
	v_add_f32_dpp v96, v207, v203 row_shr:4 row_mask:0xf bank_mask:0xa
	v_max_f32_e64 v66, |v67|, |v95|
	v_max_f32_e64 v98, |v94|, |v96|
	v_max3_f32 v97, v97, v66, v98
	v_cvt_pk_bf16_f32 v66, v67, v95
	v_cvt_pk_bf16_f32 v67, v94, v96
	v_lshlrev_b32_e32 v94, 16, v64
	v_and_b32_e32 v64, 0xffff0000, v64
	v_lshlrev_b32_e32 v95, 16, v65
	v_and_b32_e32 v65, 0xffff0000, v65
	v_add_f32_e32 v96, v94, v64
	v_sub_f32_e32 v64, v94, v64
	v_add_f32_e32 v94, v95, v65
	v_sub_f32_e32 v65, v95, v65
	v_add_f32_e32 v95, v96, v94
	v_sub_f32_e32 v94, v96, v94
	v_add_f32_e32 v98, v64, v65
	v_sub_f32_e32 v64, v64, v65
	v_xor_b32_e32 v65, v82, v95
	v_xor_b32_e32 v96, v82, v94
	s_nop 0
	v_add_f32_dpp v65, v95, v65 quad_perm:[1,0,3,2] row_mask:0xf bank_mask:0xf bound_ctrl:1
	v_xor_b32_e32 v95, v82, v98
	v_add_f32_dpp v94, v94, v96 quad_perm:[1,0,3,2] row_mask:0xf bank_mask:0xf bound_ctrl:1
	v_xor_b32_e32 v96, v82, v64
	v_add_f32_dpp v95, v98, v95 quad_perm:[1,0,3,2] row_mask:0xf bank_mask:0xf bound_ctrl:1
	s_nop 0
	v_add_f32_dpp v64, v64, v96 quad_perm:[1,0,3,2] row_mask:0xf bank_mask:0xf bound_ctrl:1
	v_xor_b32_e32 v200, v83, v65
	v_xor_b32_e32 v201, v83, v95
	v_xor_b32_e32 v202, v83, v94
	v_xor_b32_e32 v203, v83, v64
	v_add_f32_dpp v204, v65, v200 quad_perm:[2,3,0,1] row_mask:0xf bank_mask:0xf bound_ctrl:1
	v_add_f32_dpp v205, v95, v201 quad_perm:[2,3,0,1] row_mask:0xf bank_mask:0xf bound_ctrl:1
	v_add_f32_dpp v206, v94, v202 quad_perm:[2,3,0,1] row_mask:0xf bank_mask:0xf bound_ctrl:1
	v_add_f32_dpp v207, v64, v203 quad_perm:[2,3,0,1] row_mask:0xf bank_mask:0xf bound_ctrl:1
	v_xor_b32_e32 v200, v84, v204
	v_xor_b32_e32 v201, v84, v205
	v_xor_b32_e32 v202, v84, v206
	v_xor_b32_e32 v203, v84, v207
	v_add_f32_dpp v65, v204, v200 row_shl:4 row_mask:0xf bank_mask:0x5
	v_add_f32_dpp v95, v205, v201 row_shl:4 row_mask:0xf bank_mask:0x5
	v_add_f32_dpp v94, v206, v202 row_shl:4 row_mask:0xf bank_mask:0x5
	v_add_f32_dpp v96, v207, v203 row_shl:4 row_mask:0xf bank_mask:0x5
	v_add_f32_dpp v65, v204, v200 row_shr:4 row_mask:0xf bank_mask:0xa
	v_add_f32_dpp v95, v205, v201 row_shr:4 row_mask:0xf bank_mask:0xa
	v_add_f32_dpp v94, v206, v202 row_shr:4 row_mask:0xf bank_mask:0xa
	v_add_f32_dpp v96, v207, v203 row_shr:4 row_mask:0xf bank_mask:0xa
	v_max_f32_e64 v64, |v65|, |v95|
	v_max_f32_e64 v98, |v94|, |v96|
	v_max3_f32 v97, v97, v64, v98
	v_cvt_pk_bf16_f32 v64, v65, v95
	v_cvt_pk_bf16_f32 v65, v94, v96
	v_lshlrev_b32_e32 v94, 16, v62
	v_and_b32_e32 v62, 0xffff0000, v62
	v_lshlrev_b32_e32 v95, 16, v63
	v_and_b32_e32 v63, 0xffff0000, v63
	v_add_f32_e32 v96, v94, v62
	v_sub_f32_e32 v62, v94, v62
	v_add_f32_e32 v94, v95, v63
	v_sub_f32_e32 v63, v95, v63
	v_add_f32_e32 v95, v96, v94
	v_sub_f32_e32 v94, v96, v94
	v_add_f32_e32 v98, v62, v63
	v_sub_f32_e32 v62, v62, v63
	v_xor_b32_e32 v63, v82, v95
	v_xor_b32_e32 v96, v82, v94
	s_nop 0
	v_add_f32_dpp v63, v95, v63 quad_perm:[1,0,3,2] row_mask:0xf bank_mask:0xf bound_ctrl:1
	v_xor_b32_e32 v95, v82, v98
	v_add_f32_dpp v94, v94, v96 quad_perm:[1,0,3,2] row_mask:0xf bank_mask:0xf bound_ctrl:1
	v_xor_b32_e32 v96, v82, v62
	v_add_f32_dpp v95, v98, v95 quad_perm:[1,0,3,2] row_mask:0xf bank_mask:0xf bound_ctrl:1
	s_nop 0
	v_add_f32_dpp v62, v62, v96 quad_perm:[1,0,3,2] row_mask:0xf bank_mask:0xf bound_ctrl:1
	v_xor_b32_e32 v200, v83, v63
	v_xor_b32_e32 v201, v83, v95
	v_xor_b32_e32 v202, v83, v94
	v_xor_b32_e32 v203, v83, v62
	v_add_f32_dpp v204, v63, v200 quad_perm:[2,3,0,1] row_mask:0xf bank_mask:0xf bound_ctrl:1
	v_add_f32_dpp v205, v95, v201 quad_perm:[2,3,0,1] row_mask:0xf bank_mask:0xf bound_ctrl:1
	v_add_f32_dpp v206, v94, v202 quad_perm:[2,3,0,1] row_mask:0xf bank_mask:0xf bound_ctrl:1
	v_add_f32_dpp v207, v62, v203 quad_perm:[2,3,0,1] row_mask:0xf bank_mask:0xf bound_ctrl:1
	v_xor_b32_e32 v200, v84, v204
	v_xor_b32_e32 v201, v84, v205
	v_xor_b32_e32 v202, v84, v206
	v_xor_b32_e32 v203, v84, v207
	v_add_f32_dpp v63, v204, v200 row_shl:4 row_mask:0xf bank_mask:0x5
	v_add_f32_dpp v95, v205, v201 row_shl:4 row_mask:0xf bank_mask:0x5
	v_add_f32_dpp v94, v206, v202 row_shl:4 row_mask:0xf bank_mask:0x5
	v_add_f32_dpp v96, v207, v203 row_shl:4 row_mask:0xf bank_mask:0x5
	v_add_f32_dpp v63, v204, v200 row_shr:4 row_mask:0xf bank_mask:0xa
	v_add_f32_dpp v95, v205, v201 row_shr:4 row_mask:0xf bank_mask:0xa
	v_add_f32_dpp v94, v206, v202 row_shr:4 row_mask:0xf bank_mask:0xa
	v_add_f32_dpp v96, v207, v203 row_shr:4 row_mask:0xf bank_mask:0xa
	v_max_f32_e64 v62, |v63|, |v95|
	v_max_f32_e64 v98, |v94|, |v96|
	v_max3_f32 v97, v97, v62, v98
	v_cvt_pk_bf16_f32 v62, v63, v95
	v_cvt_pk_bf16_f32 v63, v94, v96
	v_lshlrev_b32_e32 v94, 16, v60
	v_and_b32_e32 v60, 0xffff0000, v60
	v_lshlrev_b32_e32 v95, 16, v61
	v_and_b32_e32 v61, 0xffff0000, v61
	v_add_f32_e32 v96, v94, v60
	v_sub_f32_e32 v60, v94, v60
	v_add_f32_e32 v94, v95, v61
	v_sub_f32_e32 v61, v95, v61
	v_add_f32_e32 v95, v96, v94
	v_sub_f32_e32 v94, v96, v94
	v_add_f32_e32 v98, v60, v61
	v_sub_f32_e32 v60, v60, v61
	v_xor_b32_e32 v61, v82, v95
	v_xor_b32_e32 v96, v82, v94
	s_nop 0
	v_add_f32_dpp v61, v95, v61 quad_perm:[1,0,3,2] row_mask:0xf bank_mask:0xf bound_ctrl:1
	v_xor_b32_e32 v95, v82, v98
	v_add_f32_dpp v94, v94, v96 quad_perm:[1,0,3,2] row_mask:0xf bank_mask:0xf bound_ctrl:1
	v_xor_b32_e32 v96, v82, v60
	v_add_f32_dpp v95, v98, v95 quad_perm:[1,0,3,2] row_mask:0xf bank_mask:0xf bound_ctrl:1
	s_nop 0
	v_add_f32_dpp v60, v60, v96 quad_perm:[1,0,3,2] row_mask:0xf bank_mask:0xf bound_ctrl:1
	v_xor_b32_e32 v200, v83, v61
	v_xor_b32_e32 v201, v83, v95
	v_xor_b32_e32 v202, v83, v94
	v_xor_b32_e32 v203, v83, v60
	v_add_f32_dpp v204, v61, v200 quad_perm:[2,3,0,1] row_mask:0xf bank_mask:0xf bound_ctrl:1
	v_add_f32_dpp v205, v95, v201 quad_perm:[2,3,0,1] row_mask:0xf bank_mask:0xf bound_ctrl:1
	v_add_f32_dpp v206, v94, v202 quad_perm:[2,3,0,1] row_mask:0xf bank_mask:0xf bound_ctrl:1
	v_add_f32_dpp v207, v60, v203 quad_perm:[2,3,0,1] row_mask:0xf bank_mask:0xf bound_ctrl:1
	v_xor_b32_e32 v200, v84, v204
	v_xor_b32_e32 v201, v84, v205
	v_xor_b32_e32 v202, v84, v206
	v_xor_b32_e32 v203, v84, v207
	v_add_f32_dpp v61, v204, v200 row_shl:4 row_mask:0xf bank_mask:0x5
	v_add_f32_dpp v95, v205, v201 row_shl:4 row_mask:0xf bank_mask:0x5
	v_add_f32_dpp v94, v206, v202 row_shl:4 row_mask:0xf bank_mask:0x5
	v_add_f32_dpp v96, v207, v203 row_shl:4 row_mask:0xf bank_mask:0x5
	v_add_f32_dpp v61, v204, v200 row_shr:4 row_mask:0xf bank_mask:0xa
	v_add_f32_dpp v95, v205, v201 row_shr:4 row_mask:0xf bank_mask:0xa
	v_add_f32_dpp v94, v206, v202 row_shr:4 row_mask:0xf bank_mask:0xa
	v_add_f32_dpp v96, v207, v203 row_shr:4 row_mask:0xf bank_mask:0xa
	v_max_f32_e64 v60, |v61|, |v95|
	v_max_f32_e64 v98, |v94|, |v96|
	v_max3_f32 v97, v97, v60, v98
	v_cvt_pk_bf16_f32 v60, v61, v95
	v_cvt_pk_bf16_f32 v61, v94, v96
	v_lshlrev_b32_e32 v94, 16, v58
	v_and_b32_e32 v58, 0xffff0000, v58
	v_lshlrev_b32_e32 v95, 16, v59
	v_and_b32_e32 v59, 0xffff0000, v59
	v_add_f32_e32 v96, v94, v58
	v_sub_f32_e32 v58, v94, v58
	v_add_f32_e32 v94, v95, v59
	v_sub_f32_e32 v59, v95, v59
	v_add_f32_e32 v95, v96, v94
	v_sub_f32_e32 v94, v96, v94
	v_add_f32_e32 v98, v58, v59
	v_sub_f32_e32 v58, v58, v59
	v_xor_b32_e32 v59, v82, v95
	v_xor_b32_e32 v96, v82, v94
	s_nop 0
	v_add_f32_dpp v59, v95, v59 quad_perm:[1,0,3,2] row_mask:0xf bank_mask:0xf bound_ctrl:1
	v_xor_b32_e32 v95, v82, v98
	v_add_f32_dpp v94, v94, v96 quad_perm:[1,0,3,2] row_mask:0xf bank_mask:0xf bound_ctrl:1
	v_xor_b32_e32 v96, v82, v58
	v_add_f32_dpp v95, v98, v95 quad_perm:[1,0,3,2] row_mask:0xf bank_mask:0xf bound_ctrl:1
	s_nop 0
	v_add_f32_dpp v58, v58, v96 quad_perm:[1,0,3,2] row_mask:0xf bank_mask:0xf bound_ctrl:1
	v_xor_b32_e32 v200, v83, v59
	v_xor_b32_e32 v201, v83, v95
	v_xor_b32_e32 v202, v83, v94
	v_xor_b32_e32 v203, v83, v58
	v_add_f32_dpp v204, v59, v200 quad_perm:[2,3,0,1] row_mask:0xf bank_mask:0xf bound_ctrl:1
	v_add_f32_dpp v205, v95, v201 quad_perm:[2,3,0,1] row_mask:0xf bank_mask:0xf bound_ctrl:1
	v_add_f32_dpp v206, v94, v202 quad_perm:[2,3,0,1] row_mask:0xf bank_mask:0xf bound_ctrl:1
	v_add_f32_dpp v207, v58, v203 quad_perm:[2,3,0,1] row_mask:0xf bank_mask:0xf bound_ctrl:1
	v_xor_b32_e32 v200, v84, v204
	v_xor_b32_e32 v201, v84, v205
	v_xor_b32_e32 v202, v84, v206
	v_xor_b32_e32 v203, v84, v207
	v_add_f32_dpp v59, v204, v200 row_shl:4 row_mask:0xf bank_mask:0x5
	v_add_f32_dpp v95, v205, v201 row_shl:4 row_mask:0xf bank_mask:0x5
	v_add_f32_dpp v94, v206, v202 row_shl:4 row_mask:0xf bank_mask:0x5
	v_add_f32_dpp v96, v207, v203 row_shl:4 row_mask:0xf bank_mask:0x5
	v_add_f32_dpp v59, v204, v200 row_shr:4 row_mask:0xf bank_mask:0xa
	v_add_f32_dpp v95, v205, v201 row_shr:4 row_mask:0xf bank_mask:0xa
	v_add_f32_dpp v94, v206, v202 row_shr:4 row_mask:0xf bank_mask:0xa
	v_add_f32_dpp v96, v207, v203 row_shr:4 row_mask:0xf bank_mask:0xa
	v_max_f32_e64 v58, |v59|, |v95|
	v_max_f32_e64 v98, |v94|, |v96|
	v_max3_f32 v97, v97, v58, v98
	v_cvt_pk_bf16_f32 v58, v59, v95
	v_cvt_pk_bf16_f32 v59, v94, v96
	s_waitcnt vmcnt(2)
	v_lshlrev_b32_e32 v94, 16, v56
	v_and_b32_e32 v56, 0xffff0000, v56
	v_lshlrev_b32_e32 v95, 16, v57
	v_and_b32_e32 v57, 0xffff0000, v57
	v_add_f32_e32 v96, v94, v56
	v_sub_f32_e32 v56, v94, v56
	v_add_f32_e32 v94, v95, v57
	v_sub_f32_e32 v57, v95, v57
	v_add_f32_e32 v95, v96, v94
	v_sub_f32_e32 v94, v96, v94
	v_add_f32_e32 v98, v56, v57
	v_sub_f32_e32 v56, v56, v57
	v_xor_b32_e32 v57, v82, v95
	v_xor_b32_e32 v96, v82, v94
	s_nop 0
	v_add_f32_dpp v57, v95, v57 quad_perm:[1,0,3,2] row_mask:0xf bank_mask:0xf bound_ctrl:1
	v_xor_b32_e32 v95, v82, v98
	v_add_f32_dpp v94, v94, v96 quad_perm:[1,0,3,2] row_mask:0xf bank_mask:0xf bound_ctrl:1
	v_xor_b32_e32 v96, v82, v56
	v_add_f32_dpp v95, v98, v95 quad_perm:[1,0,3,2] row_mask:0xf bank_mask:0xf bound_ctrl:1
	s_nop 0
	v_add_f32_dpp v56, v56, v96 quad_perm:[1,0,3,2] row_mask:0xf bank_mask:0xf bound_ctrl:1
	v_xor_b32_e32 v200, v83, v57
	v_xor_b32_e32 v201, v83, v95
	v_xor_b32_e32 v202, v83, v94
	v_xor_b32_e32 v203, v83, v56
	v_add_f32_dpp v204, v57, v200 quad_perm:[2,3,0,1] row_mask:0xf bank_mask:0xf bound_ctrl:1
	v_add_f32_dpp v205, v95, v201 quad_perm:[2,3,0,1] row_mask:0xf bank_mask:0xf bound_ctrl:1
	v_add_f32_dpp v206, v94, v202 quad_perm:[2,3,0,1] row_mask:0xf bank_mask:0xf bound_ctrl:1
	v_add_f32_dpp v207, v56, v203 quad_perm:[2,3,0,1] row_mask:0xf bank_mask:0xf bound_ctrl:1
	v_xor_b32_e32 v200, v84, v204
	v_xor_b32_e32 v201, v84, v205
	v_xor_b32_e32 v202, v84, v206
	v_xor_b32_e32 v203, v84, v207
	v_add_f32_dpp v57, v204, v200 row_shl:4 row_mask:0xf bank_mask:0x5
	v_add_f32_dpp v95, v205, v201 row_shl:4 row_mask:0xf bank_mask:0x5
	v_add_f32_dpp v94, v206, v202 row_shl:4 row_mask:0xf bank_mask:0x5
	v_add_f32_dpp v96, v207, v203 row_shl:4 row_mask:0xf bank_mask:0x5
	v_add_f32_dpp v57, v204, v200 row_shr:4 row_mask:0xf bank_mask:0xa
	v_add_f32_dpp v95, v205, v201 row_shr:4 row_mask:0xf bank_mask:0xa
	v_add_f32_dpp v94, v206, v202 row_shr:4 row_mask:0xf bank_mask:0xa
	v_add_f32_dpp v96, v207, v203 row_shr:4 row_mask:0xf bank_mask:0xa
	v_max_f32_e64 v56, |v57|, |v95|
	v_max_f32_e64 v98, |v94|, |v96|
	v_max3_f32 v97, v97, v56, v98
	v_cvt_pk_bf16_f32 v56, v57, v95
	v_cvt_pk_bf16_f32 v57, v94, v96
	s_waitcnt vmcnt(1)
	v_lshlrev_b32_e32 v94, 16, v54
	v_and_b32_e32 v54, 0xffff0000, v54
	v_lshlrev_b32_e32 v95, 16, v55
	v_and_b32_e32 v55, 0xffff0000, v55
	v_add_f32_e32 v96, v94, v54
	v_sub_f32_e32 v54, v94, v54
	v_add_f32_e32 v94, v95, v55
	v_sub_f32_e32 v55, v95, v55
	v_add_f32_e32 v95, v96, v94
	v_sub_f32_e32 v94, v96, v94
	v_add_f32_e32 v98, v54, v55
	v_sub_f32_e32 v54, v54, v55
	v_xor_b32_e32 v55, v82, v95
	v_xor_b32_e32 v96, v82, v94
	s_nop 0
	v_add_f32_dpp v55, v95, v55 quad_perm:[1,0,3,2] row_mask:0xf bank_mask:0xf bound_ctrl:1
	v_xor_b32_e32 v95, v82, v98
	v_add_f32_dpp v94, v94, v96 quad_perm:[1,0,3,2] row_mask:0xf bank_mask:0xf bound_ctrl:1
	v_xor_b32_e32 v96, v82, v54
	v_add_f32_dpp v95, v98, v95 quad_perm:[1,0,3,2] row_mask:0xf bank_mask:0xf bound_ctrl:1
	s_nop 0
	v_add_f32_dpp v54, v54, v96 quad_perm:[1,0,3,2] row_mask:0xf bank_mask:0xf bound_ctrl:1
	v_xor_b32_e32 v200, v83, v55
	v_xor_b32_e32 v201, v83, v95
	v_xor_b32_e32 v202, v83, v94
	v_xor_b32_e32 v203, v83, v54
	v_add_f32_dpp v204, v55, v200 quad_perm:[2,3,0,1] row_mask:0xf bank_mask:0xf bound_ctrl:1
	v_add_f32_dpp v205, v95, v201 quad_perm:[2,3,0,1] row_mask:0xf bank_mask:0xf bound_ctrl:1
	v_add_f32_dpp v206, v94, v202 quad_perm:[2,3,0,1] row_mask:0xf bank_mask:0xf bound_ctrl:1
	v_add_f32_dpp v207, v54, v203 quad_perm:[2,3,0,1] row_mask:0xf bank_mask:0xf bound_ctrl:1
	v_xor_b32_e32 v200, v84, v204
	v_xor_b32_e32 v201, v84, v205
	v_xor_b32_e32 v202, v84, v206
	v_xor_b32_e32 v203, v84, v207
	v_add_f32_dpp v55, v204, v200 row_shl:4 row_mask:0xf bank_mask:0x5
	v_add_f32_dpp v95, v205, v201 row_shl:4 row_mask:0xf bank_mask:0x5
	v_add_f32_dpp v94, v206, v202 row_shl:4 row_mask:0xf bank_mask:0x5
	v_add_f32_dpp v96, v207, v203 row_shl:4 row_mask:0xf bank_mask:0x5
	v_add_f32_dpp v55, v204, v200 row_shr:4 row_mask:0xf bank_mask:0xa
	v_add_f32_dpp v95, v205, v201 row_shr:4 row_mask:0xf bank_mask:0xa
	v_add_f32_dpp v94, v206, v202 row_shr:4 row_mask:0xf bank_mask:0xa
	v_add_f32_dpp v96, v207, v203 row_shr:4 row_mask:0xf bank_mask:0xa
	v_max_f32_e64 v54, |v55|, |v95|
	v_max_f32_e64 v98, |v94|, |v96|
	v_max3_f32 v97, v97, v54, v98
	v_cvt_pk_bf16_f32 v54, v55, v95
	v_cvt_pk_bf16_f32 v55, v94, v96
	v_lshlrev_b32_e32 v94, 16, v52
	v_and_b32_e32 v52, 0xffff0000, v52
	v_lshlrev_b32_e32 v95, 16, v53
	v_and_b32_e32 v53, 0xffff0000, v53
	v_add_f32_e32 v96, v94, v52
	v_sub_f32_e32 v52, v94, v52
	v_add_f32_e32 v94, v95, v53
	v_sub_f32_e32 v53, v95, v53
	v_add_f32_e32 v95, v96, v94
	v_sub_f32_e32 v94, v96, v94
	v_add_f32_e32 v98, v52, v53
	v_sub_f32_e32 v52, v52, v53
	v_xor_b32_e32 v53, v82, v95
	v_xor_b32_e32 v96, v82, v94
	s_nop 0
	v_add_f32_dpp v53, v95, v53 quad_perm:[1,0,3,2] row_mask:0xf bank_mask:0xf bound_ctrl:1
	v_xor_b32_e32 v95, v82, v98
	v_add_f32_dpp v94, v94, v96 quad_perm:[1,0,3,2] row_mask:0xf bank_mask:0xf bound_ctrl:1
	v_xor_b32_e32 v96, v82, v52
	v_add_f32_dpp v95, v98, v95 quad_perm:[1,0,3,2] row_mask:0xf bank_mask:0xf bound_ctrl:1
	s_nop 0
	v_add_f32_dpp v52, v52, v96 quad_perm:[1,0,3,2] row_mask:0xf bank_mask:0xf bound_ctrl:1
	v_xor_b32_e32 v200, v83, v53
	v_xor_b32_e32 v201, v83, v95
	v_xor_b32_e32 v202, v83, v94
	v_xor_b32_e32 v203, v83, v52
	v_add_f32_dpp v204, v53, v200 quad_perm:[2,3,0,1] row_mask:0xf bank_mask:0xf bound_ctrl:1
	v_add_f32_dpp v205, v95, v201 quad_perm:[2,3,0,1] row_mask:0xf bank_mask:0xf bound_ctrl:1
	v_add_f32_dpp v206, v94, v202 quad_perm:[2,3,0,1] row_mask:0xf bank_mask:0xf bound_ctrl:1
	v_add_f32_dpp v207, v52, v203 quad_perm:[2,3,0,1] row_mask:0xf bank_mask:0xf bound_ctrl:1
	v_xor_b32_e32 v200, v84, v204
	v_xor_b32_e32 v201, v84, v205
	v_xor_b32_e32 v202, v84, v206
	v_xor_b32_e32 v203, v84, v207
	v_add_f32_dpp v53, v204, v200 row_shl:4 row_mask:0xf bank_mask:0x5
	v_add_f32_dpp v95, v205, v201 row_shl:4 row_mask:0xf bank_mask:0x5
	v_add_f32_dpp v94, v206, v202 row_shl:4 row_mask:0xf bank_mask:0x5
	v_add_f32_dpp v96, v207, v203 row_shl:4 row_mask:0xf bank_mask:0x5
	v_add_f32_dpp v53, v204, v200 row_shr:4 row_mask:0xf bank_mask:0xa
	v_add_f32_dpp v95, v205, v201 row_shr:4 row_mask:0xf bank_mask:0xa
	v_add_f32_dpp v94, v206, v202 row_shr:4 row_mask:0xf bank_mask:0xa
	v_add_f32_dpp v96, v207, v203 row_shr:4 row_mask:0xf bank_mask:0xa
	v_max_f32_e64 v52, |v53|, |v95|
	v_max_f32_e64 v98, |v94|, |v96|
	v_max3_f32 v97, v97, v52, v98
	v_cvt_pk_bf16_f32 v52, v53, v95
	v_cvt_pk_bf16_f32 v53, v94, v96
	v_lshlrev_b32_e32 v94, 16, v50
	v_and_b32_e32 v50, 0xffff0000, v50
	v_lshlrev_b32_e32 v95, 16, v51
	v_and_b32_e32 v51, 0xffff0000, v51
	v_add_f32_e32 v96, v94, v50
	v_sub_f32_e32 v50, v94, v50
	v_add_f32_e32 v94, v95, v51
	v_sub_f32_e32 v51, v95, v51
	v_add_f32_e32 v95, v96, v94
	v_sub_f32_e32 v94, v96, v94
	v_add_f32_e32 v98, v50, v51
	v_sub_f32_e32 v50, v50, v51
	v_xor_b32_e32 v51, v82, v95
	v_xor_b32_e32 v96, v82, v94
	s_nop 0
	v_add_f32_dpp v51, v95, v51 quad_perm:[1,0,3,2] row_mask:0xf bank_mask:0xf bound_ctrl:1
	v_xor_b32_e32 v95, v82, v98
	v_add_f32_dpp v94, v94, v96 quad_perm:[1,0,3,2] row_mask:0xf bank_mask:0xf bound_ctrl:1
	v_xor_b32_e32 v96, v82, v50
	v_add_f32_dpp v95, v98, v95 quad_perm:[1,0,3,2] row_mask:0xf bank_mask:0xf bound_ctrl:1
	s_nop 0
	v_add_f32_dpp v50, v50, v96 quad_perm:[1,0,3,2] row_mask:0xf bank_mask:0xf bound_ctrl:1
	v_xor_b32_e32 v200, v83, v51
	v_xor_b32_e32 v201, v83, v95
	v_xor_b32_e32 v202, v83, v94
	v_xor_b32_e32 v203, v83, v50
	v_add_f32_dpp v204, v51, v200 quad_perm:[2,3,0,1] row_mask:0xf bank_mask:0xf bound_ctrl:1
	v_add_f32_dpp v205, v95, v201 quad_perm:[2,3,0,1] row_mask:0xf bank_mask:0xf bound_ctrl:1
	v_add_f32_dpp v206, v94, v202 quad_perm:[2,3,0,1] row_mask:0xf bank_mask:0xf bound_ctrl:1
	v_add_f32_dpp v207, v50, v203 quad_perm:[2,3,0,1] row_mask:0xf bank_mask:0xf bound_ctrl:1
	v_xor_b32_e32 v200, v84, v204
	v_xor_b32_e32 v201, v84, v205
	v_xor_b32_e32 v202, v84, v206
	v_xor_b32_e32 v203, v84, v207
	v_add_f32_dpp v51, v204, v200 row_shl:4 row_mask:0xf bank_mask:0x5
	v_add_f32_dpp v95, v205, v201 row_shl:4 row_mask:0xf bank_mask:0x5
	v_add_f32_dpp v94, v206, v202 row_shl:4 row_mask:0xf bank_mask:0x5
	v_add_f32_dpp v96, v207, v203 row_shl:4 row_mask:0xf bank_mask:0x5
	v_add_f32_dpp v51, v204, v200 row_shr:4 row_mask:0xf bank_mask:0xa
	v_add_f32_dpp v95, v205, v201 row_shr:4 row_mask:0xf bank_mask:0xa
	v_add_f32_dpp v94, v206, v202 row_shr:4 row_mask:0xf bank_mask:0xa
	v_add_f32_dpp v96, v207, v203 row_shr:4 row_mask:0xf bank_mask:0xa
	v_max_f32_e64 v50, |v51|, |v95|
	v_max_f32_e64 v98, |v94|, |v96|
	v_max3_f32 v97, v97, v50, v98
	v_cvt_pk_bf16_f32 v50, v51, v95
	v_cvt_pk_bf16_f32 v51, v94, v96
	v_lshlrev_b32_e32 v94, 16, v48
	v_and_b32_e32 v48, 0xffff0000, v48
	v_lshlrev_b32_e32 v95, 16, v49
	v_and_b32_e32 v49, 0xffff0000, v49
	v_add_f32_e32 v96, v94, v48
	v_sub_f32_e32 v48, v94, v48
	v_add_f32_e32 v94, v95, v49
	v_sub_f32_e32 v49, v95, v49
	v_add_f32_e32 v95, v96, v94
	v_sub_f32_e32 v94, v96, v94
	v_add_f32_e32 v98, v48, v49
	v_sub_f32_e32 v48, v48, v49
	v_xor_b32_e32 v49, v82, v95
	v_xor_b32_e32 v96, v82, v94
	s_nop 0
	v_add_f32_dpp v49, v95, v49 quad_perm:[1,0,3,2] row_mask:0xf bank_mask:0xf bound_ctrl:1
	v_xor_b32_e32 v95, v82, v98
	v_add_f32_dpp v94, v94, v96 quad_perm:[1,0,3,2] row_mask:0xf bank_mask:0xf bound_ctrl:1
	v_xor_b32_e32 v96, v82, v48
	v_add_f32_dpp v95, v98, v95 quad_perm:[1,0,3,2] row_mask:0xf bank_mask:0xf bound_ctrl:1
	s_nop 0
	v_add_f32_dpp v48, v48, v96 quad_perm:[1,0,3,2] row_mask:0xf bank_mask:0xf bound_ctrl:1
	v_xor_b32_e32 v200, v83, v49
	v_xor_b32_e32 v201, v83, v95
	v_xor_b32_e32 v202, v83, v94
	v_xor_b32_e32 v203, v83, v48
	v_add_f32_dpp v204, v49, v200 quad_perm:[2,3,0,1] row_mask:0xf bank_mask:0xf bound_ctrl:1
	v_add_f32_dpp v205, v95, v201 quad_perm:[2,3,0,1] row_mask:0xf bank_mask:0xf bound_ctrl:1
	v_add_f32_dpp v206, v94, v202 quad_perm:[2,3,0,1] row_mask:0xf bank_mask:0xf bound_ctrl:1
	v_add_f32_dpp v207, v48, v203 quad_perm:[2,3,0,1] row_mask:0xf bank_mask:0xf bound_ctrl:1
	v_xor_b32_e32 v200, v84, v204
	v_xor_b32_e32 v201, v84, v205
	v_xor_b32_e32 v202, v84, v206
	v_xor_b32_e32 v203, v84, v207
	v_add_f32_dpp v49, v204, v200 row_shl:4 row_mask:0xf bank_mask:0x5
	v_add_f32_dpp v95, v205, v201 row_shl:4 row_mask:0xf bank_mask:0x5
	v_add_f32_dpp v94, v206, v202 row_shl:4 row_mask:0xf bank_mask:0x5
	v_add_f32_dpp v96, v207, v203 row_shl:4 row_mask:0xf bank_mask:0x5
	v_add_f32_dpp v49, v204, v200 row_shr:4 row_mask:0xf bank_mask:0xa
	v_add_f32_dpp v95, v205, v201 row_shr:4 row_mask:0xf bank_mask:0xa
	v_add_f32_dpp v94, v206, v202 row_shr:4 row_mask:0xf bank_mask:0xa
	v_add_f32_dpp v96, v207, v203 row_shr:4 row_mask:0xf bank_mask:0xa
	v_max_f32_e64 v48, |v49|, |v95|
	v_max_f32_e64 v98, |v94|, |v96|
	v_max3_f32 v97, v97, v48, v98
	v_cvt_pk_bf16_f32 v48, v49, v95
	v_cvt_pk_bf16_f32 v49, v94, v96
	v_lshlrev_b32_e32 v94, 16, v46
	v_and_b32_e32 v46, 0xffff0000, v46
	v_lshlrev_b32_e32 v95, 16, v47
	v_and_b32_e32 v47, 0xffff0000, v47
	v_add_f32_e32 v96, v94, v46
	v_sub_f32_e32 v46, v94, v46
	v_add_f32_e32 v94, v95, v47
	v_sub_f32_e32 v47, v95, v47
	v_add_f32_e32 v95, v96, v94
	v_sub_f32_e32 v94, v96, v94
	v_add_f32_e32 v98, v46, v47
	v_sub_f32_e32 v46, v46, v47
	v_xor_b32_e32 v47, v82, v95
	v_xor_b32_e32 v96, v82, v94
	s_nop 0
	v_add_f32_dpp v47, v95, v47 quad_perm:[1,0,3,2] row_mask:0xf bank_mask:0xf bound_ctrl:1
	v_xor_b32_e32 v95, v82, v98
	v_add_f32_dpp v94, v94, v96 quad_perm:[1,0,3,2] row_mask:0xf bank_mask:0xf bound_ctrl:1
	v_xor_b32_e32 v96, v82, v46
	v_add_f32_dpp v95, v98, v95 quad_perm:[1,0,3,2] row_mask:0xf bank_mask:0xf bound_ctrl:1
	s_nop 0
	v_add_f32_dpp v46, v46, v96 quad_perm:[1,0,3,2] row_mask:0xf bank_mask:0xf bound_ctrl:1
	v_xor_b32_e32 v200, v83, v47
	v_xor_b32_e32 v201, v83, v95
	v_xor_b32_e32 v202, v83, v94
	v_xor_b32_e32 v203, v83, v46
	v_add_f32_dpp v204, v47, v200 quad_perm:[2,3,0,1] row_mask:0xf bank_mask:0xf bound_ctrl:1
	v_add_f32_dpp v205, v95, v201 quad_perm:[2,3,0,1] row_mask:0xf bank_mask:0xf bound_ctrl:1
	v_add_f32_dpp v206, v94, v202 quad_perm:[2,3,0,1] row_mask:0xf bank_mask:0xf bound_ctrl:1
	v_add_f32_dpp v207, v46, v203 quad_perm:[2,3,0,1] row_mask:0xf bank_mask:0xf bound_ctrl:1
	v_xor_b32_e32 v200, v84, v204
	v_xor_b32_e32 v201, v84, v205
	v_xor_b32_e32 v202, v84, v206
	v_xor_b32_e32 v203, v84, v207
	v_add_f32_dpp v47, v204, v200 row_shl:4 row_mask:0xf bank_mask:0x5
	v_add_f32_dpp v95, v205, v201 row_shl:4 row_mask:0xf bank_mask:0x5
	v_add_f32_dpp v94, v206, v202 row_shl:4 row_mask:0xf bank_mask:0x5
	v_add_f32_dpp v96, v207, v203 row_shl:4 row_mask:0xf bank_mask:0x5
	v_add_f32_dpp v47, v204, v200 row_shr:4 row_mask:0xf bank_mask:0xa
	v_add_f32_dpp v95, v205, v201 row_shr:4 row_mask:0xf bank_mask:0xa
	v_add_f32_dpp v94, v206, v202 row_shr:4 row_mask:0xf bank_mask:0xa
	v_add_f32_dpp v96, v207, v203 row_shr:4 row_mask:0xf bank_mask:0xa
	v_max_f32_e64 v46, |v47|, |v95|
	v_max_f32_e64 v98, |v94|, |v96|
	v_max3_f32 v97, v97, v46, v98
	v_cvt_pk_bf16_f32 v46, v47, v95
	v_cvt_pk_bf16_f32 v47, v94, v96
	v_lshlrev_b32_e32 v94, 16, v44
	v_and_b32_e32 v44, 0xffff0000, v44
	v_lshlrev_b32_e32 v95, 16, v45
	v_and_b32_e32 v45, 0xffff0000, v45
	v_add_f32_e32 v96, v94, v44
	v_sub_f32_e32 v44, v94, v44
	v_add_f32_e32 v94, v95, v45
	v_sub_f32_e32 v45, v95, v45
	v_add_f32_e32 v95, v96, v94
	v_sub_f32_e32 v94, v96, v94
	v_add_f32_e32 v98, v44, v45
	v_sub_f32_e32 v44, v44, v45
	v_xor_b32_e32 v45, v82, v95
	v_xor_b32_e32 v96, v82, v94
	s_nop 0
	v_add_f32_dpp v45, v95, v45 quad_perm:[1,0,3,2] row_mask:0xf bank_mask:0xf bound_ctrl:1
	v_xor_b32_e32 v95, v82, v98
	v_add_f32_dpp v94, v94, v96 quad_perm:[1,0,3,2] row_mask:0xf bank_mask:0xf bound_ctrl:1
	v_xor_b32_e32 v96, v82, v44
	v_add_f32_dpp v95, v98, v95 quad_perm:[1,0,3,2] row_mask:0xf bank_mask:0xf bound_ctrl:1
	s_nop 0
	v_add_f32_dpp v44, v44, v96 quad_perm:[1,0,3,2] row_mask:0xf bank_mask:0xf bound_ctrl:1
	v_xor_b32_e32 v200, v83, v45
	v_xor_b32_e32 v201, v83, v95
	v_xor_b32_e32 v202, v83, v94
	v_xor_b32_e32 v203, v83, v44
	v_add_f32_dpp v204, v45, v200 quad_perm:[2,3,0,1] row_mask:0xf bank_mask:0xf bound_ctrl:1
	v_add_f32_dpp v205, v95, v201 quad_perm:[2,3,0,1] row_mask:0xf bank_mask:0xf bound_ctrl:1
	v_add_f32_dpp v206, v94, v202 quad_perm:[2,3,0,1] row_mask:0xf bank_mask:0xf bound_ctrl:1
	v_add_f32_dpp v207, v44, v203 quad_perm:[2,3,0,1] row_mask:0xf bank_mask:0xf bound_ctrl:1
	v_xor_b32_e32 v200, v84, v204
	v_xor_b32_e32 v201, v84, v205
	v_xor_b32_e32 v202, v84, v206
	v_xor_b32_e32 v203, v84, v207
	v_add_f32_dpp v45, v204, v200 row_shl:4 row_mask:0xf bank_mask:0x5
	v_add_f32_dpp v95, v205, v201 row_shl:4 row_mask:0xf bank_mask:0x5
	v_add_f32_dpp v94, v206, v202 row_shl:4 row_mask:0xf bank_mask:0x5
	v_add_f32_dpp v96, v207, v203 row_shl:4 row_mask:0xf bank_mask:0x5
	v_add_f32_dpp v45, v204, v200 row_shr:4 row_mask:0xf bank_mask:0xa
	v_add_f32_dpp v95, v205, v201 row_shr:4 row_mask:0xf bank_mask:0xa
	v_add_f32_dpp v94, v206, v202 row_shr:4 row_mask:0xf bank_mask:0xa
	v_add_f32_dpp v96, v207, v203 row_shr:4 row_mask:0xf bank_mask:0xa
	v_max_f32_e64 v44, |v45|, |v95|
	v_max_f32_e64 v98, |v94|, |v96|
	v_max3_f32 v97, v97, v44, v98
	v_cvt_pk_bf16_f32 v44, v45, v95
	v_cvt_pk_bf16_f32 v45, v94, v96
	v_lshlrev_b32_e32 v94, 16, v42
	v_and_b32_e32 v42, 0xffff0000, v42
	v_lshlrev_b32_e32 v95, 16, v43
	v_and_b32_e32 v43, 0xffff0000, v43
	v_add_f32_e32 v96, v94, v42
	v_sub_f32_e32 v42, v94, v42
	v_add_f32_e32 v94, v95, v43
	v_sub_f32_e32 v43, v95, v43
	v_add_f32_e32 v95, v96, v94
	v_sub_f32_e32 v94, v96, v94
	v_add_f32_e32 v98, v42, v43
	v_sub_f32_e32 v42, v42, v43
	v_xor_b32_e32 v43, v82, v95
	v_xor_b32_e32 v96, v82, v94
	s_nop 0
	v_add_f32_dpp v43, v95, v43 quad_perm:[1,0,3,2] row_mask:0xf bank_mask:0xf bound_ctrl:1
	v_xor_b32_e32 v95, v82, v98
	v_add_f32_dpp v94, v94, v96 quad_perm:[1,0,3,2] row_mask:0xf bank_mask:0xf bound_ctrl:1
	v_xor_b32_e32 v96, v82, v42
	v_add_f32_dpp v95, v98, v95 quad_perm:[1,0,3,2] row_mask:0xf bank_mask:0xf bound_ctrl:1
	s_nop 0
	v_add_f32_dpp v42, v42, v96 quad_perm:[1,0,3,2] row_mask:0xf bank_mask:0xf bound_ctrl:1
	v_xor_b32_e32 v200, v83, v43
	v_xor_b32_e32 v201, v83, v95
	v_xor_b32_e32 v202, v83, v94
	v_xor_b32_e32 v203, v83, v42
	v_add_f32_dpp v204, v43, v200 quad_perm:[2,3,0,1] row_mask:0xf bank_mask:0xf bound_ctrl:1
	v_add_f32_dpp v205, v95, v201 quad_perm:[2,3,0,1] row_mask:0xf bank_mask:0xf bound_ctrl:1
	v_add_f32_dpp v206, v94, v202 quad_perm:[2,3,0,1] row_mask:0xf bank_mask:0xf bound_ctrl:1
	v_add_f32_dpp v207, v42, v203 quad_perm:[2,3,0,1] row_mask:0xf bank_mask:0xf bound_ctrl:1
	v_xor_b32_e32 v200, v84, v204
	v_xor_b32_e32 v201, v84, v205
	v_xor_b32_e32 v202, v84, v206
	v_xor_b32_e32 v203, v84, v207
	v_add_f32_dpp v43, v204, v200 row_shl:4 row_mask:0xf bank_mask:0x5
	v_add_f32_dpp v95, v205, v201 row_shl:4 row_mask:0xf bank_mask:0x5
	v_add_f32_dpp v94, v206, v202 row_shl:4 row_mask:0xf bank_mask:0x5
	v_add_f32_dpp v96, v207, v203 row_shl:4 row_mask:0xf bank_mask:0x5
	v_add_f32_dpp v43, v204, v200 row_shr:4 row_mask:0xf bank_mask:0xa
	v_add_f32_dpp v95, v205, v201 row_shr:4 row_mask:0xf bank_mask:0xa
	v_add_f32_dpp v94, v206, v202 row_shr:4 row_mask:0xf bank_mask:0xa
	v_add_f32_dpp v96, v207, v203 row_shr:4 row_mask:0xf bank_mask:0xa
	v_max_f32_e64 v42, |v43|, |v95|
	v_max_f32_e64 v98, |v94|, |v96|
	v_max3_f32 v97, v97, v42, v98
	v_cvt_pk_bf16_f32 v42, v43, v95
	v_cvt_pk_bf16_f32 v43, v94, v96
	v_lshlrev_b32_e32 v94, 16, v40
	v_and_b32_e32 v40, 0xffff0000, v40
	v_lshlrev_b32_e32 v95, 16, v41
	v_and_b32_e32 v41, 0xffff0000, v41
	v_add_f32_e32 v96, v94, v40
	v_sub_f32_e32 v40, v94, v40
	v_add_f32_e32 v94, v95, v41
	v_sub_f32_e32 v41, v95, v41
	v_add_f32_e32 v95, v96, v94
	v_sub_f32_e32 v94, v96, v94
	v_add_f32_e32 v98, v40, v41
	v_sub_f32_e32 v40, v40, v41
	v_xor_b32_e32 v41, v82, v95
	v_xor_b32_e32 v96, v82, v94
	s_nop 0
	v_add_f32_dpp v41, v95, v41 quad_perm:[1,0,3,2] row_mask:0xf bank_mask:0xf bound_ctrl:1
	v_xor_b32_e32 v95, v82, v98
	v_add_f32_dpp v94, v94, v96 quad_perm:[1,0,3,2] row_mask:0xf bank_mask:0xf bound_ctrl:1
	v_xor_b32_e32 v96, v82, v40
	v_add_f32_dpp v95, v98, v95 quad_perm:[1,0,3,2] row_mask:0xf bank_mask:0xf bound_ctrl:1
	s_nop 0
	v_add_f32_dpp v40, v40, v96 quad_perm:[1,0,3,2] row_mask:0xf bank_mask:0xf bound_ctrl:1
	v_xor_b32_e32 v200, v83, v41
	v_xor_b32_e32 v201, v83, v95
	v_xor_b32_e32 v202, v83, v94
	v_xor_b32_e32 v203, v83, v40
	v_add_f32_dpp v204, v41, v200 quad_perm:[2,3,0,1] row_mask:0xf bank_mask:0xf bound_ctrl:1
	v_add_f32_dpp v205, v95, v201 quad_perm:[2,3,0,1] row_mask:0xf bank_mask:0xf bound_ctrl:1
	v_add_f32_dpp v206, v94, v202 quad_perm:[2,3,0,1] row_mask:0xf bank_mask:0xf bound_ctrl:1
	v_add_f32_dpp v207, v40, v203 quad_perm:[2,3,0,1] row_mask:0xf bank_mask:0xf bound_ctrl:1
	v_xor_b32_e32 v200, v84, v204
	v_xor_b32_e32 v201, v84, v205
	v_xor_b32_e32 v202, v84, v206
	v_xor_b32_e32 v203, v84, v207
	v_add_f32_dpp v41, v204, v200 row_shl:4 row_mask:0xf bank_mask:0x5
	v_add_f32_dpp v95, v205, v201 row_shl:4 row_mask:0xf bank_mask:0x5
	v_add_f32_dpp v94, v206, v202 row_shl:4 row_mask:0xf bank_mask:0x5
	v_add_f32_dpp v96, v207, v203 row_shl:4 row_mask:0xf bank_mask:0x5
	v_add_f32_dpp v41, v204, v200 row_shr:4 row_mask:0xf bank_mask:0xa
	v_add_f32_dpp v95, v205, v201 row_shr:4 row_mask:0xf bank_mask:0xa
	v_add_f32_dpp v94, v206, v202 row_shr:4 row_mask:0xf bank_mask:0xa
	v_add_f32_dpp v96, v207, v203 row_shr:4 row_mask:0xf bank_mask:0xa
	v_max_f32_e64 v40, |v41|, |v95|
	v_max_f32_e64 v98, |v94|, |v96|
	v_max3_f32 v97, v97, v40, v98
	v_cvt_pk_bf16_f32 v40, v41, v95
	v_cvt_pk_bf16_f32 v41, v94, v96
	v_lshlrev_b32_e32 v94, 16, v38
	v_and_b32_e32 v38, 0xffff0000, v38
	v_lshlrev_b32_e32 v95, 16, v39
	v_and_b32_e32 v39, 0xffff0000, v39
	v_add_f32_e32 v96, v94, v38
	v_sub_f32_e32 v38, v94, v38
	v_add_f32_e32 v94, v95, v39
	v_sub_f32_e32 v39, v95, v39
	v_add_f32_e32 v95, v96, v94
	v_sub_f32_e32 v94, v96, v94
	v_add_f32_e32 v98, v38, v39
	v_sub_f32_e32 v38, v38, v39
	v_xor_b32_e32 v39, v82, v95
	v_xor_b32_e32 v96, v82, v94
	s_nop 0
	v_add_f32_dpp v39, v95, v39 quad_perm:[1,0,3,2] row_mask:0xf bank_mask:0xf bound_ctrl:1
	v_xor_b32_e32 v95, v82, v98
	v_add_f32_dpp v94, v94, v96 quad_perm:[1,0,3,2] row_mask:0xf bank_mask:0xf bound_ctrl:1
	v_xor_b32_e32 v96, v82, v38
	v_add_f32_dpp v95, v98, v95 quad_perm:[1,0,3,2] row_mask:0xf bank_mask:0xf bound_ctrl:1
	s_nop 0
	v_add_f32_dpp v38, v38, v96 quad_perm:[1,0,3,2] row_mask:0xf bank_mask:0xf bound_ctrl:1
	v_xor_b32_e32 v200, v83, v39
	v_xor_b32_e32 v201, v83, v95
	v_xor_b32_e32 v202, v83, v94
	v_xor_b32_e32 v203, v83, v38
	v_add_f32_dpp v204, v39, v200 quad_perm:[2,3,0,1] row_mask:0xf bank_mask:0xf bound_ctrl:1
	v_add_f32_dpp v205, v95, v201 quad_perm:[2,3,0,1] row_mask:0xf bank_mask:0xf bound_ctrl:1
	v_add_f32_dpp v206, v94, v202 quad_perm:[2,3,0,1] row_mask:0xf bank_mask:0xf bound_ctrl:1
	v_add_f32_dpp v207, v38, v203 quad_perm:[2,3,0,1] row_mask:0xf bank_mask:0xf bound_ctrl:1
	v_xor_b32_e32 v200, v84, v204
	v_xor_b32_e32 v201, v84, v205
	v_xor_b32_e32 v202, v84, v206
	v_xor_b32_e32 v203, v84, v207
	v_add_f32_dpp v39, v204, v200 row_shl:4 row_mask:0xf bank_mask:0x5
	v_add_f32_dpp v95, v205, v201 row_shl:4 row_mask:0xf bank_mask:0x5
	v_add_f32_dpp v94, v206, v202 row_shl:4 row_mask:0xf bank_mask:0x5
	v_add_f32_dpp v96, v207, v203 row_shl:4 row_mask:0xf bank_mask:0x5
	v_add_f32_dpp v39, v204, v200 row_shr:4 row_mask:0xf bank_mask:0xa
	v_add_f32_dpp v95, v205, v201 row_shr:4 row_mask:0xf bank_mask:0xa
	v_add_f32_dpp v94, v206, v202 row_shr:4 row_mask:0xf bank_mask:0xa
	v_add_f32_dpp v96, v207, v203 row_shr:4 row_mask:0xf bank_mask:0xa
	v_max_f32_e64 v38, |v39|, |v95|
	v_max_f32_e64 v98, |v94|, |v96|
	v_max3_f32 v97, v97, v38, v98
	v_cvt_pk_bf16_f32 v38, v39, v95
	v_cvt_pk_bf16_f32 v39, v94, v96
	v_lshlrev_b32_e32 v94, 16, v36
	v_and_b32_e32 v36, 0xffff0000, v36
	v_lshlrev_b32_e32 v95, 16, v37
	v_and_b32_e32 v37, 0xffff0000, v37
	v_add_f32_e32 v96, v94, v36
	v_sub_f32_e32 v36, v94, v36
	v_add_f32_e32 v94, v95, v37
	v_sub_f32_e32 v37, v95, v37
	v_add_f32_e32 v95, v96, v94
	v_sub_f32_e32 v94, v96, v94
	v_add_f32_e32 v98, v36, v37
	v_sub_f32_e32 v36, v36, v37
	v_xor_b32_e32 v37, v82, v95
	v_xor_b32_e32 v96, v82, v94
	s_nop 0
	v_add_f32_dpp v37, v95, v37 quad_perm:[1,0,3,2] row_mask:0xf bank_mask:0xf bound_ctrl:1
	v_xor_b32_e32 v95, v82, v98
	v_add_f32_dpp v94, v94, v96 quad_perm:[1,0,3,2] row_mask:0xf bank_mask:0xf bound_ctrl:1
	v_xor_b32_e32 v96, v82, v36
	v_add_f32_dpp v95, v98, v95 quad_perm:[1,0,3,2] row_mask:0xf bank_mask:0xf bound_ctrl:1
	s_nop 0
	v_add_f32_dpp v36, v36, v96 quad_perm:[1,0,3,2] row_mask:0xf bank_mask:0xf bound_ctrl:1
	v_xor_b32_e32 v200, v83, v37
	v_xor_b32_e32 v201, v83, v95
	v_xor_b32_e32 v202, v83, v94
	v_xor_b32_e32 v203, v83, v36
	v_add_f32_dpp v204, v37, v200 quad_perm:[2,3,0,1] row_mask:0xf bank_mask:0xf bound_ctrl:1
	v_add_f32_dpp v205, v95, v201 quad_perm:[2,3,0,1] row_mask:0xf bank_mask:0xf bound_ctrl:1
	v_add_f32_dpp v206, v94, v202 quad_perm:[2,3,0,1] row_mask:0xf bank_mask:0xf bound_ctrl:1
	v_add_f32_dpp v207, v36, v203 quad_perm:[2,3,0,1] row_mask:0xf bank_mask:0xf bound_ctrl:1
	v_xor_b32_e32 v200, v84, v204
	v_xor_b32_e32 v201, v84, v205
	v_xor_b32_e32 v202, v84, v206
	v_xor_b32_e32 v203, v84, v207
	v_add_f32_dpp v37, v204, v200 row_shl:4 row_mask:0xf bank_mask:0x5
	v_add_f32_dpp v95, v205, v201 row_shl:4 row_mask:0xf bank_mask:0x5
	v_add_f32_dpp v94, v206, v202 row_shl:4 row_mask:0xf bank_mask:0x5
	v_add_f32_dpp v96, v207, v203 row_shl:4 row_mask:0xf bank_mask:0x5
	v_add_f32_dpp v37, v204, v200 row_shr:4 row_mask:0xf bank_mask:0xa
	v_add_f32_dpp v95, v205, v201 row_shr:4 row_mask:0xf bank_mask:0xa
	v_add_f32_dpp v94, v206, v202 row_shr:4 row_mask:0xf bank_mask:0xa
	v_add_f32_dpp v96, v207, v203 row_shr:4 row_mask:0xf bank_mask:0xa
	v_max_f32_e64 v36, |v37|, |v95|
	v_max_f32_e64 v98, |v94|, |v96|
	v_max3_f32 v97, v97, v36, v98
	v_cvt_pk_bf16_f32 v36, v37, v95
	v_cvt_pk_bf16_f32 v37, v94, v96
	v_lshlrev_b32_e32 v94, 16, v34
	v_and_b32_e32 v34, 0xffff0000, v34
	v_lshlrev_b32_e32 v95, 16, v35
	v_and_b32_e32 v35, 0xffff0000, v35
	v_add_f32_e32 v96, v94, v34
	v_sub_f32_e32 v34, v94, v34
	v_add_f32_e32 v94, v95, v35
	v_sub_f32_e32 v35, v95, v35
	v_add_f32_e32 v95, v96, v94
	v_sub_f32_e32 v94, v96, v94
	v_add_f32_e32 v98, v34, v35
	v_sub_f32_e32 v34, v34, v35
	v_xor_b32_e32 v35, v82, v95
	v_xor_b32_e32 v96, v82, v94
	s_nop 0
	v_add_f32_dpp v35, v95, v35 quad_perm:[1,0,3,2] row_mask:0xf bank_mask:0xf bound_ctrl:1
	v_xor_b32_e32 v95, v82, v98
	v_add_f32_dpp v94, v94, v96 quad_perm:[1,0,3,2] row_mask:0xf bank_mask:0xf bound_ctrl:1
	v_xor_b32_e32 v96, v82, v34
	v_add_f32_dpp v95, v98, v95 quad_perm:[1,0,3,2] row_mask:0xf bank_mask:0xf bound_ctrl:1
	s_nop 0
	v_add_f32_dpp v34, v34, v96 quad_perm:[1,0,3,2] row_mask:0xf bank_mask:0xf bound_ctrl:1
	v_xor_b32_e32 v200, v83, v35
	v_xor_b32_e32 v201, v83, v95
	v_xor_b32_e32 v202, v83, v94
	v_xor_b32_e32 v203, v83, v34
	v_add_f32_dpp v204, v35, v200 quad_perm:[2,3,0,1] row_mask:0xf bank_mask:0xf bound_ctrl:1
	v_add_f32_dpp v205, v95, v201 quad_perm:[2,3,0,1] row_mask:0xf bank_mask:0xf bound_ctrl:1
	v_add_f32_dpp v206, v94, v202 quad_perm:[2,3,0,1] row_mask:0xf bank_mask:0xf bound_ctrl:1
	v_add_f32_dpp v207, v34, v203 quad_perm:[2,3,0,1] row_mask:0xf bank_mask:0xf bound_ctrl:1
	v_xor_b32_e32 v200, v84, v204
	v_xor_b32_e32 v201, v84, v205
	v_xor_b32_e32 v202, v84, v206
	v_xor_b32_e32 v203, v84, v207
	v_add_f32_dpp v35, v204, v200 row_shl:4 row_mask:0xf bank_mask:0x5
	v_add_f32_dpp v95, v205, v201 row_shl:4 row_mask:0xf bank_mask:0x5
	v_add_f32_dpp v94, v206, v202 row_shl:4 row_mask:0xf bank_mask:0x5
	v_add_f32_dpp v96, v207, v203 row_shl:4 row_mask:0xf bank_mask:0x5
	v_add_f32_dpp v35, v204, v200 row_shr:4 row_mask:0xf bank_mask:0xa
	v_add_f32_dpp v95, v205, v201 row_shr:4 row_mask:0xf bank_mask:0xa
	v_add_f32_dpp v94, v206, v202 row_shr:4 row_mask:0xf bank_mask:0xa
	v_add_f32_dpp v96, v207, v203 row_shr:4 row_mask:0xf bank_mask:0xa
	v_max_f32_e64 v34, |v35|, |v95|
	v_max_f32_e64 v98, |v94|, |v96|
	v_max3_f32 v97, v97, v34, v98
	v_cvt_pk_bf16_f32 v34, v35, v95
	v_cvt_pk_bf16_f32 v35, v94, v96
	v_lshlrev_b32_e32 v94, 16, v32
	v_and_b32_e32 v32, 0xffff0000, v32
	v_lshlrev_b32_e32 v95, 16, v33
	v_and_b32_e32 v33, 0xffff0000, v33
	v_add_f32_e32 v96, v94, v32
	v_sub_f32_e32 v32, v94, v32
	v_add_f32_e32 v94, v95, v33
	v_sub_f32_e32 v33, v95, v33
	v_add_f32_e32 v95, v96, v94
	v_sub_f32_e32 v94, v96, v94
	v_add_f32_e32 v98, v32, v33
	v_sub_f32_e32 v32, v32, v33
	v_xor_b32_e32 v33, v82, v95
	v_xor_b32_e32 v96, v82, v94
	s_nop 0
	v_add_f32_dpp v33, v95, v33 quad_perm:[1,0,3,2] row_mask:0xf bank_mask:0xf bound_ctrl:1
	v_xor_b32_e32 v95, v82, v98
	v_add_f32_dpp v94, v94, v96 quad_perm:[1,0,3,2] row_mask:0xf bank_mask:0xf bound_ctrl:1
	v_xor_b32_e32 v96, v82, v32
	v_add_f32_dpp v95, v98, v95 quad_perm:[1,0,3,2] row_mask:0xf bank_mask:0xf bound_ctrl:1
	s_nop 0
	v_add_f32_dpp v32, v32, v96 quad_perm:[1,0,3,2] row_mask:0xf bank_mask:0xf bound_ctrl:1
	v_xor_b32_e32 v200, v83, v33
	v_xor_b32_e32 v201, v83, v95
	v_xor_b32_e32 v202, v83, v94
	v_xor_b32_e32 v203, v83, v32
	v_add_f32_dpp v204, v33, v200 quad_perm:[2,3,0,1] row_mask:0xf bank_mask:0xf bound_ctrl:1
	v_add_f32_dpp v205, v95, v201 quad_perm:[2,3,0,1] row_mask:0xf bank_mask:0xf bound_ctrl:1
	v_add_f32_dpp v206, v94, v202 quad_perm:[2,3,0,1] row_mask:0xf bank_mask:0xf bound_ctrl:1
	v_add_f32_dpp v207, v32, v203 quad_perm:[2,3,0,1] row_mask:0xf bank_mask:0xf bound_ctrl:1
	v_xor_b32_e32 v200, v84, v204
	v_xor_b32_e32 v201, v84, v205
	v_xor_b32_e32 v202, v84, v206
	v_xor_b32_e32 v203, v84, v207
	v_add_f32_dpp v33, v204, v200 row_shl:4 row_mask:0xf bank_mask:0x5
	v_add_f32_dpp v95, v205, v201 row_shl:4 row_mask:0xf bank_mask:0x5
	v_add_f32_dpp v94, v206, v202 row_shl:4 row_mask:0xf bank_mask:0x5
	v_add_f32_dpp v96, v207, v203 row_shl:4 row_mask:0xf bank_mask:0x5
	v_add_f32_dpp v33, v204, v200 row_shr:4 row_mask:0xf bank_mask:0xa
	v_add_f32_dpp v95, v205, v201 row_shr:4 row_mask:0xf bank_mask:0xa
	v_add_f32_dpp v94, v206, v202 row_shr:4 row_mask:0xf bank_mask:0xa
	v_add_f32_dpp v96, v207, v203 row_shr:4 row_mask:0xf bank_mask:0xa
	v_max_f32_e64 v32, |v33|, |v95|
	v_max_f32_e64 v98, |v94|, |v96|
	v_max3_f32 v97, v97, v32, v98
	v_cvt_pk_bf16_f32 v32, v33, v95
	v_cvt_pk_bf16_f32 v33, v94, v96
	v_lshlrev_b32_e32 v94, 16, v30
	v_and_b32_e32 v30, 0xffff0000, v30
	v_lshlrev_b32_e32 v95, 16, v31
	v_and_b32_e32 v31, 0xffff0000, v31
	v_add_f32_e32 v96, v94, v30
	v_sub_f32_e32 v30, v94, v30
	v_add_f32_e32 v94, v95, v31
	v_sub_f32_e32 v31, v95, v31
	v_add_f32_e32 v95, v96, v94
	v_sub_f32_e32 v94, v96, v94
	v_add_f32_e32 v98, v30, v31
	v_sub_f32_e32 v30, v30, v31
	v_xor_b32_e32 v31, v82, v95
	v_xor_b32_e32 v96, v82, v94
	s_nop 0
	v_add_f32_dpp v31, v95, v31 quad_perm:[1,0,3,2] row_mask:0xf bank_mask:0xf bound_ctrl:1
	v_xor_b32_e32 v95, v82, v98
	v_add_f32_dpp v94, v94, v96 quad_perm:[1,0,3,2] row_mask:0xf bank_mask:0xf bound_ctrl:1
	v_xor_b32_e32 v96, v82, v30
	v_add_f32_dpp v95, v98, v95 quad_perm:[1,0,3,2] row_mask:0xf bank_mask:0xf bound_ctrl:1
	s_nop 0
	v_add_f32_dpp v30, v30, v96 quad_perm:[1,0,3,2] row_mask:0xf bank_mask:0xf bound_ctrl:1
	v_xor_b32_e32 v200, v83, v31
	v_xor_b32_e32 v201, v83, v95
	v_xor_b32_e32 v202, v83, v94
	v_xor_b32_e32 v203, v83, v30
	v_add_f32_dpp v204, v31, v200 quad_perm:[2,3,0,1] row_mask:0xf bank_mask:0xf bound_ctrl:1
	v_add_f32_dpp v205, v95, v201 quad_perm:[2,3,0,1] row_mask:0xf bank_mask:0xf bound_ctrl:1
	v_add_f32_dpp v206, v94, v202 quad_perm:[2,3,0,1] row_mask:0xf bank_mask:0xf bound_ctrl:1
	v_add_f32_dpp v207, v30, v203 quad_perm:[2,3,0,1] row_mask:0xf bank_mask:0xf bound_ctrl:1
	v_xor_b32_e32 v200, v84, v204
	v_xor_b32_e32 v201, v84, v205
	v_xor_b32_e32 v202, v84, v206
	v_xor_b32_e32 v203, v84, v207
	v_add_f32_dpp v31, v204, v200 row_shl:4 row_mask:0xf bank_mask:0x5
	v_add_f32_dpp v95, v205, v201 row_shl:4 row_mask:0xf bank_mask:0x5
	v_add_f32_dpp v94, v206, v202 row_shl:4 row_mask:0xf bank_mask:0x5
	v_add_f32_dpp v96, v207, v203 row_shl:4 row_mask:0xf bank_mask:0x5
	v_add_f32_dpp v31, v204, v200 row_shr:4 row_mask:0xf bank_mask:0xa
	v_add_f32_dpp v95, v205, v201 row_shr:4 row_mask:0xf bank_mask:0xa
	v_add_f32_dpp v94, v206, v202 row_shr:4 row_mask:0xf bank_mask:0xa
	v_add_f32_dpp v96, v207, v203 row_shr:4 row_mask:0xf bank_mask:0xa
	v_max_f32_e64 v30, |v31|, |v95|
	v_max_f32_e64 v98, |v94|, |v96|
	v_max3_f32 v97, v97, v30, v98
	v_cvt_pk_bf16_f32 v30, v31, v95
	v_cvt_pk_bf16_f32 v31, v94, v96
	v_lshlrev_b32_e32 v94, 16, v28
	v_and_b32_e32 v28, 0xffff0000, v28
	v_lshlrev_b32_e32 v95, 16, v29
	v_and_b32_e32 v29, 0xffff0000, v29
	v_add_f32_e32 v96, v94, v28
	v_sub_f32_e32 v28, v94, v28
	v_add_f32_e32 v94, v95, v29
	v_sub_f32_e32 v29, v95, v29
	v_add_f32_e32 v95, v96, v94
	v_sub_f32_e32 v94, v96, v94
	v_add_f32_e32 v98, v28, v29
	v_sub_f32_e32 v28, v28, v29
	v_xor_b32_e32 v29, v82, v95
	v_xor_b32_e32 v96, v82, v94
	s_nop 0
	v_add_f32_dpp v29, v95, v29 quad_perm:[1,0,3,2] row_mask:0xf bank_mask:0xf bound_ctrl:1
	v_xor_b32_e32 v95, v82, v98
	v_add_f32_dpp v94, v94, v96 quad_perm:[1,0,3,2] row_mask:0xf bank_mask:0xf bound_ctrl:1
	v_xor_b32_e32 v96, v82, v28
	v_add_f32_dpp v95, v98, v95 quad_perm:[1,0,3,2] row_mask:0xf bank_mask:0xf bound_ctrl:1
	s_nop 0
	v_add_f32_dpp v28, v28, v96 quad_perm:[1,0,3,2] row_mask:0xf bank_mask:0xf bound_ctrl:1
	v_xor_b32_e32 v200, v83, v29
	v_xor_b32_e32 v201, v83, v95
	v_xor_b32_e32 v202, v83, v94
	v_xor_b32_e32 v203, v83, v28
	v_add_f32_dpp v204, v29, v200 quad_perm:[2,3,0,1] row_mask:0xf bank_mask:0xf bound_ctrl:1
	v_add_f32_dpp v205, v95, v201 quad_perm:[2,3,0,1] row_mask:0xf bank_mask:0xf bound_ctrl:1
	v_add_f32_dpp v206, v94, v202 quad_perm:[2,3,0,1] row_mask:0xf bank_mask:0xf bound_ctrl:1
	v_add_f32_dpp v207, v28, v203 quad_perm:[2,3,0,1] row_mask:0xf bank_mask:0xf bound_ctrl:1
	v_xor_b32_e32 v200, v84, v204
	v_xor_b32_e32 v201, v84, v205
	v_xor_b32_e32 v202, v84, v206
	v_xor_b32_e32 v203, v84, v207
	v_add_f32_dpp v29, v204, v200 row_shl:4 row_mask:0xf bank_mask:0x5
	v_add_f32_dpp v95, v205, v201 row_shl:4 row_mask:0xf bank_mask:0x5
	v_add_f32_dpp v94, v206, v202 row_shl:4 row_mask:0xf bank_mask:0x5
	v_add_f32_dpp v96, v207, v203 row_shl:4 row_mask:0xf bank_mask:0x5
	v_add_f32_dpp v29, v204, v200 row_shr:4 row_mask:0xf bank_mask:0xa
	v_add_f32_dpp v95, v205, v201 row_shr:4 row_mask:0xf bank_mask:0xa
	v_add_f32_dpp v94, v206, v202 row_shr:4 row_mask:0xf bank_mask:0xa
	v_add_f32_dpp v96, v207, v203 row_shr:4 row_mask:0xf bank_mask:0xa
	v_max_f32_e64 v28, |v29|, |v95|
	v_max_f32_e64 v98, |v94|, |v96|
	v_max3_f32 v97, v97, v28, v98
	v_cvt_pk_bf16_f32 v28, v29, v95
	v_cvt_pk_bf16_f32 v29, v94, v96
	v_lshlrev_b32_e32 v94, 16, v26
	v_and_b32_e32 v26, 0xffff0000, v26
	v_lshlrev_b32_e32 v95, 16, v27
	v_and_b32_e32 v27, 0xffff0000, v27
	v_add_f32_e32 v96, v94, v26
	v_sub_f32_e32 v26, v94, v26
	v_add_f32_e32 v94, v95, v27
	v_sub_f32_e32 v27, v95, v27
	v_add_f32_e32 v95, v96, v94
	v_sub_f32_e32 v94, v96, v94
	v_add_f32_e32 v98, v26, v27
	v_sub_f32_e32 v26, v26, v27
	v_xor_b32_e32 v27, v82, v95
	v_xor_b32_e32 v96, v82, v94
	s_nop 0
	v_add_f32_dpp v27, v95, v27 quad_perm:[1,0,3,2] row_mask:0xf bank_mask:0xf bound_ctrl:1
	v_xor_b32_e32 v95, v82, v98
	v_add_f32_dpp v94, v94, v96 quad_perm:[1,0,3,2] row_mask:0xf bank_mask:0xf bound_ctrl:1
	v_xor_b32_e32 v96, v82, v26
	v_add_f32_dpp v95, v98, v95 quad_perm:[1,0,3,2] row_mask:0xf bank_mask:0xf bound_ctrl:1
	s_nop 0
	v_add_f32_dpp v26, v26, v96 quad_perm:[1,0,3,2] row_mask:0xf bank_mask:0xf bound_ctrl:1
	v_xor_b32_e32 v200, v83, v27
	v_xor_b32_e32 v201, v83, v95
	v_xor_b32_e32 v202, v83, v94
	v_xor_b32_e32 v203, v83, v26
	v_add_f32_dpp v204, v27, v200 quad_perm:[2,3,0,1] row_mask:0xf bank_mask:0xf bound_ctrl:1
	v_add_f32_dpp v205, v95, v201 quad_perm:[2,3,0,1] row_mask:0xf bank_mask:0xf bound_ctrl:1
	v_add_f32_dpp v206, v94, v202 quad_perm:[2,3,0,1] row_mask:0xf bank_mask:0xf bound_ctrl:1
	v_add_f32_dpp v207, v26, v203 quad_perm:[2,3,0,1] row_mask:0xf bank_mask:0xf bound_ctrl:1
	v_xor_b32_e32 v200, v84, v204
	v_xor_b32_e32 v201, v84, v205
	v_xor_b32_e32 v202, v84, v206
	v_xor_b32_e32 v203, v84, v207
	v_add_f32_dpp v27, v204, v200 row_shl:4 row_mask:0xf bank_mask:0x5
	v_add_f32_dpp v95, v205, v201 row_shl:4 row_mask:0xf bank_mask:0x5
	v_add_f32_dpp v94, v206, v202 row_shl:4 row_mask:0xf bank_mask:0x5
	v_add_f32_dpp v96, v207, v203 row_shl:4 row_mask:0xf bank_mask:0x5
	v_add_f32_dpp v27, v204, v200 row_shr:4 row_mask:0xf bank_mask:0xa
	v_add_f32_dpp v95, v205, v201 row_shr:4 row_mask:0xf bank_mask:0xa
	v_add_f32_dpp v94, v206, v202 row_shr:4 row_mask:0xf bank_mask:0xa
	v_add_f32_dpp v96, v207, v203 row_shr:4 row_mask:0xf bank_mask:0xa
	v_max_f32_e64 v26, |v27|, |v95|
	v_max_f32_e64 v98, |v94|, |v96|
	v_max3_f32 v97, v97, v26, v98
	v_cvt_pk_bf16_f32 v26, v27, v95
	v_cvt_pk_bf16_f32 v27, v94, v96
	v_lshlrev_b32_e32 v94, 16, v24
	v_and_b32_e32 v24, 0xffff0000, v24
	v_lshlrev_b32_e32 v95, 16, v25
	v_and_b32_e32 v25, 0xffff0000, v25
	v_add_f32_e32 v96, v94, v24
	v_sub_f32_e32 v24, v94, v24
	v_add_f32_e32 v94, v95, v25
	v_sub_f32_e32 v25, v95, v25
	v_add_f32_e32 v95, v96, v94
	v_sub_f32_e32 v94, v96, v94
	v_add_f32_e32 v98, v24, v25
	v_sub_f32_e32 v24, v24, v25
	v_xor_b32_e32 v25, v82, v95
	v_xor_b32_e32 v96, v82, v94
	s_nop 0
	v_add_f32_dpp v25, v95, v25 quad_perm:[1,0,3,2] row_mask:0xf bank_mask:0xf bound_ctrl:1
	v_xor_b32_e32 v95, v82, v98
	v_add_f32_dpp v94, v94, v96 quad_perm:[1,0,3,2] row_mask:0xf bank_mask:0xf bound_ctrl:1
	v_xor_b32_e32 v96, v82, v24
	v_add_f32_dpp v95, v98, v95 quad_perm:[1,0,3,2] row_mask:0xf bank_mask:0xf bound_ctrl:1
	s_nop 0
	v_add_f32_dpp v24, v24, v96 quad_perm:[1,0,3,2] row_mask:0xf bank_mask:0xf bound_ctrl:1
	v_xor_b32_e32 v200, v83, v25
	v_xor_b32_e32 v201, v83, v95
	v_xor_b32_e32 v202, v83, v94
	v_xor_b32_e32 v203, v83, v24
	v_add_f32_dpp v204, v25, v200 quad_perm:[2,3,0,1] row_mask:0xf bank_mask:0xf bound_ctrl:1
	v_add_f32_dpp v205, v95, v201 quad_perm:[2,3,0,1] row_mask:0xf bank_mask:0xf bound_ctrl:1
	v_add_f32_dpp v206, v94, v202 quad_perm:[2,3,0,1] row_mask:0xf bank_mask:0xf bound_ctrl:1
	v_add_f32_dpp v207, v24, v203 quad_perm:[2,3,0,1] row_mask:0xf bank_mask:0xf bound_ctrl:1
	v_xor_b32_e32 v200, v84, v204
	v_xor_b32_e32 v201, v84, v205
	v_xor_b32_e32 v202, v84, v206
	v_xor_b32_e32 v203, v84, v207
	v_add_f32_dpp v24, v204, v200 row_shl:4 row_mask:0xf bank_mask:0x5
	v_add_f32_dpp v25, v205, v201 row_shl:4 row_mask:0xf bank_mask:0x5
	v_add_f32_dpp v94, v206, v202 row_shl:4 row_mask:0xf bank_mask:0x5
	v_add_f32_dpp v95, v207, v203 row_shl:4 row_mask:0xf bank_mask:0x5
	v_add_f32_dpp v24, v204, v200 row_shr:4 row_mask:0xf bank_mask:0xa
	v_add_f32_dpp v25, v205, v201 row_shr:4 row_mask:0xf bank_mask:0xa
	v_add_f32_dpp v94, v206, v202 row_shr:4 row_mask:0xf bank_mask:0xa
	v_add_f32_dpp v95, v207, v203 row_shr:4 row_mask:0xf bank_mask:0xa
	v_max_f32_e64 v96, |v24|, |v25|
	v_max_f32_e64 v98, |v94|, |v95|
	v_max3_f32 v98, v97, v96, v98
	v_lshlrev_b32_e32 v96, 16, v22
	v_and_b32_e32 v22, 0xffff0000, v22
	v_lshlrev_b32_e32 v97, 16, v23
	v_and_b32_e32 v23, 0xffff0000, v23
	v_add_f32_e32 v99, v96, v22
	v_sub_f32_e32 v22, v96, v22
	v_add_f32_e32 v96, v97, v23
	v_sub_f32_e32 v23, v97, v23
	v_add_f32_e32 v97, v99, v96
	v_sub_f32_e32 v96, v99, v96
	v_add_f32_e32 v100, v22, v23
	v_sub_f32_e32 v22, v22, v23
	v_xor_b32_e32 v23, v82, v97
	v_xor_b32_e32 v99, v82, v96
	v_cvt_pk_bf16_f32 v24, v24, v25
	v_cvt_pk_bf16_f32 v25, v94, v95
	s_nop 0
	v_add_f32_dpp v23, v97, v23 quad_perm:[1,0,3,2] row_mask:0xf bank_mask:0xf bound_ctrl:1
	v_xor_b32_e32 v97, v82, v100
	v_add_f32_dpp v96, v96, v99 quad_perm:[1,0,3,2] row_mask:0xf bank_mask:0xf bound_ctrl:1
	v_xor_b32_e32 v99, v82, v22
	v_add_f32_dpp v97, v100, v97 quad_perm:[1,0,3,2] row_mask:0xf bank_mask:0xf bound_ctrl:1
	s_nop 0
	v_add_f32_dpp v22, v22, v99 quad_perm:[1,0,3,2] row_mask:0xf bank_mask:0xf bound_ctrl:1
	v_xor_b32_e32 v200, v83, v23
	v_xor_b32_e32 v201, v83, v97
	v_xor_b32_e32 v202, v83, v96
	v_xor_b32_e32 v203, v83, v22
	v_add_f32_dpp v204, v23, v200 quad_perm:[2,3,0,1] row_mask:0xf bank_mask:0xf bound_ctrl:1
	v_add_f32_dpp v205, v97, v201 quad_perm:[2,3,0,1] row_mask:0xf bank_mask:0xf bound_ctrl:1
	v_add_f32_dpp v206, v96, v202 quad_perm:[2,3,0,1] row_mask:0xf bank_mask:0xf bound_ctrl:1
	v_add_f32_dpp v207, v22, v203 quad_perm:[2,3,0,1] row_mask:0xf bank_mask:0xf bound_ctrl:1
	v_xor_b32_e32 v200, v84, v204
	v_xor_b32_e32 v201, v84, v205
	v_xor_b32_e32 v202, v84, v206
	v_xor_b32_e32 v203, v84, v207
	v_add_f32_dpp v22, v204, v200 row_shl:4 row_mask:0xf bank_mask:0x5
	v_add_f32_dpp v23, v205, v201 row_shl:4 row_mask:0xf bank_mask:0x5
	v_add_f32_dpp v96, v206, v202 row_shl:4 row_mask:0xf bank_mask:0x5
	v_add_f32_dpp v97, v207, v203 row_shl:4 row_mask:0xf bank_mask:0x5
	v_add_f32_dpp v22, v204, v200 row_shr:4 row_mask:0xf bank_mask:0xa
	v_add_f32_dpp v23, v205, v201 row_shr:4 row_mask:0xf bank_mask:0xa
	v_add_f32_dpp v96, v206, v202 row_shr:4 row_mask:0xf bank_mask:0xa
	v_add_f32_dpp v97, v207, v203 row_shr:4 row_mask:0xf bank_mask:0xa
	v_max_f32_e64 v99, |v22|, |v23|
	v_max_f32_e64 v100, |v96|, |v97|
	v_max3_f32 v98, v98, v99, v100
	v_lshlrev_b32_e32 v99, 16, v20
	v_and_b32_e32 v20, 0xffff0000, v20
	v_lshlrev_b32_e32 v100, 16, v21
	v_and_b32_e32 v21, 0xffff0000, v21
	v_add_f32_e32 v101, v99, v20
	v_sub_f32_e32 v20, v99, v20
	v_add_f32_e32 v99, v100, v21
	v_sub_f32_e32 v21, v100, v21
	v_add_f32_e32 v100, v101, v99
	v_sub_f32_e32 v99, v101, v99
	v_add_f32_e32 v102, v20, v21
	v_sub_f32_e32 v20, v20, v21
	v_xor_b32_e32 v21, v82, v100
	v_xor_b32_e32 v101, v82, v99
	v_cvt_pk_bf16_f32 v22, v22, v23
	v_cvt_pk_bf16_f32 v23, v96, v97
	s_nop 0
	v_add_f32_dpp v21, v100, v21 quad_perm:[1,0,3,2] row_mask:0xf bank_mask:0xf bound_ctrl:1
	v_xor_b32_e32 v100, v82, v102
	v_add_f32_dpp v99, v99, v101 quad_perm:[1,0,3,2] row_mask:0xf bank_mask:0xf bound_ctrl:1
	v_xor_b32_e32 v101, v82, v20
	v_add_f32_dpp v100, v102, v100 quad_perm:[1,0,3,2] row_mask:0xf bank_mask:0xf bound_ctrl:1
	s_nop 0
	v_add_f32_dpp v20, v20, v101 quad_perm:[1,0,3,2] row_mask:0xf bank_mask:0xf bound_ctrl:1
	v_xor_b32_e32 v200, v83, v21
	v_xor_b32_e32 v201, v83, v100
	v_xor_b32_e32 v202, v83, v99
	v_xor_b32_e32 v203, v83, v20
	v_add_f32_dpp v204, v21, v200 quad_perm:[2,3,0,1] row_mask:0xf bank_mask:0xf bound_ctrl:1
	v_add_f32_dpp v205, v100, v201 quad_perm:[2,3,0,1] row_mask:0xf bank_mask:0xf bound_ctrl:1
	v_add_f32_dpp v206, v99, v202 quad_perm:[2,3,0,1] row_mask:0xf bank_mask:0xf bound_ctrl:1
	v_add_f32_dpp v207, v20, v203 quad_perm:[2,3,0,1] row_mask:0xf bank_mask:0xf bound_ctrl:1
	v_xor_b32_e32 v200, v84, v204
	v_xor_b32_e32 v201, v84, v205
	v_xor_b32_e32 v202, v84, v206
	v_xor_b32_e32 v203, v84, v207
	v_add_f32_dpp v21, v204, v200 row_shl:4 row_mask:0xf bank_mask:0x5
	v_add_f32_dpp v100, v205, v201 row_shl:4 row_mask:0xf bank_mask:0x5
	v_add_f32_dpp v99, v206, v202 row_shl:4 row_mask:0xf bank_mask:0x5
	v_add_f32_dpp v20, v207, v203 row_shl:4 row_mask:0xf bank_mask:0x5
	v_add_f32_dpp v21, v204, v200 row_shr:4 row_mask:0xf bank_mask:0xa
	v_add_f32_dpp v100, v205, v201 row_shr:4 row_mask:0xf bank_mask:0xa
	v_add_f32_dpp v99, v206, v202 row_shr:4 row_mask:0xf bank_mask:0xa
	v_add_f32_dpp v20, v207, v203 row_shr:4 row_mask:0xf bank_mask:0xa
	v_cvt_pk_bf16_f32 v96, v21, v100
	v_max_f32_e64 v101, |v21|, |v100|
	v_max_f32_e64 v102, |v99|, |v20|
	v_max3_f32 v98, v98, v101, v102
	v_lshlrev_b32_e32 v101, 16, v18
	v_and_b32_e32 v18, 0xffff0000, v18
	v_lshlrev_b32_e32 v102, 16, v19
	v_and_b32_e32 v19, 0xffff0000, v19
	v_add_f32_e32 v103, v101, v18
	v_sub_f32_e32 v18, v101, v18
	v_add_f32_e32 v101, v102, v19
	v_sub_f32_e32 v19, v102, v19
	v_add_f32_e32 v102, v103, v101
	v_sub_f32_e32 v101, v103, v101
	v_add_f32_e32 v104, v18, v19
	v_sub_f32_e32 v18, v18, v19
	v_xor_b32_e32 v19, v82, v102
	v_xor_b32_e32 v103, v82, v101
	v_cvt_pk_bf16_f32 v97, v99, v20
	s_nop 0
	v_add_f32_dpp v19, v102, v19 quad_perm:[1,0,3,2] row_mask:0xf bank_mask:0xf bound_ctrl:1
	v_xor_b32_e32 v102, v82, v104
	v_add_f32_dpp v101, v101, v103 quad_perm:[1,0,3,2] row_mask:0xf bank_mask:0xf bound_ctrl:1
	v_xor_b32_e32 v103, v82, v18
	v_add_f32_dpp v102, v104, v102 quad_perm:[1,0,3,2] row_mask:0xf bank_mask:0xf bound_ctrl:1
	s_nop 0
	v_add_f32_dpp v18, v18, v103 quad_perm:[1,0,3,2] row_mask:0xf bank_mask:0xf bound_ctrl:1
	v_xor_b32_e32 v200, v83, v19
	v_xor_b32_e32 v201, v83, v102
	v_xor_b32_e32 v202, v83, v101
	v_xor_b32_e32 v203, v83, v18
	v_add_f32_dpp v204, v19, v200 quad_perm:[2,3,0,1] row_mask:0xf bank_mask:0xf bound_ctrl:1
	v_add_f32_dpp v205, v102, v201 quad_perm:[2,3,0,1] row_mask:0xf bank_mask:0xf bound_ctrl:1
	v_add_f32_dpp v206, v101, v202 quad_perm:[2,3,0,1] row_mask:0xf bank_mask:0xf bound_ctrl:1
	v_add_f32_dpp v207, v18, v203 quad_perm:[2,3,0,1] row_mask:0xf bank_mask:0xf bound_ctrl:1
	v_xor_b32_e32 v200, v84, v204
	v_xor_b32_e32 v201, v84, v205
	v_xor_b32_e32 v202, v84, v206
	v_xor_b32_e32 v203, v84, v207
	v_add_f32_dpp v19, v204, v200 row_shl:4 row_mask:0xf bank_mask:0x5
	v_add_f32_dpp v102, v205, v201 row_shl:4 row_mask:0xf bank_mask:0x5
	v_add_f32_dpp v101, v206, v202 row_shl:4 row_mask:0xf bank_mask:0x5
	v_add_f32_dpp v18, v207, v203 row_shl:4 row_mask:0xf bank_mask:0x5
	v_add_f32_dpp v19, v204, v200 row_shr:4 row_mask:0xf bank_mask:0xa
	v_add_f32_dpp v102, v205, v201 row_shr:4 row_mask:0xf bank_mask:0xa
	v_add_f32_dpp v101, v206, v202 row_shr:4 row_mask:0xf bank_mask:0xa
	v_add_f32_dpp v18, v207, v203 row_shr:4 row_mask:0xf bank_mask:0xa
	v_max_f32_e64 v103, |v19|, |v102|
	v_max_f32_e64 v104, |v101|, |v18|
	v_max3_f32 v98, v98, v103, v104
	v_lshlrev_b32_e32 v103, 16, v16
	v_and_b32_e32 v16, 0xffff0000, v16
	v_lshlrev_b32_e32 v104, 16, v17
	v_and_b32_e32 v17, 0xffff0000, v17
	v_add_f32_e32 v105, v103, v16
	v_sub_f32_e32 v16, v103, v16
	v_add_f32_e32 v103, v104, v17
	v_sub_f32_e32 v17, v104, v17
	v_add_f32_e32 v104, v105, v103
	v_sub_f32_e32 v103, v105, v103
	v_add_f32_e32 v106, v16, v17
	v_sub_f32_e32 v16, v16, v17
	v_xor_b32_e32 v17, v82, v104
	v_xor_b32_e32 v105, v82, v103
	v_cvt_pk_bf16_f32 v19, v19, v102
	s_nop 0
	v_add_f32_dpp v17, v104, v17 quad_perm:[1,0,3,2] row_mask:0xf bank_mask:0xf bound_ctrl:1
	v_xor_b32_e32 v104, v82, v106
	v_add_f32_dpp v103, v103, v105 quad_perm:[1,0,3,2] row_mask:0xf bank_mask:0xf bound_ctrl:1
	v_xor_b32_e32 v105, v82, v16
	v_add_f32_dpp v104, v106, v104 quad_perm:[1,0,3,2] row_mask:0xf bank_mask:0xf bound_ctrl:1
	s_nop 0
	v_add_f32_dpp v16, v16, v105 quad_perm:[1,0,3,2] row_mask:0xf bank_mask:0xf bound_ctrl:1
	v_xor_b32_e32 v200, v83, v17
	v_xor_b32_e32 v201, v83, v104
	v_xor_b32_e32 v202, v83, v103
	v_xor_b32_e32 v203, v83, v16
	v_add_f32_dpp v204, v17, v200 quad_perm:[2,3,0,1] row_mask:0xf bank_mask:0xf bound_ctrl:1
	v_add_f32_dpp v205, v104, v201 quad_perm:[2,3,0,1] row_mask:0xf bank_mask:0xf bound_ctrl:1
	v_add_f32_dpp v206, v103, v202 quad_perm:[2,3,0,1] row_mask:0xf bank_mask:0xf bound_ctrl:1
	v_add_f32_dpp v207, v16, v203 quad_perm:[2,3,0,1] row_mask:0xf bank_mask:0xf bound_ctrl:1
	v_xor_b32_e32 v200, v84, v204
	v_xor_b32_e32 v201, v84, v205
	v_xor_b32_e32 v202, v84, v206
	v_xor_b32_e32 v203, v84, v207
	v_add_f32_dpp v17, v204, v200 row_shl:4 row_mask:0xf bank_mask:0x5
	v_add_f32_dpp v104, v205, v201 row_shl:4 row_mask:0xf bank_mask:0x5
	v_add_f32_dpp v103, v206, v202 row_shl:4 row_mask:0xf bank_mask:0x5
	v_add_f32_dpp v16, v207, v203 row_shl:4 row_mask:0xf bank_mask:0x5
	v_add_f32_dpp v17, v204, v200 row_shr:4 row_mask:0xf bank_mask:0xa
	v_add_f32_dpp v104, v205, v201 row_shr:4 row_mask:0xf bank_mask:0xa
	v_add_f32_dpp v103, v206, v202 row_shr:4 row_mask:0xf bank_mask:0xa
	v_add_f32_dpp v16, v207, v203 row_shr:4 row_mask:0xf bank_mask:0xa
	v_max_f32_e64 v105, |v17|, |v104|
	v_max_f32_e64 v106, |v103|, |v16|
	v_max3_f32 v98, v98, v105, v106
	v_lshlrev_b32_e32 v105, 16, v14
	v_and_b32_e32 v14, 0xffff0000, v14
	v_lshlrev_b32_e32 v106, 16, v15
	v_and_b32_e32 v15, 0xffff0000, v15
	v_add_f32_e32 v107, v105, v14
	v_sub_f32_e32 v14, v105, v14
	v_add_f32_e32 v105, v106, v15
	v_sub_f32_e32 v15, v106, v15
	v_add_f32_e32 v106, v107, v105
	v_sub_f32_e32 v105, v107, v105
	v_add_f32_e32 v108, v14, v15
	v_sub_f32_e32 v14, v14, v15
	v_xor_b32_e32 v15, v82, v106
	v_xor_b32_e32 v107, v82, v105
	s_nop 0
	v_add_f32_dpp v15, v106, v15 quad_perm:[1,0,3,2] row_mask:0xf bank_mask:0xf bound_ctrl:1
	v_xor_b32_e32 v106, v82, v108
	v_add_f32_dpp v105, v105, v107 quad_perm:[1,0,3,2] row_mask:0xf bank_mask:0xf bound_ctrl:1
	v_xor_b32_e32 v107, v82, v14
	v_add_f32_dpp v106, v108, v106 quad_perm:[1,0,3,2] row_mask:0xf bank_mask:0xf bound_ctrl:1
	s_nop 0
	v_add_f32_dpp v14, v14, v107 quad_perm:[1,0,3,2] row_mask:0xf bank_mask:0xf bound_ctrl:1
	v_xor_b32_e32 v200, v83, v15
	v_xor_b32_e32 v201, v83, v106
	v_xor_b32_e32 v202, v83, v105
	v_xor_b32_e32 v203, v83, v14
	v_add_f32_dpp v204, v15, v200 quad_perm:[2,3,0,1] row_mask:0xf bank_mask:0xf bound_ctrl:1
	v_add_f32_dpp v205, v106, v201 quad_perm:[2,3,0,1] row_mask:0xf bank_mask:0xf bound_ctrl:1
	v_add_f32_dpp v206, v105, v202 quad_perm:[2,3,0,1] row_mask:0xf bank_mask:0xf bound_ctrl:1
	v_add_f32_dpp v207, v14, v203 quad_perm:[2,3,0,1] row_mask:0xf bank_mask:0xf bound_ctrl:1
	v_xor_b32_e32 v200, v84, v204
	v_xor_b32_e32 v201, v84, v205
	v_xor_b32_e32 v202, v84, v206
	v_xor_b32_e32 v203, v84, v207
	v_add_f32_dpp v15, v204, v200 row_shl:4 row_mask:0xf bank_mask:0x5
	v_add_f32_dpp v106, v205, v201 row_shl:4 row_mask:0xf bank_mask:0x5
	v_add_f32_dpp v105, v206, v202 row_shl:4 row_mask:0xf bank_mask:0x5
	v_add_f32_dpp v14, v207, v203 row_shl:4 row_mask:0xf bank_mask:0x5
	v_add_f32_dpp v15, v204, v200 row_shr:4 row_mask:0xf bank_mask:0xa
	v_add_f32_dpp v106, v205, v201 row_shr:4 row_mask:0xf bank_mask:0xa
	v_add_f32_dpp v105, v206, v202 row_shr:4 row_mask:0xf bank_mask:0xa
	v_add_f32_dpp v14, v207, v203 row_shr:4 row_mask:0xf bank_mask:0xa
	v_max_f32_e64 v107, |v15|, |v106|
	v_max_f32_e64 v108, |v105|, |v14|
	v_max3_f32 v98, v98, v107, v108
	v_lshlrev_b32_e32 v107, 16, v12
	v_and_b32_e32 v12, 0xffff0000, v12
	v_lshlrev_b32_e32 v108, 16, v13
	v_and_b32_e32 v13, 0xffff0000, v13
	v_add_f32_e32 v109, v107, v12
	v_sub_f32_e32 v12, v107, v12
	v_add_f32_e32 v107, v108, v13
	v_sub_f32_e32 v13, v108, v13
	v_add_f32_e32 v108, v109, v107
	v_sub_f32_e32 v107, v109, v107
	v_add_f32_e32 v110, v12, v13
	v_sub_f32_e32 v12, v12, v13
	v_xor_b32_e32 v13, v82, v108
	v_xor_b32_e32 v109, v82, v107
	s_nop 0
	v_add_f32_dpp v13, v108, v13 quad_perm:[1,0,3,2] row_mask:0xf bank_mask:0xf bound_ctrl:1
	v_xor_b32_e32 v108, v82, v110
	v_add_f32_dpp v107, v107, v109 quad_perm:[1,0,3,2] row_mask:0xf bank_mask:0xf bound_ctrl:1
	v_xor_b32_e32 v109, v82, v12
	v_add_f32_dpp v108, v110, v108 quad_perm:[1,0,3,2] row_mask:0xf bank_mask:0xf bound_ctrl:1
	s_nop 0
	v_add_f32_dpp v12, v12, v109 quad_perm:[1,0,3,2] row_mask:0xf bank_mask:0xf bound_ctrl:1
	v_xor_b32_e32 v200, v83, v13
	v_xor_b32_e32 v201, v83, v108
	v_xor_b32_e32 v202, v83, v107
	v_xor_b32_e32 v203, v83, v12
	v_add_f32_dpp v204, v13, v200 quad_perm:[2,3,0,1] row_mask:0xf bank_mask:0xf bound_ctrl:1
	v_add_f32_dpp v205, v108, v201 quad_perm:[2,3,0,1] row_mask:0xf bank_mask:0xf bound_ctrl:1
	v_add_f32_dpp v206, v107, v202 quad_perm:[2,3,0,1] row_mask:0xf bank_mask:0xf bound_ctrl:1
	v_add_f32_dpp v207, v12, v203 quad_perm:[2,3,0,1] row_mask:0xf bank_mask:0xf bound_ctrl:1
	v_xor_b32_e32 v200, v84, v204
	v_xor_b32_e32 v201, v84, v205
	v_xor_b32_e32 v202, v84, v206
	v_xor_b32_e32 v203, v84, v207
	v_add_f32_dpp v13, v204, v200 row_shl:4 row_mask:0xf bank_mask:0x5
	v_add_f32_dpp v108, v205, v201 row_shl:4 row_mask:0xf bank_mask:0x5
	v_add_f32_dpp v107, v206, v202 row_shl:4 row_mask:0xf bank_mask:0x5
	v_add_f32_dpp v12, v207, v203 row_shl:4 row_mask:0xf bank_mask:0x5
	v_add_f32_dpp v13, v204, v200 row_shr:4 row_mask:0xf bank_mask:0xa
	v_add_f32_dpp v108, v205, v201 row_shr:4 row_mask:0xf bank_mask:0xa
	v_add_f32_dpp v107, v206, v202 row_shr:4 row_mask:0xf bank_mask:0xa
	v_add_f32_dpp v12, v207, v203 row_shr:4 row_mask:0xf bank_mask:0xa
	v_max_f32_e64 v109, |v13|, |v108|
	v_max_f32_e64 v110, |v107|, |v12|
	v_max3_f32 v98, v98, v109, v110
	v_lshlrev_b32_e32 v109, 16, v10
	v_and_b32_e32 v10, 0xffff0000, v10
	v_lshlrev_b32_e32 v110, 16, v11
	v_and_b32_e32 v11, 0xffff0000, v11
	v_add_f32_e32 v111, v109, v10
	v_sub_f32_e32 v10, v109, v10
	v_add_f32_e32 v109, v110, v11
	v_sub_f32_e32 v11, v110, v11
	v_add_f32_e32 v110, v111, v109
	v_sub_f32_e32 v109, v111, v109
	v_add_f32_e32 v112, v10, v11
	v_sub_f32_e32 v10, v10, v11
	v_xor_b32_e32 v11, v82, v110
	v_xor_b32_e32 v111, v82, v109
	s_nop 0
	v_add_f32_dpp v11, v110, v11 quad_perm:[1,0,3,2] row_mask:0xf bank_mask:0xf bound_ctrl:1
	v_xor_b32_e32 v110, v82, v112
	v_add_f32_dpp v109, v109, v111 quad_perm:[1,0,3,2] row_mask:0xf bank_mask:0xf bound_ctrl:1
	v_xor_b32_e32 v111, v82, v10
	v_add_f32_dpp v110, v112, v110 quad_perm:[1,0,3,2] row_mask:0xf bank_mask:0xf bound_ctrl:1
	s_nop 0
	v_add_f32_dpp v10, v10, v111 quad_perm:[1,0,3,2] row_mask:0xf bank_mask:0xf bound_ctrl:1
	v_xor_b32_e32 v200, v83, v11
	v_xor_b32_e32 v201, v83, v110
	v_xor_b32_e32 v202, v83, v109
	v_xor_b32_e32 v203, v83, v10
	v_add_f32_dpp v204, v11, v200 quad_perm:[2,3,0,1] row_mask:0xf bank_mask:0xf bound_ctrl:1
	v_add_f32_dpp v205, v110, v201 quad_perm:[2,3,0,1] row_mask:0xf bank_mask:0xf bound_ctrl:1
	v_add_f32_dpp v206, v109, v202 quad_perm:[2,3,0,1] row_mask:0xf bank_mask:0xf bound_ctrl:1
	v_add_f32_dpp v207, v10, v203 quad_perm:[2,3,0,1] row_mask:0xf bank_mask:0xf bound_ctrl:1
	v_xor_b32_e32 v200, v84, v204
	v_xor_b32_e32 v201, v84, v205
	v_xor_b32_e32 v202, v84, v206
	v_xor_b32_e32 v203, v84, v207
	v_add_f32_dpp v11, v204, v200 row_shl:4 row_mask:0xf bank_mask:0x5
	v_add_f32_dpp v110, v205, v201 row_shl:4 row_mask:0xf bank_mask:0x5
	v_add_f32_dpp v109, v206, v202 row_shl:4 row_mask:0xf bank_mask:0x5
	v_add_f32_dpp v10, v207, v203 row_shl:4 row_mask:0xf bank_mask:0x5
	v_add_f32_dpp v11, v204, v200 row_shr:4 row_mask:0xf bank_mask:0xa
	v_add_f32_dpp v110, v205, v201 row_shr:4 row_mask:0xf bank_mask:0xa
	v_add_f32_dpp v109, v206, v202 row_shr:4 row_mask:0xf bank_mask:0xa
	v_add_f32_dpp v10, v207, v203 row_shr:4 row_mask:0xf bank_mask:0xa
	v_max_f32_e64 v111, |v11|, |v110|
	v_max_f32_e64 v112, |v109|, |v10|
	v_max3_f32 v98, v98, v111, v112
	v_lshlrev_b32_e32 v111, 16, v8
	v_and_b32_e32 v8, 0xffff0000, v8
	v_lshlrev_b32_e32 v112, 16, v9
	v_and_b32_e32 v9, 0xffff0000, v9
	v_add_f32_e32 v113, v111, v8
	v_sub_f32_e32 v8, v111, v8
	v_add_f32_e32 v111, v112, v9
	v_sub_f32_e32 v9, v112, v9
	v_add_f32_e32 v112, v113, v111
	v_sub_f32_e32 v111, v113, v111
	v_add_f32_e32 v114, v8, v9
	v_sub_f32_e32 v8, v8, v9
	v_xor_b32_e32 v9, v82, v112
	v_xor_b32_e32 v113, v82, v111
	s_nop 0
	v_add_f32_dpp v9, v112, v9 quad_perm:[1,0,3,2] row_mask:0xf bank_mask:0xf bound_ctrl:1
	v_xor_b32_e32 v112, v82, v114
	v_add_f32_dpp v111, v111, v113 quad_perm:[1,0,3,2] row_mask:0xf bank_mask:0xf bound_ctrl:1
	v_xor_b32_e32 v113, v82, v8
	v_add_f32_dpp v112, v114, v112 quad_perm:[1,0,3,2] row_mask:0xf bank_mask:0xf bound_ctrl:1
	s_nop 0
	v_add_f32_dpp v8, v8, v113 quad_perm:[1,0,3,2] row_mask:0xf bank_mask:0xf bound_ctrl:1
	v_xor_b32_e32 v200, v83, v9
	v_xor_b32_e32 v201, v83, v112
	v_xor_b32_e32 v202, v83, v111
	v_xor_b32_e32 v203, v83, v8
	v_add_f32_dpp v204, v9, v200 quad_perm:[2,3,0,1] row_mask:0xf bank_mask:0xf bound_ctrl:1
	v_add_f32_dpp v205, v112, v201 quad_perm:[2,3,0,1] row_mask:0xf bank_mask:0xf bound_ctrl:1
	v_add_f32_dpp v206, v111, v202 quad_perm:[2,3,0,1] row_mask:0xf bank_mask:0xf bound_ctrl:1
	v_add_f32_dpp v207, v8, v203 quad_perm:[2,3,0,1] row_mask:0xf bank_mask:0xf bound_ctrl:1
	v_xor_b32_e32 v200, v84, v204
	v_xor_b32_e32 v201, v84, v205
	v_xor_b32_e32 v202, v84, v206
	v_xor_b32_e32 v203, v84, v207
	v_add_f32_dpp v9, v204, v200 row_shl:4 row_mask:0xf bank_mask:0x5
	v_add_f32_dpp v112, v205, v201 row_shl:4 row_mask:0xf bank_mask:0x5
	v_add_f32_dpp v111, v206, v202 row_shl:4 row_mask:0xf bank_mask:0x5
	v_add_f32_dpp v8, v207, v203 row_shl:4 row_mask:0xf bank_mask:0x5
	v_add_f32_dpp v9, v204, v200 row_shr:4 row_mask:0xf bank_mask:0xa
	v_add_f32_dpp v112, v205, v201 row_shr:4 row_mask:0xf bank_mask:0xa
	v_add_f32_dpp v111, v206, v202 row_shr:4 row_mask:0xf bank_mask:0xa
	v_add_f32_dpp v8, v207, v203 row_shr:4 row_mask:0xf bank_mask:0xa
	v_max_f32_e64 v113, |v9|, |v112|
	v_max_f32_e64 v114, |v111|, |v8|
	v_max3_f32 v98, v98, v113, v114
	v_lshlrev_b32_e32 v113, 16, v6
	v_and_b32_e32 v6, 0xffff0000, v6
	v_lshlrev_b32_e32 v114, 16, v7
	v_and_b32_e32 v7, 0xffff0000, v7
	v_add_f32_e32 v115, v113, v6
	v_sub_f32_e32 v6, v113, v6
	v_add_f32_e32 v113, v114, v7
	v_sub_f32_e32 v7, v114, v7
	v_add_f32_e32 v114, v115, v113
	v_sub_f32_e32 v113, v115, v113
	v_add_f32_e32 v116, v6, v7
	v_sub_f32_e32 v6, v6, v7
	v_xor_b32_e32 v7, v82, v114
	v_xor_b32_e32 v115, v82, v113
	s_nop 0
	v_add_f32_dpp v7, v114, v7 quad_perm:[1,0,3,2] row_mask:0xf bank_mask:0xf bound_ctrl:1
	v_xor_b32_e32 v114, v82, v116
	v_add_f32_dpp v113, v113, v115 quad_perm:[1,0,3,2] row_mask:0xf bank_mask:0xf bound_ctrl:1
	v_xor_b32_e32 v115, v82, v6
	v_add_f32_dpp v114, v116, v114 quad_perm:[1,0,3,2] row_mask:0xf bank_mask:0xf bound_ctrl:1
	s_nop 0
	v_add_f32_dpp v6, v6, v115 quad_perm:[1,0,3,2] row_mask:0xf bank_mask:0xf bound_ctrl:1
	v_xor_b32_e32 v200, v83, v7
	v_xor_b32_e32 v201, v83, v114
	v_xor_b32_e32 v202, v83, v113
	v_xor_b32_e32 v203, v83, v6
	v_add_f32_dpp v204, v7, v200 quad_perm:[2,3,0,1] row_mask:0xf bank_mask:0xf bound_ctrl:1
	v_add_f32_dpp v205, v114, v201 quad_perm:[2,3,0,1] row_mask:0xf bank_mask:0xf bound_ctrl:1
	v_add_f32_dpp v206, v113, v202 quad_perm:[2,3,0,1] row_mask:0xf bank_mask:0xf bound_ctrl:1
	v_add_f32_dpp v207, v6, v203 quad_perm:[2,3,0,1] row_mask:0xf bank_mask:0xf bound_ctrl:1
	v_xor_b32_e32 v200, v84, v204
	v_xor_b32_e32 v201, v84, v205
	v_xor_b32_e32 v202, v84, v206
	v_xor_b32_e32 v203, v84, v207
	v_add_f32_dpp v7, v204, v200 row_shl:4 row_mask:0xf bank_mask:0x5
	v_add_f32_dpp v114, v205, v201 row_shl:4 row_mask:0xf bank_mask:0x5
	v_add_f32_dpp v113, v206, v202 row_shl:4 row_mask:0xf bank_mask:0x5
	v_add_f32_dpp v6, v207, v203 row_shl:4 row_mask:0xf bank_mask:0x5
	v_add_f32_dpp v7, v204, v200 row_shr:4 row_mask:0xf bank_mask:0xa
	v_add_f32_dpp v114, v205, v201 row_shr:4 row_mask:0xf bank_mask:0xa
	v_add_f32_dpp v113, v206, v202 row_shr:4 row_mask:0xf bank_mask:0xa
	v_add_f32_dpp v6, v207, v203 row_shr:4 row_mask:0xf bank_mask:0xa
	v_max_f32_e64 v115, |v7|, |v114|
	v_max_f32_e64 v116, |v113|, |v6|
	v_max3_f32 v98, v98, v115, v116
	s_waitcnt vmcnt(0)
	v_lshlrev_b32_e32 v115, 16, v4
	v_and_b32_e32 v4, 0xffff0000, v4
	v_lshlrev_b32_e32 v116, 16, v5
	v_and_b32_e32 v5, 0xffff0000, v5
	v_add_f32_e32 v117, v115, v4
	v_sub_f32_e32 v4, v115, v4
	v_add_f32_e32 v115, v116, v5
	v_sub_f32_e32 v5, v116, v5
	v_add_f32_e32 v116, v117, v115
	v_sub_f32_e32 v115, v117, v115
	v_add_f32_e32 v118, v4, v5
	v_sub_f32_e32 v4, v4, v5
	v_xor_b32_e32 v5, v82, v116
	v_xor_b32_e32 v117, v82, v115
	s_nop 0
	v_add_f32_dpp v5, v116, v5 quad_perm:[1,0,3,2] row_mask:0xf bank_mask:0xf bound_ctrl:1
	v_xor_b32_e32 v116, v82, v118
	v_add_f32_dpp v115, v115, v117 quad_perm:[1,0,3,2] row_mask:0xf bank_mask:0xf bound_ctrl:1
	v_xor_b32_e32 v117, v82, v4
	v_add_f32_dpp v116, v118, v116 quad_perm:[1,0,3,2] row_mask:0xf bank_mask:0xf bound_ctrl:1
	s_nop 0
	v_add_f32_dpp v4, v4, v117 quad_perm:[1,0,3,2] row_mask:0xf bank_mask:0xf bound_ctrl:1
	v_xor_b32_e32 v200, v83, v5
	v_xor_b32_e32 v201, v83, v116
	v_xor_b32_e32 v202, v83, v115
	v_xor_b32_e32 v203, v83, v4
	v_add_f32_dpp v204, v5, v200 quad_perm:[2,3,0,1] row_mask:0xf bank_mask:0xf bound_ctrl:1
	v_add_f32_dpp v205, v116, v201 quad_perm:[2,3,0,1] row_mask:0xf bank_mask:0xf bound_ctrl:1
	v_add_f32_dpp v206, v115, v202 quad_perm:[2,3,0,1] row_mask:0xf bank_mask:0xf bound_ctrl:1
	v_add_f32_dpp v207, v4, v203 quad_perm:[2,3,0,1] row_mask:0xf bank_mask:0xf bound_ctrl:1
	v_xor_b32_e32 v200, v84, v204
	v_xor_b32_e32 v201, v84, v205
	v_xor_b32_e32 v202, v84, v206
	v_xor_b32_e32 v203, v84, v207
	v_add_f32_dpp v5, v204, v200 row_shl:4 row_mask:0xf bank_mask:0x5
	v_add_f32_dpp v116, v205, v201 row_shl:4 row_mask:0xf bank_mask:0x5
	v_add_f32_dpp v115, v206, v202 row_shl:4 row_mask:0xf bank_mask:0x5
	v_add_f32_dpp v4, v207, v203 row_shl:4 row_mask:0xf bank_mask:0x5
	v_add_f32_dpp v5, v204, v200 row_shr:4 row_mask:0xf bank_mask:0xa
	v_add_f32_dpp v116, v205, v201 row_shr:4 row_mask:0xf bank_mask:0xa
	v_add_f32_dpp v115, v206, v202 row_shr:4 row_mask:0xf bank_mask:0xa
	v_add_f32_dpp v4, v207, v203 row_shr:4 row_mask:0xf bank_mask:0xa
	v_max_f32_e64 v117, |v5|, |v116|
	v_max_f32_e64 v118, |v115|, |v4|
	v_max3_f32 v98, v98, v117, v118
	ds_swizzle_b32 v117, v98 offset:swizzle(SWAP,1)
	s_waitcnt lgkmcnt(0)
	v_max_f32_e32 v94, v117, v117
	v_max_f32_e32 v94, v98, v94
	ds_swizzle_b32 v95, v94 offset:swizzle(SWAP,2)
	v_cvt_pk_bf16_f32 v98, v101, v18
	s_waitcnt lgkmcnt(0)
	v_max_f32_e32 v18, v95, v95
	v_max_f32_e32 v18, v94, v18
	ds_swizzle_b32 v20, v18 offset:swizzle(SWAP,4)
	v_cvt_pk_bf16_f32 v94, v17, v104
	v_cvt_pk_bf16_f32 v95, v103, v16
	v_cvt_pk_bf16_f32 v99, v15, v106
	v_cvt_pk_bf16_f32 v100, v105, v14
	s_waitcnt lgkmcnt(0)
	v_max_f32_e32 v14, v20, v20
	v_max_f32_e32 v14, v18, v14
	ds_swizzle_b32 v16, v14 offset:swizzle(SWAP,8)
	v_cvt_pk_bf16_f32 v18, v13, v108
	v_cvt_pk_bf16_f32 v101, v107, v12
	v_cvt_pk_bf16_f32 v15, v11, v110
	v_cvt_pk_bf16_f32 v17, v109, v10
	s_waitcnt lgkmcnt(0)
	v_max_f32_e32 v10, v16, v16
	v_max_f32_e32 v10, v14, v10
	ds_swizzle_b32 v12, v10 offset:swizzle(SWAP,16)
	v_cvt_pk_bf16_f32 v13, v9, v112
	v_cvt_pk_bf16_f32 v14, v111, v8
	v_cvt_pk_bf16_f32 v9, v7, v114
	v_cvt_pk_bf16_f32 v11, v113, v6
	s_waitcnt lgkmcnt(0)
	v_max_f32_e32 v6, v12, v12
	v_max_f32_e32 v6, v10, v6
	v_mov_b32_e32 v7, v6
	s_nop 1
	v_permlane32_swap_b32_e32 v6, v7
	v_max_f32_e32 v7, v7, v7
	v_max_f32_e32 v6, v6, v6
	v_max_f32_e32 v6, v6, v7
	v_mul_f32_e32 v8, 0x3f808000, v6
	v_div_scale_f32 v6, s[18:19], v8, v8, s27
	v_rcp_f32_e32 v7, v6
	v_cvt_pk_bf16_f32 v10, v5, v116
	v_cvt_pk_bf16_f32 v12, v115, v4
	v_lshl_add_u64 v[4:5], s[8:9], 0, v[0:1]
	v_fma_f32 v16, -v6, v7, 1.0
	v_fmac_f32_e32 v7, v16, v7
	v_div_scale_f32 v16, vcc, s27, v8, s27
	v_mul_f32_e32 v20, v16, v7
	v_fma_f32 v21, -v6, v20, v16
	v_fmac_f32_e32 v20, v21, v7
	v_fma_f32 v6, -v6, v20, v16
	v_div_fmas_f32 v6, v6, v7, v20
	v_div_fixup_f32 v6, v6, v8, s27
	v_cmp_lt_f32_e32 vcc, 0, v8
	v_lshlrev_b32_e32 v7, 16, v87
	v_lshlrev_b32_e32 v20, 16, v86
	v_cndmask_b32_e32 v16, 0, v6, vcc
	v_and_b32_e32 v6, 0xffff0000, v87
	v_fmaak_f32 v6, v6, v16, 0x4b400000
	v_fmaak_f32 v7, v7, v16, 0x4b400000
	v_perm_b32 v6, v6, v7, s28
	v_and_b32_e32 v7, 0xffff0000, v86
	v_fmaak_f32 v7, v7, v16, 0x4b400000
	v_fmaak_f32 v20, v20, v16, 0x4b400000
	v_perm_b32 v7, v7, v20, s28
	v_add_co_u32_e32 v20, vcc, s30, v4
	v_perm_b32 v86, v6, v7, s29
	s_nop 0
	v_addc_co_u32_e32 v21, vcc, 0, v5, vcc
	v_add_co_u32_e32 v6, vcc, s31, v4
	v_lshlrev_b32_e32 v87, 16, v89
	s_nop 0
	v_addc_co_u32_e32 v7, vcc, 0, v5, vcc
	global_store_dword v[6:7], v86, off offset:-4096 sc1
	v_and_b32_e32 v86, 0xffff0000, v89
	v_fmaak_f32 v86, v86, v16, 0x4b400000
	v_fmaak_f32 v87, v87, v16, 0x4b400000
	v_perm_b32 v86, v86, v87, s28
	v_and_b32_e32 v87, 0xffff0000, v88
	v_lshlrev_b32_e32 v88, 16, v88
	v_fmaak_f32 v87, v87, v16, 0x4b400000
	v_fmaak_f32 v88, v88, v16, 0x4b400000
	v_perm_b32 v87, v87, v88, s28
	v_perm_b32 v86, v86, v87, s29
	global_store_dword v[20:21], v86, off offset:256 sc1
	v_and_b32_e32 v86, 0xffff0000, v91
	v_lshlrev_b32_e32 v87, 16, v91
	v_fmaak_f32 v86, v86, v16, 0x4b400000
	v_fmaak_f32 v87, v87, v16, 0x4b400000
	v_perm_b32 v86, v86, v87, s28
	v_and_b32_e32 v87, 0xffff0000, v90
	v_lshlrev_b32_e32 v88, 16, v90
	v_fmaak_f32 v87, v87, v16, 0x4b400000
	v_fmaak_f32 v88, v88, v16, 0x4b400000
	v_perm_b32 v87, v87, v88, s28
	v_perm_b32 v86, v86, v87, s29
	global_store_dword v[20:21], v86, off offset:512 sc1
	v_and_b32_e32 v86, 0xffff0000, v93
	v_lshlrev_b32_e32 v87, 16, v93
	v_fmaak_f32 v86, v86, v16, 0x4b400000
	v_fmaak_f32 v87, v87, v16, 0x4b400000
	v_perm_b32 v86, v86, v87, s28
	v_and_b32_e32 v87, 0xffff0000, v92
	v_lshlrev_b32_e32 v88, 16, v92
	v_fmaak_f32 v87, v87, v16, 0x4b400000
	v_fmaak_f32 v88, v88, v16, 0x4b400000
	v_perm_b32 v87, v87, v88, s28
	v_perm_b32 v86, v86, v87, s29
	global_store_dword v[20:21], v86, off offset:768 sc1
	v_and_b32_e32 v86, 0xffff0000, v81
	v_lshlrev_b32_e32 v81, 16, v81
	v_fmaak_f32 v86, v86, v16, 0x4b400000
	v_fmaak_f32 v81, v81, v16, 0x4b400000
	v_perm_b32 v81, v86, v81, s28
	v_and_b32_e32 v86, 0xffff0000, v80
	v_lshlrev_b32_e32 v80, 16, v80
	v_fmaak_f32 v86, v86, v16, 0x4b400000
	v_fmaak_f32 v80, v80, v16, 0x4b400000
	v_perm_b32 v80, v86, v80, s28
	v_perm_b32 v80, v81, v80, s29
	global_store_dword v[20:21], v80, off offset:1024 sc1
	v_and_b32_e32 v80, 0xffff0000, v79
	v_lshlrev_b32_e32 v79, 16, v79
	v_fmaak_f32 v80, v80, v16, 0x4b400000
	v_fmaak_f32 v79, v79, v16, 0x4b400000
	v_perm_b32 v79, v80, v79, s28
	v_and_b32_e32 v80, 0xffff0000, v78
	v_lshlrev_b32_e32 v78, 16, v78
	v_fmaak_f32 v80, v80, v16, 0x4b400000
	v_fmaak_f32 v78, v78, v16, 0x4b400000
	v_perm_b32 v78, v80, v78, s28
	v_perm_b32 v78, v79, v78, s29
	global_store_dword v[20:21], v78, off offset:1280 sc1
	v_and_b32_e32 v78, 0xffff0000, v77
	v_lshlrev_b32_e32 v77, 16, v77
	v_fmaak_f32 v78, v78, v16, 0x4b400000
	v_fmaak_f32 v77, v77, v16, 0x4b400000
	v_perm_b32 v77, v78, v77, s28
	v_and_b32_e32 v78, 0xffff0000, v76
	v_lshlrev_b32_e32 v76, 16, v76
	v_fmaak_f32 v78, v78, v16, 0x4b400000
	v_fmaak_f32 v76, v76, v16, 0x4b400000
	v_perm_b32 v76, v78, v76, s28
	v_perm_b32 v76, v77, v76, s29
	global_store_dword v[20:21], v76, off offset:1536 sc1
	v_and_b32_e32 v76, 0xffff0000, v75
	v_lshlrev_b32_e32 v75, 16, v75
	v_fmaak_f32 v76, v76, v16, 0x4b400000
	v_fmaak_f32 v75, v75, v16, 0x4b400000
	v_perm_b32 v75, v76, v75, s28
	v_and_b32_e32 v76, 0xffff0000, v74
	v_lshlrev_b32_e32 v74, 16, v74
	v_fmaak_f32 v76, v76, v16, 0x4b400000
	v_fmaak_f32 v74, v74, v16, 0x4b400000
	v_perm_b32 v74, v76, v74, s28
	v_perm_b32 v74, v75, v74, s29
	global_store_dword v[20:21], v74, off offset:1792 sc1
	v_and_b32_e32 v74, 0xffff0000, v73
	v_lshlrev_b32_e32 v73, 16, v73
	v_fmaak_f32 v74, v74, v16, 0x4b400000
	v_fmaak_f32 v73, v73, v16, 0x4b400000
	v_perm_b32 v73, v74, v73, s28
	v_and_b32_e32 v74, 0xffff0000, v72
	v_lshlrev_b32_e32 v72, 16, v72
	v_fmaak_f32 v74, v74, v16, 0x4b400000
	v_fmaak_f32 v72, v72, v16, 0x4b400000
	v_perm_b32 v72, v74, v72, s28
	v_perm_b32 v72, v73, v72, s29
	global_store_dword v[20:21], v72, off offset:2048 sc1
	v_and_b32_e32 v72, 0xffff0000, v71
	v_lshlrev_b32_e32 v71, 16, v71
	v_fmaak_f32 v72, v72, v16, 0x4b400000
	v_fmaak_f32 v71, v71, v16, 0x4b400000
	v_perm_b32 v71, v72, v71, s28
	v_and_b32_e32 v72, 0xffff0000, v70
	v_lshlrev_b32_e32 v70, 16, v70
	v_fmaak_f32 v72, v72, v16, 0x4b400000
	v_fmaak_f32 v70, v70, v16, 0x4b400000
	v_perm_b32 v70, v72, v70, s28
	v_perm_b32 v70, v71, v70, s29
	global_store_dword v[20:21], v70, off offset:2304 sc1
	v_and_b32_e32 v70, 0xffff0000, v69
	v_lshlrev_b32_e32 v69, 16, v69
	v_fmaak_f32 v70, v70, v16, 0x4b400000
	v_fmaak_f32 v69, v69, v16, 0x4b400000
	v_perm_b32 v69, v70, v69, s28
	v_and_b32_e32 v70, 0xffff0000, v68
	v_lshlrev_b32_e32 v68, 16, v68
	v_fmaak_f32 v70, v70, v16, 0x4b400000
	v_fmaak_f32 v68, v68, v16, 0x4b400000
	v_perm_b32 v68, v70, v68, s28
	v_perm_b32 v68, v69, v68, s29
	global_store_dword v[20:21], v68, off offset:2560 sc1
	v_and_b32_e32 v68, 0xffff0000, v67
	v_lshlrev_b32_e32 v67, 16, v67
	v_fmaak_f32 v68, v68, v16, 0x4b400000
	v_fmaak_f32 v67, v67, v16, 0x4b400000
	v_perm_b32 v67, v68, v67, s28
	v_and_b32_e32 v68, 0xffff0000, v66
	v_lshlrev_b32_e32 v66, 16, v66
	v_fmaak_f32 v68, v68, v16, 0x4b400000
	v_fmaak_f32 v66, v66, v16, 0x4b400000
	v_perm_b32 v66, v68, v66, s28
	v_perm_b32 v66, v67, v66, s29
	global_store_dword v[20:21], v66, off offset:2816 sc1
	v_and_b32_e32 v66, 0xffff0000, v65
	v_lshlrev_b32_e32 v65, 16, v65
	v_fmaak_f32 v66, v66, v16, 0x4b400000
	v_fmaak_f32 v65, v65, v16, 0x4b400000
	v_perm_b32 v65, v66, v65, s28
	v_and_b32_e32 v66, 0xffff0000, v64
	v_lshlrev_b32_e32 v64, 16, v64
	v_fmaak_f32 v66, v66, v16, 0x4b400000
	v_fmaak_f32 v64, v64, v16, 0x4b400000
	v_perm_b32 v64, v66, v64, s28
	v_perm_b32 v64, v65, v64, s29
	global_store_dword v[20:21], v64, off offset:3072 sc1
	v_and_b32_e32 v64, 0xffff0000, v63
	v_lshlrev_b32_e32 v63, 16, v63
	v_fmaak_f32 v64, v64, v16, 0x4b400000
	v_fmaak_f32 v63, v63, v16, 0x4b400000
	v_perm_b32 v63, v64, v63, s28
	v_and_b32_e32 v64, 0xffff0000, v62
	v_lshlrev_b32_e32 v62, 16, v62
	v_fmaak_f32 v64, v64, v16, 0x4b400000
	v_fmaak_f32 v62, v62, v16, 0x4b400000
	v_perm_b32 v62, v64, v62, s28
	v_perm_b32 v62, v63, v62, s29
	global_store_dword v[20:21], v62, off offset:3328 sc1
	v_and_b32_e32 v62, 0xffff0000, v61
	v_lshlrev_b32_e32 v61, 16, v61
	v_fmaak_f32 v62, v62, v16, 0x4b400000
	v_fmaak_f32 v61, v61, v16, 0x4b400000
	v_perm_b32 v61, v62, v61, s28
	v_and_b32_e32 v62, 0xffff0000, v60
	v_lshlrev_b32_e32 v60, 16, v60
	v_fmaak_f32 v62, v62, v16, 0x4b400000
	v_fmaak_f32 v60, v60, v16, 0x4b400000
	v_perm_b32 v60, v62, v60, s28
	v_perm_b32 v60, v61, v60, s29
	global_store_dword v[20:21], v60, off offset:3584 sc1
	v_and_b32_e32 v60, 0xffff0000, v59
	v_lshlrev_b32_e32 v59, 16, v59
	v_fmaak_f32 v60, v60, v16, 0x4b400000
	v_fmaak_f32 v59, v59, v16, 0x4b400000
	v_perm_b32 v59, v60, v59, s28
	v_and_b32_e32 v60, 0xffff0000, v58
	v_lshlrev_b32_e32 v58, 16, v58
	v_fmaak_f32 v60, v60, v16, 0x4b400000
	v_fmaak_f32 v58, v58, v16, 0x4b400000
	v_perm_b32 v58, v60, v58, s28
	v_perm_b32 v58, v59, v58, s29
	global_store_dword v[20:21], v58, off offset:3840 sc1
	v_and_b32_e32 v20, 0xffff0000, v57
	v_lshlrev_b32_e32 v21, 16, v57
	v_fmaak_f32 v20, v20, v16, 0x4b400000
	v_fmaak_f32 v21, v21, v16, 0x4b400000
	v_perm_b32 v20, v20, v21, s28
	v_and_b32_e32 v21, 0xffff0000, v56
	v_lshlrev_b32_e32 v56, 16, v56
	v_fmaak_f32 v21, v21, v16, 0x4b400000
	v_fmaak_f32 v56, v56, v16, 0x4b400000
	v_perm_b32 v21, v21, v56, s28
	v_perm_b32 v20, v20, v21, s29
	global_store_dword v[6:7], v20, off sc1
	v_and_b32_e32 v20, 0xffff0000, v55
	v_lshlrev_b32_e32 v21, 16, v55
	v_fmaak_f32 v20, v20, v16, 0x4b400000
	v_fmaak_f32 v21, v21, v16, 0x4b400000
	v_perm_b32 v20, v20, v21, s28
	v_and_b32_e32 v21, 0xffff0000, v54
	v_lshlrev_b32_e32 v54, 16, v54
	v_fmaak_f32 v21, v21, v16, 0x4b400000
	v_fmaak_f32 v54, v54, v16, 0x4b400000
	v_perm_b32 v21, v21, v54, s28
	v_perm_b32 v20, v20, v21, s29
	global_store_dword v[6:7], v20, off offset:256 sc1
	v_and_b32_e32 v20, 0xffff0000, v53
	v_lshlrev_b32_e32 v21, 16, v53
	v_fmaak_f32 v20, v20, v16, 0x4b400000
	v_fmaak_f32 v21, v21, v16, 0x4b400000
	v_perm_b32 v20, v20, v21, s28
	v_and_b32_e32 v21, 0xffff0000, v52
	v_lshlrev_b32_e32 v52, 16, v52
	v_fmaak_f32 v21, v21, v16, 0x4b400000
	v_fmaak_f32 v52, v52, v16, 0x4b400000
	v_perm_b32 v21, v21, v52, s28
	v_perm_b32 v20, v20, v21, s29
	global_store_dword v[6:7], v20, off offset:512 sc1
	v_and_b32_e32 v20, 0xffff0000, v51
	v_lshlrev_b32_e32 v21, 16, v51
	v_fmaak_f32 v20, v20, v16, 0x4b400000
	v_fmaak_f32 v21, v21, v16, 0x4b400000
	v_perm_b32 v20, v20, v21, s28
	v_and_b32_e32 v21, 0xffff0000, v50
	v_lshlrev_b32_e32 v50, 16, v50
	v_fmaak_f32 v21, v21, v16, 0x4b400000
	v_fmaak_f32 v50, v50, v16, 0x4b400000
	v_perm_b32 v21, v21, v50, s28
	v_perm_b32 v20, v20, v21, s29
	global_store_dword v[6:7], v20, off offset:768 sc1
	v_and_b32_e32 v20, 0xffff0000, v49
	v_lshlrev_b32_e32 v21, 16, v49
	v_fmaak_f32 v20, v20, v16, 0x4b400000
	v_fmaak_f32 v21, v21, v16, 0x4b400000
	v_perm_b32 v20, v20, v21, s28
	v_and_b32_e32 v21, 0xffff0000, v48
	v_lshlrev_b32_e32 v48, 16, v48
	v_fmaak_f32 v21, v21, v16, 0x4b400000
	v_fmaak_f32 v48, v48, v16, 0x4b400000
	v_perm_b32 v21, v21, v48, s28
	v_perm_b32 v20, v20, v21, s29
	global_store_dword v[6:7], v20, off offset:1024 sc1
	v_and_b32_e32 v20, 0xffff0000, v47
	v_lshlrev_b32_e32 v21, 16, v47
	v_fmaak_f32 v20, v20, v16, 0x4b400000
	v_fmaak_f32 v21, v21, v16, 0x4b400000
	v_perm_b32 v20, v20, v21, s28
	v_and_b32_e32 v21, 0xffff0000, v46
	v_lshlrev_b32_e32 v46, 16, v46
	v_fmaak_f32 v21, v21, v16, 0x4b400000
	v_fmaak_f32 v46, v46, v16, 0x4b400000
	v_perm_b32 v21, v21, v46, s28
	v_perm_b32 v20, v20, v21, s29
	global_store_dword v[6:7], v20, off offset:1280 sc1
	v_and_b32_e32 v20, 0xffff0000, v45
	v_lshlrev_b32_e32 v21, 16, v45
	v_fmaak_f32 v20, v20, v16, 0x4b400000
	v_fmaak_f32 v21, v21, v16, 0x4b400000
	v_perm_b32 v20, v20, v21, s28
	v_and_b32_e32 v21, 0xffff0000, v44
	v_lshlrev_b32_e32 v44, 16, v44
	v_fmaak_f32 v21, v21, v16, 0x4b400000
	v_fmaak_f32 v44, v44, v16, 0x4b400000
	v_perm_b32 v21, v21, v44, s28
	v_perm_b32 v20, v20, v21, s29
	global_store_dword v[6:7], v20, off offset:1536 sc1
	v_and_b32_e32 v20, 0xffff0000, v43
	v_lshlrev_b32_e32 v21, 16, v43
	v_fmaak_f32 v20, v20, v16, 0x4b400000
	v_fmaak_f32 v21, v21, v16, 0x4b400000
	v_perm_b32 v20, v20, v21, s28
	v_and_b32_e32 v21, 0xffff0000, v42
	v_lshlrev_b32_e32 v42, 16, v42
	v_fmaak_f32 v21, v21, v16, 0x4b400000
	v_fmaak_f32 v42, v42, v16, 0x4b400000
	v_perm_b32 v21, v21, v42, s28
	v_perm_b32 v20, v20, v21, s29
	global_store_dword v[6:7], v20, off offset:1792 sc1
	v_and_b32_e32 v20, 0xffff0000, v41
	v_lshlrev_b32_e32 v21, 16, v41
	v_fmaak_f32 v20, v20, v16, 0x4b400000
	v_fmaak_f32 v21, v21, v16, 0x4b400000
	v_perm_b32 v20, v20, v21, s28
	v_and_b32_e32 v21, 0xffff0000, v40
	v_lshlrev_b32_e32 v40, 16, v40
	v_fmaak_f32 v21, v21, v16, 0x4b400000
	v_fmaak_f32 v40, v40, v16, 0x4b400000
	v_perm_b32 v21, v21, v40, s28
	v_perm_b32 v20, v20, v21, s29
	global_store_dword v[6:7], v20, off offset:2048 sc1
	v_and_b32_e32 v20, 0xffff0000, v39
	v_lshlrev_b32_e32 v21, 16, v39
	v_fmaak_f32 v20, v20, v16, 0x4b400000
	v_fmaak_f32 v21, v21, v16, 0x4b400000
	v_perm_b32 v20, v20, v21, s28
	v_and_b32_e32 v21, 0xffff0000, v38
	v_lshlrev_b32_e32 v38, 16, v38
	v_fmaak_f32 v21, v21, v16, 0x4b400000
	v_fmaak_f32 v38, v38, v16, 0x4b400000
	v_perm_b32 v21, v21, v38, s28
	v_perm_b32 v20, v20, v21, s29
	global_store_dword v[6:7], v20, off offset:2304 sc1
	v_and_b32_e32 v20, 0xffff0000, v37
	v_lshlrev_b32_e32 v21, 16, v37
	v_fmaak_f32 v20, v20, v16, 0x4b400000
	v_fmaak_f32 v21, v21, v16, 0x4b400000
	v_perm_b32 v20, v20, v21, s28
	v_and_b32_e32 v21, 0xffff0000, v36
	v_lshlrev_b32_e32 v36, 16, v36
	v_fmaak_f32 v21, v21, v16, 0x4b400000
	v_fmaak_f32 v36, v36, v16, 0x4b400000
	v_perm_b32 v21, v21, v36, s28
	v_perm_b32 v20, v20, v21, s29
	global_store_dword v[6:7], v20, off offset:2560 sc1
	v_and_b32_e32 v20, 0xffff0000, v35
	v_lshlrev_b32_e32 v21, 16, v35
	v_fmaak_f32 v20, v20, v16, 0x4b400000
	v_fmaak_f32 v21, v21, v16, 0x4b400000
	v_perm_b32 v20, v20, v21, s28
	v_and_b32_e32 v21, 0xffff0000, v34
	v_lshlrev_b32_e32 v34, 16, v34
	v_fmaak_f32 v21, v21, v16, 0x4b400000
	v_fmaak_f32 v34, v34, v16, 0x4b400000
	v_perm_b32 v21, v21, v34, s28
	v_perm_b32 v20, v20, v21, s29
	global_store_dword v[6:7], v20, off offset:2816 sc1
	v_and_b32_e32 v20, 0xffff0000, v33
	v_lshlrev_b32_e32 v21, 16, v33
	v_fmaak_f32 v20, v20, v16, 0x4b400000
	v_fmaak_f32 v21, v21, v16, 0x4b400000
	v_perm_b32 v20, v20, v21, s28
	v_and_b32_e32 v21, 0xffff0000, v32
	v_lshlrev_b32_e32 v32, 16, v32
	v_fmaak_f32 v21, v21, v16, 0x4b400000
	v_fmaak_f32 v32, v32, v16, 0x4b400000
	v_perm_b32 v21, v21, v32, s28
	v_perm_b32 v20, v20, v21, s29
	global_store_dword v[6:7], v20, off offset:3072 sc1
	v_and_b32_e32 v20, 0xffff0000, v31
	v_lshlrev_b32_e32 v21, 16, v31
	v_fmaak_f32 v20, v20, v16, 0x4b400000
	v_fmaak_f32 v21, v21, v16, 0x4b400000
	v_perm_b32 v20, v20, v21, s28
	v_and_b32_e32 v21, 0xffff0000, v30
	v_lshlrev_b32_e32 v30, 16, v30
	v_fmaak_f32 v21, v21, v16, 0x4b400000
	v_fmaak_f32 v30, v30, v16, 0x4b400000
	v_perm_b32 v21, v21, v30, s28
	v_perm_b32 v20, v20, v21, s29
	global_store_dword v[6:7], v20, off offset:3328 sc1
	v_and_b32_e32 v20, 0xffff0000, v29
	v_lshlrev_b32_e32 v21, 16, v29
	v_fmaak_f32 v20, v20, v16, 0x4b400000
	v_fmaak_f32 v21, v21, v16, 0x4b400000
	v_perm_b32 v20, v20, v21, s28
	v_and_b32_e32 v21, 0xffff0000, v28
	v_lshlrev_b32_e32 v28, 16, v28
	v_fmaak_f32 v21, v21, v16, 0x4b400000
	v_fmaak_f32 v28, v28, v16, 0x4b400000
	v_perm_b32 v21, v21, v28, s28
	v_perm_b32 v20, v20, v21, s29
	global_store_dword v[6:7], v20, off offset:3584 sc1
	v_and_b32_e32 v20, 0xffff0000, v27
	v_lshlrev_b32_e32 v21, 16, v27
	v_fmaak_f32 v20, v20, v16, 0x4b400000
	v_fmaak_f32 v21, v21, v16, 0x4b400000
	v_perm_b32 v20, v20, v21, s28
	v_and_b32_e32 v21, 0xffff0000, v26
	v_lshlrev_b32_e32 v26, 16, v26
	v_fmaak_f32 v21, v21, v16, 0x4b400000
	v_fmaak_f32 v26, v26, v16, 0x4b400000
	v_perm_b32 v21, v21, v26, s28
	v_perm_b32 v20, v20, v21, s29
	global_store_dword v[6:7], v20, off offset:3840 sc1
	v_and_b32_e32 v6, 0xffff0000, v25
	v_lshlrev_b32_e32 v7, 16, v25
	v_fmaak_f32 v6, v6, v16, 0x4b400000
	v_fmaak_f32 v7, v7, v16, 0x4b400000
	v_perm_b32 v6, v6, v7, s28
	v_and_b32_e32 v7, 0xffff0000, v24
	v_lshlrev_b32_e32 v20, 16, v24
	v_fmaak_f32 v7, v7, v16, 0x4b400000
	v_fmaak_f32 v20, v20, v16, 0x4b400000
	v_perm_b32 v7, v7, v20, s28
	v_add_co_u32_e32 v4, vcc, s34, v4
	v_perm_b32 v6, v6, v7, s29
	s_nop 0
	v_addc_co_u32_e32 v5, vcc, 0, v5, vcc
	global_store_dword v[4:5], v6, off sc1
	v_and_b32_e32 v6, 0xffff0000, v23
	v_lshlrev_b32_e32 v7, 16, v23
	v_fmaak_f32 v6, v6, v16, 0x4b400000
	v_fmaak_f32 v7, v7, v16, 0x4b400000
	v_perm_b32 v6, v6, v7, s28
	v_and_b32_e32 v7, 0xffff0000, v22
	v_lshlrev_b32_e32 v20, 16, v22
	v_fmaak_f32 v7, v7, v16, 0x4b400000
	v_fmaak_f32 v20, v20, v16, 0x4b400000
	v_perm_b32 v7, v7, v20, s28
	v_perm_b32 v6, v6, v7, s29
	global_store_dword v[4:5], v6, off offset:256 sc1
	v_and_b32_e32 v6, 0xffff0000, v97
	v_lshlrev_b32_e32 v7, 16, v97
	v_fmaak_f32 v6, v6, v16, 0x4b400000
	v_fmaak_f32 v7, v7, v16, 0x4b400000
	v_perm_b32 v6, v6, v7, s28
	v_and_b32_e32 v7, 0xffff0000, v96
	v_lshlrev_b32_e32 v20, 16, v96
	v_fmaak_f32 v7, v7, v16, 0x4b400000
	v_fmaak_f32 v20, v20, v16, 0x4b400000
	v_perm_b32 v7, v7, v20, s28
	v_perm_b32 v6, v6, v7, s29
	global_store_dword v[4:5], v6, off offset:512 sc1
	v_and_b32_e32 v6, 0xffff0000, v98
	v_lshlrev_b32_e32 v7, 16, v98
	v_fmaak_f32 v6, v6, v16, 0x4b400000
	v_fmaak_f32 v7, v7, v16, 0x4b400000
	v_perm_b32 v6, v6, v7, s28
	v_and_b32_e32 v7, 0xffff0000, v19
	v_lshlrev_b32_e32 v19, 16, v19
	v_fmaak_f32 v7, v7, v16, 0x4b400000
	v_fmaak_f32 v19, v19, v16, 0x4b400000
	v_perm_b32 v7, v7, v19, s28
	v_perm_b32 v6, v6, v7, s29
	global_store_dword v[4:5], v6, off offset:768 sc1
	v_and_b32_e32 v6, 0xffff0000, v95
	v_lshlrev_b32_e32 v7, 16, v95
	v_fmaak_f32 v6, v6, v16, 0x4b400000
	v_fmaak_f32 v7, v7, v16, 0x4b400000
	v_perm_b32 v6, v6, v7, s28
	v_and_b32_e32 v7, 0xffff0000, v94
	v_lshlrev_b32_e32 v19, 16, v94
	v_fmaak_f32 v7, v7, v16, 0x4b400000
	v_fmaak_f32 v19, v19, v16, 0x4b400000
	v_perm_b32 v7, v7, v19, s28
	v_perm_b32 v6, v6, v7, s29
	global_store_dword v[4:5], v6, off offset:1024 sc1
	v_and_b32_e32 v6, 0xffff0000, v100
	v_lshlrev_b32_e32 v7, 16, v100
	v_fmaak_f32 v6, v6, v16, 0x4b400000
	v_fmaak_f32 v7, v7, v16, 0x4b400000
	v_perm_b32 v6, v6, v7, s28
	v_and_b32_e32 v7, 0xffff0000, v99
	v_lshlrev_b32_e32 v19, 16, v99
	v_fmaak_f32 v7, v7, v16, 0x4b400000
	v_fmaak_f32 v19, v19, v16, 0x4b400000
	v_perm_b32 v7, v7, v19, s28
	v_perm_b32 v6, v6, v7, s29
	global_store_dword v[4:5], v6, off offset:1280 sc1
	v_and_b32_e32 v6, 0xffff0000, v101
	v_lshlrev_b32_e32 v7, 16, v101
	v_fmaak_f32 v6, v6, v16, 0x4b400000
	v_fmaak_f32 v7, v7, v16, 0x4b400000
	v_perm_b32 v6, v6, v7, s28
	v_and_b32_e32 v7, 0xffff0000, v18
	v_lshlrev_b32_e32 v18, 16, v18
	v_fmaak_f32 v7, v7, v16, 0x4b400000
	v_fmaak_f32 v18, v18, v16, 0x4b400000
	v_perm_b32 v7, v7, v18, s28
	v_perm_b32 v6, v6, v7, s29
	global_store_dword v[4:5], v6, off offset:1536 sc1
	v_and_b32_e32 v6, 0xffff0000, v17
	v_lshlrev_b32_e32 v7, 16, v17
	v_fmaak_f32 v6, v6, v16, 0x4b400000
	v_fmaak_f32 v7, v7, v16, 0x4b400000
	v_perm_b32 v6, v6, v7, s28
	v_and_b32_e32 v7, 0xffff0000, v15
	v_lshlrev_b32_e32 v15, 16, v15
	v_fmaak_f32 v7, v7, v16, 0x4b400000
	v_fmaak_f32 v15, v15, v16, 0x4b400000
	v_perm_b32 v7, v7, v15, s28
	v_perm_b32 v6, v6, v7, s29
	global_store_dword v[4:5], v6, off offset:1792 sc1
	v_and_b32_e32 v6, 0xffff0000, v14
	v_lshlrev_b32_e32 v7, 16, v14
	v_fmaak_f32 v6, v6, v16, 0x4b400000
	v_fmaak_f32 v7, v7, v16, 0x4b400000
	v_perm_b32 v6, v6, v7, s28
	v_and_b32_e32 v7, 0xffff0000, v13
	v_lshlrev_b32_e32 v13, 16, v13
	v_fmaak_f32 v7, v7, v16, 0x4b400000
	v_fmaak_f32 v13, v13, v16, 0x4b400000
	v_perm_b32 v7, v7, v13, s28
	v_perm_b32 v6, v6, v7, s29
	global_store_dword v[4:5], v6, off offset:2048 sc1
	v_and_b32_e32 v6, 0xffff0000, v11
	v_lshlrev_b32_e32 v7, 16, v11
	v_fmaak_f32 v6, v6, v16, 0x4b400000
	v_fmaak_f32 v7, v7, v16, 0x4b400000
	v_perm_b32 v6, v6, v7, s28
	v_and_b32_e32 v7, 0xffff0000, v9
	v_lshlrev_b32_e32 v9, 16, v9
	v_fmaak_f32 v7, v7, v16, 0x4b400000
	v_fmaak_f32 v9, v9, v16, 0x4b400000
	v_perm_b32 v7, v7, v9, s28
	v_perm_b32 v6, v6, v7, s29
	global_store_dword v[4:5], v6, off offset:2304 sc1
	v_and_b32_e32 v6, 0xffff0000, v12
	v_lshlrev_b32_e32 v7, 16, v12
	v_fmaak_f32 v6, v6, v16, 0x4b400000
	v_fmaak_f32 v7, v7, v16, 0x4b400000
	v_perm_b32 v6, v6, v7, s28
	v_and_b32_e32 v7, 0xffff0000, v10
	v_lshlrev_b32_e32 v9, 16, v10
	v_fmaak_f32 v7, v7, v16, 0x4b400000
	v_fmaak_f32 v9, v9, v16, 0x4b400000
	v_perm_b32 v7, v7, v9, s28
	v_perm_b32 v6, v6, v7, s29
	global_store_dword v[4:5], v6, off offset:2560 sc1
	s_and_saveexec_b64 s[18:19], s[6:7]
	s_cbranch_execz .LBB0_908
	s_add_u32 s36, s8, s2
	s_addc_u32 s37, s9, s3
	v_mul_f32_e32 v4, 0x3c010204, v8
	global_store_dword v85, v4, s[36:37] sc1
	s_branch .LBB0_908
